# v2 + nt hint on P0 weight loads + removed mid-segment s_setprio 0/1 toggle and the redundant post-barrier lgkmcnt(0) in the GEMM K-loops
# speedup vs baseline: 1.0048x; 1.0048x over previous
; #define LAS __attribute__((address_space(3)))
; template <int MAP> __device__ __forceinline__ void conv_matrix(const float* W, int K, int N, bf16* WT, LAS float* scr, int gw, int NGW, int lane) {
;     const int nblk = N / 32, nitems = (K / 64) * nblk;
;     for (int it = gw; it < nitems; it += NGW) {
;         const int kb = it / nblk, nb = it % nblk, k0 = 64 * kb, n0 = 32 * nb;
; #pragma unroll 8
;         for (int i = 0; i < 32; ++i) { const int kk = 2 * i + (lane >> 5); scr[kk * 33 + (lane & 31)] = W[(size_t)(k0 + kk) * N + n0 + (lane & 31)]; }
.LBB0_12:
	s_lshl_b32 s33, s17, 1
	s_lshl_b32 s34, s28, 1
	v_or_b32_e32 v7, s33, v3
	v_or_b32_e32 v21, s34, v14
	s_add_i32 s35, s33, 4
	s_add_i32 s36, s34, 4
	s_add_i32 s37, s33, 8
	s_add_i32 s38, s34, 8
	s_add_i32 s39, s33, 12
	s_add_i32 s40, s34, 12
	s_add_i32 s41, s33, 16
	s_add_i32 s42, s34, 16
	s_add_i32 s43, s33, 20
	s_add_i32 s44, s34, 20
	s_add_i32 s45, s33, 24
	s_add_i32 s46, s34, 24
	s_add_i32 s47, s33, 28
	s_add_i32 s48, s34, 28
	v_mad_i64_i32 v[22:23], s[30:31], v21, s22, v[12:13]
	v_mad_i64_i32 v[24:25], s[30:31], v7, s22, v[12:13]
	v_or_b32_e32 v7, s35, v3
	v_or_b32_e32 v21, s36, v14
	v_or_b32_e32 v31, s37, v3
	v_or_b32_e32 v32, s38, v14
	v_or_b32_e32 v38, s39, v3
	v_or_b32_e32 v36, s40, v14
	v_or_b32_e32 v42, s41, v3
	v_or_b32_e32 v40, s42, v14
	v_or_b32_e32 v46, s43, v3
	v_or_b32_e32 v44, s44, v14
	v_or_b32_e32 v50, s45, v3
	v_or_b32_e32 v48, s46, v14
	v_or_b32_e32 v54, s47, v3
	v_or_b32_e32 v52, s48, v14
	v_mad_i64_i32 v[26:27], s[30:31], v21, s22, v[12:13]
	v_mad_i64_i32 v[28:29], s[30:31], v7, s22, v[12:13]
	v_mad_i64_i32 v[32:33], s[30:31], v32, s22, v[12:13]
	v_mad_i64_i32 v[34:35], s[30:31], v31, s22, v[12:13]
	v_mad_i64_i32 v[36:37], s[30:31], v36, s22, v[12:13]
	v_mad_i64_i32 v[38:39], s[30:31], v38, s22, v[12:13]
	v_mad_i64_i32 v[40:41], s[30:31], v40, s22, v[12:13]
	v_mad_i64_i32 v[42:43], s[30:31], v42, s22, v[12:13]
	v_mad_i64_i32 v[44:45], s[30:31], v44, s22, v[12:13]
	v_mad_i64_i32 v[46:47], s[30:31], v46, s22, v[12:13]
	v_mad_i64_i32 v[48:49], s[30:31], v48, s22, v[12:13]
	v_mad_i64_i32 v[50:51], s[30:31], v50, s22, v[12:13]
	v_mad_i64_i32 v[52:53], s[30:31], v52, s22, v[12:13]
	v_mad_i64_i32 v[54:55], s[30:31], v54, s22, v[12:13]
	global_load_dword v7, v[22:23], off nt
	global_load_dword v21, v[24:25], off nt
	global_load_dword v31, v[26:27], off nt
	global_load_dword v56, v[28:29], off nt
	global_load_dword v57, v[32:33], off nt
	global_load_dword v58, v[34:35], off nt
	global_load_dword v59, v[36:37], off nt
	global_load_dword v60, v[38:39], off nt
	global_load_dword v61, v[40:41], off nt
	global_load_dword v62, v[42:43], off nt
	global_load_dword v63, v[44:45], off nt
	global_load_dword v64, v[46:47], off nt
	global_load_dword v65, v[48:49], off nt
	global_load_dword v66, v[50:51], off nt
	global_load_dword v67, v[52:53], off nt
	global_load_dword v68, v[54:55], off nt
	v_or_b32_e32 v24, s33, v1
	v_or_b32_e32 v22, s34, v0
	s_add_i32 s28, s28, 16
	s_add_i32 s17, s17, 16
	s_add_i32 s29, s29, -16
	v_mad_u64_u32 v[22:23], s[30:31], v22, s21, v[2:3]
	v_mad_u64_u32 v[24:25], s[30:31], v24, s21, v[2:3]
	v_or_b32_e32 v23, s35, v1
	v_or_b32_e32 v25, s36, v0
	v_or_b32_e32 v34, s37, v1
	v_or_b32_e32 v32, s38, v0
	v_or_b32_e32 v38, s39, v1
	v_or_b32_e32 v36, s40, v0
	v_or_b32_e32 v42, s41, v1
	v_or_b32_e32 v40, s42, v0
	v_or_b32_e32 v46, s43, v1
	v_or_b32_e32 v44, s44, v0
	v_or_b32_e32 v50, s45, v1
	v_or_b32_e32 v48, s46, v0
	v_or_b32_e32 v54, s47, v1
	v_or_b32_e32 v52, s48, v0
	s_cmp_lg_u32 s29, 0
	v_mad_u64_u32 v[26:27], s[30:31], v25, s21, v[2:3]
	v_mad_u64_u32 v[28:29], s[30:31], v23, s21, v[2:3]
	v_mad_u64_u32 v[32:33], s[30:31], v32, s21, v[2:3]
	v_mad_u64_u32 v[34:35], s[30:31], v34, s21, v[2:3]
	v_mad_u64_u32 v[36:37], s[30:31], v36, s21, v[2:3]
	v_mad_u64_u32 v[38:39], s[30:31], v38, s21, v[2:3]
	v_mad_u64_u32 v[40:41], s[30:31], v40, s21, v[2:3]
	v_mad_u64_u32 v[42:43], s[30:31], v42, s21, v[2:3]
	v_mad_u64_u32 v[44:45], s[30:31], v44, s21, v[2:3]
	v_mad_u64_u32 v[46:47], s[30:31], v46, s21, v[2:3]
	v_mad_u64_u32 v[48:49], s[30:31], v48, s21, v[2:3]
	v_mad_u64_u32 v[50:51], s[30:31], v50, s21, v[2:3]
	v_mad_u64_u32 v[52:53], s[30:31], v52, s21, v[2:3]
	v_mad_u64_u32 v[54:55], s[30:31], v54, s21, v[2:3]
	s_waitcnt vmcnt(15)
	ds_write_b32 v22, v7
	s_waitcnt vmcnt(14)
	ds_write_b32 v24, v21
	s_waitcnt vmcnt(13)
	ds_write_b32 v26, v31
	s_waitcnt vmcnt(12)
	ds_write_b32 v28, v56
	s_waitcnt vmcnt(11)
	ds_write_b32 v32, v57
	s_waitcnt vmcnt(10)
	ds_write_b32 v34, v58
	s_waitcnt vmcnt(9)
	ds_write_b32 v36, v59
	s_waitcnt vmcnt(8)
	ds_write_b32 v38, v60
	s_waitcnt vmcnt(7)
	ds_write_b32 v40, v61
	s_waitcnt vmcnt(6)
	ds_write_b32 v42, v62
	s_waitcnt vmcnt(5)
	ds_write_b32 v44, v63
	s_waitcnt vmcnt(4)
	ds_write_b32 v46, v64
	s_waitcnt vmcnt(3)
	ds_write_b32 v48, v65
	s_waitcnt vmcnt(2)
	ds_write_b32 v50, v66
	s_waitcnt vmcnt(1)
	ds_write_b32 v52, v67
	s_waitcnt vmcnt(0)
	ds_write_b32 v54, v68
	s_cbranch_scc1 .LBB0_12
; #define LAS __attribute__((address_space(3)))
; #define LDS_WAIT() asm volatile("s_waitcnt lgkmcnt(0)" ::: "memory")
; __device__ __forceinline__ unsigned pk2(float lo, float hi) { return pg8::cvt_pk_bf16(lo, hi); }
; template <int MAP> __device__ __forceinline__ void conv_matrix(const float* W, int K, int N, bf16* WT, LAS float* scr, int gw, int NGW, int lane) {
;     ...
;         const int kb = it / nblk, nb = it % nblk, k0 = 64 * kb, n0 = 32 * nb;
; #pragma unroll 8
;         for (int i = 0; i < 32; ++i) { const int kk = 2 * i + (lane >> 5); scr[kk * 33 + (lane & 31)] = W[(size_t)(k0 + kk) * N + n0 + (lane & 31)]; }
;         LDS_WAIT(); asm volatile("" ::: "memory");
;         const int c = lane & 7; const int r0 = map_row<MAP>(n0);
; #pragma unroll
;         for (int j = 0; j < 4; ++j) { const int n = (lane >> 3) + 8 * j; const LAS float* s = scr + (8 * c) * 33 + n;
;             v4u o; o.x = pk2(s[0 * 33], s[1 * 33]); o.y = pk2(s[2 * 33], s[3 * 33]); o.z = pk2(s[4 * 33], s[5 * 33]); o.w = pk2(s[6 * 33], s[7 * 33]);
;             *(v4u*)(WT + (size_t)(r0 + n) * K + k0 + 8 * c) = o; }
;         LDS_WAIT(); asm volatile("" ::: "memory");
;     }
	s_cmpk_gt_i32 s15, 0xaf
	s_cselect_b32 s17, 0xffffea00, 0
	s_cselect_b32 s28, 0x80, 0
	s_ashr_i32 s15, s14, 31
	s_add_i32 s17, s17, s16
	s_and_b32 s29, s16, 0x60
	v_lshl_add_u64 v[26:27], s[14:15], 1, v[10:11]
	s_lshl_b32 s14, s17, 1
	s_or_b32 s16, s28, s29
	s_and_b32 s14, s14, 0xffffff00
	s_waitcnt lgkmcnt(0)
	s_or_b32 s14, s16, s14
	v_or_b32_e32 v28, s14, v16
	ds_read2_b32 v[12:13], v17 offset1:33
	v_ashrrev_i32_e32 v29, 31, v28
	s_waitcnt lgkmcnt(0)
	v_cvt_pk_bf16_f32 v22, v12, v13
	ds_read2_b32 v[12:13], v17 offset0:66 offset1:99
	v_lshlrev_b64 v[28:29], 12, v[28:29]
	s_waitcnt lgkmcnt(0)
	v_cvt_pk_bf16_f32 v23, v12, v13
	ds_read2_b32 v[12:13], v17 offset0:132 offset1:165
	v_lshl_add_u64 v[28:29], v[26:27], 0, v[28:29]
	s_waitcnt lgkmcnt(0)
	v_cvt_pk_bf16_f32 v24, v12, v13
	ds_read2_b32 v[12:13], v17 offset0:198 offset1:231
	s_waitcnt lgkmcnt(0)
	v_cvt_pk_bf16_f32 v25, v12, v13
	global_store_dwordx4 v[28:29], v[22:25], off
	v_or_b32_e32 v28, s14, v18
	ds_read2_b32 v[12:13], v17 offset0:8 offset1:41
	v_ashrrev_i32_e32 v29, 31, v28
	s_waitcnt lgkmcnt(0)
	v_cvt_pk_bf16_f32 v22, v12, v13
	ds_read2_b32 v[12:13], v17 offset0:74 offset1:107
	v_lshlrev_b64 v[28:29], 12, v[28:29]
	s_waitcnt lgkmcnt(0)
	v_cvt_pk_bf16_f32 v23, v12, v13
	ds_read2_b32 v[12:13], v17 offset0:140 offset1:173
	v_lshl_add_u64 v[28:29], v[26:27], 0, v[28:29]
	s_waitcnt lgkmcnt(0)
	v_cvt_pk_bf16_f32 v24, v12, v13
	ds_read2_b32 v[12:13], v17 offset0:206 offset1:239
	s_waitcnt lgkmcnt(0)
	v_cvt_pk_bf16_f32 v25, v12, v13
	global_store_dwordx4 v[28:29], v[22:25], off
	v_or_b32_e32 v28, s14, v19
	ds_read2_b32 v[12:13], v17 offset0:16 offset1:49
	v_ashrrev_i32_e32 v29, 31, v28
	s_waitcnt lgkmcnt(0)
	v_cvt_pk_bf16_f32 v22, v12, v13
	ds_read2_b32 v[12:13], v17 offset0:82 offset1:115
	v_lshlrev_b64 v[28:29], 12, v[28:29]
	s_waitcnt lgkmcnt(0)
	v_cvt_pk_bf16_f32 v23, v12, v13
	ds_read2_b32 v[12:13], v17 offset0:148 offset1:181
	v_lshl_add_u64 v[28:29], v[26:27], 0, v[28:29]
	s_waitcnt lgkmcnt(0)
	v_cvt_pk_bf16_f32 v24, v12, v13
	ds_read2_b32 v[12:13], v17 offset0:214 offset1:247
	s_waitcnt lgkmcnt(0)
	v_cvt_pk_bf16_f32 v25, v12, v13
	global_store_dwordx4 v[28:29], v[22:25], off
	v_or_b32_e32 v28, s14, v20
	ds_read2_b32 v[12:13], v17 offset0:24 offset1:57
	v_ashrrev_i32_e32 v29, 31, v28
	s_waitcnt lgkmcnt(0)
	v_cvt_pk_bf16_f32 v22, v12, v13
	ds_read2_b32 v[12:13], v17 offset0:90 offset1:123
	v_lshlrev_b64 v[28:29], 12, v[28:29]
	s_waitcnt lgkmcnt(0)
	v_cvt_pk_bf16_f32 v23, v12, v13
	ds_read2_b32 v[12:13], v17 offset0:156 offset1:189
	v_lshl_add_u64 v[26:27], v[26:27], 0, v[28:29]
	s_waitcnt lgkmcnt(0)
	v_cvt_pk_bf16_f32 v24, v12, v13
	ds_read2_b32 v[12:13], v17 offset0:222 offset1:255
	s_waitcnt lgkmcnt(0)
	v_cvt_pk_bf16_f32 v25, v12, v13
	global_store_dwordx4 v[26:27], v[22:25], off
	s_waitcnt lgkmcnt(0)
	s_add_i32 s27, s27, s52
	s_cmpk_lt_i32 s27, 0x2c00
	s_cbranch_scc1 .LBB0_11

; #define LAS __attribute__((address_space(3)))
; template <int MAP> __device__ __forceinline__ void conv_matrix(const float* W, int K, int N, bf16* WT, LAS float* scr, int gw, int NGW, int lane) {
;     const int nblk = N / 32, nitems = (K / 64) * nblk;
;     for (int it = gw; it < nitems; it += NGW) {
;         const int kb = it / nblk, nb = it % nblk, k0 = 64 * kb, n0 = 32 * nb;
; #pragma unroll 8
;         for (int i = 0; i < 32; ++i) { const int kk = 2 * i + (lane >> 5); scr[kk * 33 + (lane & 31)] = W[(size_t)(k0 + kk) * N + n0 + (lane & 31)]; }
.LBB0_17:
	s_lshl_b32 s16, s11, 1
	s_lshl_b32 s17, s13, 1
	v_or_b32_e32 v24, s17, v14
	s_add_i32 s23, s16, 4
	s_add_i32 s27, s17, 4
	s_add_i32 s28, s16, 8
	s_add_i32 s29, s17, 8
	s_add_i32 s30, s16, 12
	s_add_i32 s31, s17, 12
	s_add_i32 s33, s16, 16
	s_add_i32 s34, s17, 16
	s_add_i32 s35, s16, 20
	s_add_i32 s36, s17, 20
	s_add_i32 s37, s16, 24
	s_add_i32 s38, s17, 24
	s_add_i32 s39, s16, 28
	s_add_i32 s40, s17, 28
	v_or_b32_e32 v22, s16, v3
	v_ashrrev_i32_e32 v25, 31, v24
	v_or_b32_e32 v26, s23, v3
	v_or_b32_e32 v28, s27, v14
	v_or_b32_e32 v32, s28, v3
	v_or_b32_e32 v34, s29, v14
	v_or_b32_e32 v36, s30, v3
	v_or_b32_e32 v38, s31, v14
	v_or_b32_e32 v40, s33, v3
	v_or_b32_e32 v42, s34, v14
	v_or_b32_e32 v44, s35, v3
	v_or_b32_e32 v46, s36, v14
	v_or_b32_e32 v48, s37, v3
	v_or_b32_e32 v50, s38, v14
	v_or_b32_e32 v52, s39, v3
	v_or_b32_e32 v54, s40, v14
	v_ashrrev_i32_e32 v23, 31, v22
	v_lshlrev_b64 v[24:25], 13, v[24:25]
	v_ashrrev_i32_e32 v29, 31, v28
	v_ashrrev_i32_e32 v27, 31, v26
	v_ashrrev_i32_e32 v35, 31, v34
	v_ashrrev_i32_e32 v33, 31, v32
	v_ashrrev_i32_e32 v39, 31, v38
	v_ashrrev_i32_e32 v37, 31, v36
	v_ashrrev_i32_e32 v43, 31, v42
	v_ashrrev_i32_e32 v41, 31, v40
	v_ashrrev_i32_e32 v47, 31, v46
	v_ashrrev_i32_e32 v45, 31, v44
	v_ashrrev_i32_e32 v51, 31, v50
	v_ashrrev_i32_e32 v49, 31, v48
	v_ashrrev_i32_e32 v55, 31, v54
	v_ashrrev_i32_e32 v53, 31, v52
	v_lshlrev_b64 v[22:23], 13, v[22:23]
	v_lshl_add_u64 v[24:25], v[12:13], 0, v[24:25]
	v_lshlrev_b64 v[26:27], 13, v[26:27]
	v_lshlrev_b64 v[28:29], 13, v[28:29]
	v_lshlrev_b64 v[32:33], 13, v[32:33]
	v_lshlrev_b64 v[34:35], 13, v[34:35]
	v_lshlrev_b64 v[36:37], 13, v[36:37]
	v_lshlrev_b64 v[38:39], 13, v[38:39]
	v_lshlrev_b64 v[40:41], 13, v[40:41]
	v_lshlrev_b64 v[42:43], 13, v[42:43]
	v_lshlrev_b64 v[44:45], 13, v[44:45]
	v_lshlrev_b64 v[46:47], 13, v[46:47]
	v_lshlrev_b64 v[48:49], 13, v[48:49]
	v_lshlrev_b64 v[50:51], 13, v[50:51]
	v_lshlrev_b64 v[52:53], 13, v[52:53]
	v_lshlrev_b64 v[54:55], 13, v[54:55]
	v_lshl_add_u64 v[22:23], v[12:13], 0, v[22:23]
	v_lshl_add_u64 v[28:29], v[12:13], 0, v[28:29]
	v_lshl_add_u64 v[26:27], v[12:13], 0, v[26:27]
	v_lshl_add_u64 v[34:35], v[12:13], 0, v[34:35]
	v_lshl_add_u64 v[32:33], v[12:13], 0, v[32:33]
	v_lshl_add_u64 v[38:39], v[12:13], 0, v[38:39]
	v_lshl_add_u64 v[36:37], v[12:13], 0, v[36:37]
	v_lshl_add_u64 v[42:43], v[12:13], 0, v[42:43]
	v_lshl_add_u64 v[40:41], v[12:13], 0, v[40:41]
	v_lshl_add_u64 v[46:47], v[12:13], 0, v[46:47]
	v_lshl_add_u64 v[44:45], v[12:13], 0, v[44:45]
	v_lshl_add_u64 v[50:51], v[12:13], 0, v[50:51]
	v_lshl_add_u64 v[48:49], v[12:13], 0, v[48:49]
	v_lshl_add_u64 v[54:55], v[12:13], 0, v[54:55]
	v_lshl_add_u64 v[52:53], v[12:13], 0, v[52:53]
	global_load_dword v7, v[24:25], off nt
	global_load_dword v21, v[22:23], off nt
	global_load_dword v31, v[28:29], off nt
	global_load_dword v56, v[26:27], off nt
	global_load_dword v57, v[34:35], off nt
	global_load_dword v58, v[32:33], off nt
	global_load_dword v59, v[38:39], off nt
	global_load_dword v60, v[36:37], off nt
	global_load_dword v61, v[42:43], off nt
	global_load_dword v62, v[40:41], off nt
	global_load_dword v63, v[46:47], off nt
	global_load_dword v64, v[44:45], off nt
	global_load_dword v65, v[50:51], off nt
	global_load_dword v66, v[48:49], off nt
	global_load_dword v67, v[54:55], off nt
	global_load_dword v68, v[52:53], off nt
	v_or_b32_e32 v24, s16, v1
	v_or_b32_e32 v22, s17, v0
	s_add_i32 s13, s13, 16
	s_add_i32 s11, s11, 16
	s_add_i32 s15, s15, -16
	v_mad_u64_u32 v[22:23], s[16:17], v22, s21, v[2:3]
	v_mad_u64_u32 v[24:25], s[16:17], v24, s21, v[2:3]
	v_or_b32_e32 v23, s23, v1
	v_or_b32_e32 v25, s27, v0
	v_or_b32_e32 v34, s28, v1
	v_or_b32_e32 v32, s29, v0
	v_or_b32_e32 v38, s30, v1
	v_or_b32_e32 v36, s31, v0
	v_or_b32_e32 v42, s33, v1
	v_or_b32_e32 v40, s34, v0
	v_or_b32_e32 v46, s35, v1
	v_or_b32_e32 v44, s36, v0
	v_or_b32_e32 v50, s37, v1
	v_or_b32_e32 v48, s38, v0
	v_or_b32_e32 v54, s39, v1
	v_or_b32_e32 v52, s40, v0
	s_cmp_lg_u32 s15, 0
	v_mad_u64_u32 v[26:27], s[16:17], v25, s21, v[2:3]
	v_mad_u64_u32 v[28:29], s[16:17], v23, s21, v[2:3]
	v_mad_u64_u32 v[32:33], s[16:17], v32, s21, v[2:3]
	v_mad_u64_u32 v[34:35], s[16:17], v34, s21, v[2:3]
	v_mad_u64_u32 v[36:37], s[16:17], v36, s21, v[2:3]
	v_mad_u64_u32 v[38:39], s[16:17], v38, s21, v[2:3]
	v_mad_u64_u32 v[40:41], s[16:17], v40, s21, v[2:3]
	v_mad_u64_u32 v[42:43], s[16:17], v42, s21, v[2:3]
	v_mad_u64_u32 v[44:45], s[16:17], v44, s21, v[2:3]
	v_mad_u64_u32 v[46:47], s[16:17], v46, s21, v[2:3]
	v_mad_u64_u32 v[48:49], s[16:17], v48, s21, v[2:3]
	v_mad_u64_u32 v[50:51], s[16:17], v50, s21, v[2:3]
	v_mad_u64_u32 v[52:53], s[16:17], v52, s21, v[2:3]
	v_mad_u64_u32 v[54:55], s[16:17], v54, s21, v[2:3]
	s_waitcnt vmcnt(15)
	ds_write_b32 v22, v7
	s_waitcnt vmcnt(14)
	ds_write_b32 v24, v21
	s_waitcnt vmcnt(13)
	ds_write_b32 v26, v31
	s_waitcnt vmcnt(12)
	ds_write_b32 v28, v56
	s_waitcnt vmcnt(11)
	ds_write_b32 v32, v57
	s_waitcnt vmcnt(10)
	ds_write_b32 v34, v58
	s_waitcnt vmcnt(9)
	ds_write_b32 v36, v59
	s_waitcnt vmcnt(8)
	ds_write_b32 v38, v60
	s_waitcnt vmcnt(7)
	ds_write_b32 v40, v61
	s_waitcnt vmcnt(6)
	ds_write_b32 v42, v62
	s_waitcnt vmcnt(5)
	ds_write_b32 v44, v63
	s_waitcnt vmcnt(4)
	ds_write_b32 v46, v64
	s_waitcnt vmcnt(3)
	ds_write_b32 v48, v65
	s_waitcnt vmcnt(2)
	ds_write_b32 v50, v66
	s_waitcnt vmcnt(1)
	ds_write_b32 v52, v67
	s_waitcnt vmcnt(0)
	ds_write_b32 v54, v68
	s_cbranch_scc1 .LBB0_17
; #define LAS __attribute__((address_space(3)))
; #define LDS_WAIT() asm volatile("s_waitcnt lgkmcnt(0)" ::: "memory")
; __device__ __forceinline__ unsigned pk2(float lo, float hi) { return pg8::cvt_pk_bf16(lo, hi); }
; template <int MAP> __device__ __forceinline__ void conv_matrix(const float* W, int K, int N, bf16* WT, LAS float* scr, int gw, int NGW, int lane) {
;     ...
;         const int kb = it / nblk, nb = it % nblk, k0 = 64 * kb, n0 = 32 * nb;
; #pragma unroll 8
;         for (int i = 0; i < 32; ++i) { const int kk = 2 * i + (lane >> 5); scr[kk * 33 + (lane & 31)] = W[(size_t)(k0 + kk) * N + n0 + (lane & 31)]; }
;         LDS_WAIT(); asm volatile("" ::: "memory");
;         const int c = lane & 7; const int r0 = map_row<MAP>(n0);
; #pragma unroll
;         for (int j = 0; j < 4; ++j) { const int n = (lane >> 3) + 8 * j; const LAS float* s = scr + (8 * c) * 33 + n;
;             v4u o; o.x = pk2(s[0 * 33], s[1 * 33]); o.y = pk2(s[2 * 33], s[3 * 33]); o.z = pk2(s[4 * 33], s[5 * 33]); o.w = pk2(s[6 * 33], s[7 * 33]);
;             *(v4u*)(WT + (size_t)(r0 + n) * K + k0 + 8 * c) = o; }
;         LDS_WAIT(); asm volatile("" ::: "memory");
;     }
	s_waitcnt lgkmcnt(0)
	ds_read2_b32 v[12:13], v17 offset1:33
	s_waitcnt lgkmcnt(0)
	v_cvt_pk_bf16_f32 v22, v12, v13
	ds_read2_b32 v[12:13], v17 offset0:66 offset1:99
	v_or_b32_e32 v3, s10, v16
	s_waitcnt lgkmcnt(0)
	v_cvt_pk_bf16_f32 v23, v12, v13
	ds_read2_b32 v[12:13], v17 offset0:132 offset1:165
	s_ashr_i32 s13, s12, 31
	v_mul_lo_u32 v28, v3, s20
	s_waitcnt lgkmcnt(0)
	v_cvt_pk_bf16_f32 v24, v12, v13
	ds_read2_b32 v[12:13], v17 offset0:198 offset1:231
	v_lshl_add_u64 v[26:27], s[12:13], 1, v[10:11]
	v_ashrrev_i32_e32 v29, 31, v28
	s_waitcnt lgkmcnt(0)
	v_cvt_pk_bf16_f32 v25, v12, v13
	ds_read2_b32 v[12:13], v17 offset0:8 offset1:41
	v_lshl_add_u64 v[28:29], v[28:29], 1, v[26:27]
	global_store_dwordx4 v[28:29], v[22:25], off
	v_or_b32_e32 v3, s10, v18
	v_mul_lo_u32 v28, v3, s20
	s_waitcnt lgkmcnt(0)
	v_cvt_pk_bf16_f32 v22, v12, v13
	ds_read2_b32 v[12:13], v17 offset0:74 offset1:107
	s_waitcnt lgkmcnt(0)
	v_cvt_pk_bf16_f32 v23, v12, v13
	ds_read2_b32 v[12:13], v17 offset0:140 offset1:173
	s_waitcnt lgkmcnt(0)
	v_cvt_pk_bf16_f32 v24, v12, v13
	ds_read2_b32 v[12:13], v17 offset0:206 offset1:239
	v_ashrrev_i32_e32 v29, 31, v28
	s_waitcnt lgkmcnt(0)
	v_cvt_pk_bf16_f32 v25, v12, v13
	ds_read2_b32 v[12:13], v17 offset0:16 offset1:49
	v_lshl_add_u64 v[28:29], v[28:29], 1, v[26:27]
	v_or_b32_e32 v3, s10, v19
	global_store_dwordx4 v[28:29], v[22:25], off
	v_mul_lo_u32 v28, v3, s20
	v_ashrrev_i32_e32 v29, 31, v28
	s_waitcnt lgkmcnt(0)
	v_cvt_pk_bf16_f32 v22, v12, v13
	ds_read2_b32 v[12:13], v17 offset0:82 offset1:115
	s_waitcnt lgkmcnt(0)
	v_cvt_pk_bf16_f32 v23, v12, v13
	ds_read2_b32 v[12:13], v17 offset0:148 offset1:181
	s_waitcnt lgkmcnt(0)
	v_cvt_pk_bf16_f32 v24, v12, v13
	ds_read2_b32 v[12:13], v17 offset0:214 offset1:247
	v_lshl_add_u64 v[28:29], v[28:29], 1, v[26:27]
	v_or_b32_e32 v3, s10, v20
	s_waitcnt lgkmcnt(0)
	v_cvt_pk_bf16_f32 v25, v12, v13
	ds_read2_b32 v[12:13], v17 offset0:24 offset1:57
	global_store_dwordx4 v[28:29], v[22:25], off
	v_mul_lo_u32 v28, v3, s20
	v_ashrrev_i32_e32 v29, 31, v28
	s_waitcnt lgkmcnt(0)
	v_cvt_pk_bf16_f32 v22, v12, v13
	ds_read2_b32 v[12:13], v17 offset0:90 offset1:123
	s_waitcnt lgkmcnt(0)
	v_cvt_pk_bf16_f32 v23, v12, v13
	ds_read2_b32 v[12:13], v17 offset0:156 offset1:189
	v_lshl_add_u64 v[26:27], v[28:29], 1, v[26:27]
	s_waitcnt lgkmcnt(0)
	v_cvt_pk_bf16_f32 v24, v12, v13
	ds_read2_b32 v[12:13], v17 offset0:222 offset1:255
	s_waitcnt lgkmcnt(0)
	v_cvt_pk_bf16_f32 v25, v12, v13
	global_store_dwordx4 v[26:27], v[22:25], off
	s_waitcnt lgkmcnt(0)
	s_add_i32 s14, s14, s52
	s_cmpk_lt_i32 s14, 0x1600
	s_cbranch_scc1 .LBB0_16
	s_branch .LBB0_8

; #define LAS __attribute__((address_space(3)))
; #define LDS_WAIT() asm volatile("s_waitcnt lgkmcnt(0)" ::: "memory")
; __device__ __forceinline__ unsigned pk2(float lo, float hi) { return pg8::cvt_pk_bf16(lo, hi); }
; template <int MAP> __device__ __forceinline__ void conv_matrix(const float* W, int K, int N, bf16* WT, LAS float* scr, int gw, int NGW, int lane) {
;     ...
;     for (int it = gw; it < nitems; it += NGW) {
;         const int kb = it / nblk, nb = it % nblk, k0 = 64 * kb, n0 = 32 * nb;
; #pragma unroll 8
;         for (int i = 0; i < 32; ++i) { const int kk = 2 * i + (lane >> 5); scr[kk * 33 + (lane & 31)] = W[(size_t)(k0 + kk) * N + n0 + (lane & 31)]; }
;         LDS_WAIT(); asm volatile("" ::: "memory");
;         const int c = lane & 7; const int r0 = map_row<MAP>(n0);
; #pragma unroll
;         for (int j = 0; j < 4; ++j) { const int n = (lane >> 3) + 8 * j; const LAS float* s = scr + (8 * c) * 33 + n;
;             v4u o; o.x = pk2(s[0 * 33], s[1 * 33]); o.y = pk2(s[2 * 33], s[3 * 33]); o.z = pk2(s[4 * 33], s[5 * 33]); o.w = pk2(s[6 * 33], s[7 * 33]);
;             *(v4u*)(WT + (size_t)(r0 + n) * K + k0 + 8 * c) = o; }
;         LDS_WAIT(); asm volatile("" ::: "memory");
;     }
.LBB0_22:
	s_lshl_b32 s11, s10, 1
	s_lshl_b32 s14, s7, 1
	v_or_b32_e32 v5, s11, v3
	v_or_b32_e32 v7, s14, v14
	s_add_i32 s15, s11, 4
	s_add_i32 s16, s14, 4
	s_add_i32 s17, s11, 8
	s_add_i32 s18, s14, 8
	s_add_i32 s19, s11, 12
	s_add_i32 s20, s14, 12
	s_add_i32 s21, s11, 16
	s_add_i32 s22, s14, 16
	s_add_i32 s23, s11, 20
	s_add_i32 s27, s14, 20
	s_add_i32 s28, s11, 24
	s_add_i32 s29, s14, 24
	s_add_i32 s30, s11, 28
	s_add_i32 s31, s14, 28
	v_mad_i64_i32 v[22:23], s[12:13], v7, s3, v[12:13]
	v_mad_i64_i32 v[24:25], s[12:13], v5, s3, v[12:13]
	v_or_b32_e32 v5, s15, v3
	v_or_b32_e32 v7, s16, v14
	v_or_b32_e32 v21, s17, v3
	v_or_b32_e32 v31, s18, v14
	v_or_b32_e32 v38, s19, v3
	v_or_b32_e32 v36, s20, v14
	v_or_b32_e32 v42, s21, v3
	v_or_b32_e32 v40, s22, v14
	v_or_b32_e32 v46, s23, v3
	v_or_b32_e32 v44, s27, v14
	v_or_b32_e32 v50, s28, v3
	v_or_b32_e32 v48, s29, v14
	v_or_b32_e32 v54, s30, v3
	v_or_b32_e32 v52, s31, v14
	v_mad_i64_i32 v[26:27], s[12:13], v7, s3, v[12:13]
	v_mad_i64_i32 v[28:29], s[12:13], v5, s3, v[12:13]
	v_mad_i64_i32 v[32:33], s[12:13], v31, s3, v[12:13]
	v_mad_i64_i32 v[34:35], s[12:13], v21, s3, v[12:13]
	v_mad_i64_i32 v[36:37], s[12:13], v36, s3, v[12:13]
	v_mad_i64_i32 v[38:39], s[12:13], v38, s3, v[12:13]
	v_mad_i64_i32 v[40:41], s[12:13], v40, s3, v[12:13]
	v_mad_i64_i32 v[42:43], s[12:13], v42, s3, v[12:13]
	v_mad_i64_i32 v[44:45], s[12:13], v44, s3, v[12:13]
	v_mad_i64_i32 v[46:47], s[12:13], v46, s3, v[12:13]
	v_mad_i64_i32 v[48:49], s[12:13], v48, s3, v[12:13]
	v_mad_i64_i32 v[50:51], s[12:13], v50, s3, v[12:13]
	v_mad_i64_i32 v[52:53], s[12:13], v52, s3, v[12:13]
	v_mad_i64_i32 v[54:55], s[12:13], v54, s3, v[12:13]
	global_load_dword v5, v[22:23], off nt
	global_load_dword v7, v[24:25], off nt
	global_load_dword v21, v[26:27], off nt
	global_load_dword v31, v[28:29], off nt
	global_load_dword v56, v[32:33], off nt
	global_load_dword v57, v[34:35], off nt
	global_load_dword v58, v[36:37], off nt
	global_load_dword v59, v[38:39], off nt
	global_load_dword v60, v[40:41], off nt
	global_load_dword v61, v[42:43], off nt
	global_load_dword v62, v[44:45], off nt
	global_load_dword v63, v[46:47], off nt
	global_load_dword v64, v[48:49], off nt
	global_load_dword v65, v[50:51], off nt
	global_load_dword v66, v[52:53], off nt
	global_load_dword v67, v[54:55], off nt
	v_or_b32_e32 v24, s11, v1
	v_or_b32_e32 v22, s14, v0
	s_add_i32 s7, s7, 16
	s_add_i32 s10, s10, 16
	s_add_i32 s1, s1, -16
	v_mad_u64_u32 v[22:23], s[12:13], v22, s8, v[2:3]
	v_mad_u64_u32 v[24:25], s[12:13], v24, s8, v[2:3]
	v_or_b32_e32 v23, s15, v1
	v_or_b32_e32 v25, s16, v0
	v_or_b32_e32 v34, s17, v1
	v_or_b32_e32 v32, s18, v0
	v_or_b32_e32 v38, s19, v1
	v_or_b32_e32 v36, s20, v0
	v_or_b32_e32 v42, s21, v1
	v_or_b32_e32 v40, s22, v0
	v_or_b32_e32 v46, s23, v1
	v_or_b32_e32 v44, s27, v0
	v_or_b32_e32 v50, s28, v1
	v_or_b32_e32 v48, s29, v0
	v_or_b32_e32 v54, s30, v1
	v_or_b32_e32 v52, s31, v0
	s_cmp_lg_u32 s1, 0
	v_mad_u64_u32 v[26:27], s[12:13], v25, s8, v[2:3]
	v_mad_u64_u32 v[28:29], s[12:13], v23, s8, v[2:3]
	v_mad_u64_u32 v[32:33], s[12:13], v32, s8, v[2:3]
	v_mad_u64_u32 v[34:35], s[12:13], v34, s8, v[2:3]
	v_mad_u64_u32 v[36:37], s[12:13], v36, s8, v[2:3]
	v_mad_u64_u32 v[38:39], s[12:13], v38, s8, v[2:3]
	v_mad_u64_u32 v[40:41], s[12:13], v40, s8, v[2:3]
	v_mad_u64_u32 v[42:43], s[12:13], v42, s8, v[2:3]
	v_mad_u64_u32 v[44:45], s[12:13], v44, s8, v[2:3]
	v_mad_u64_u32 v[46:47], s[12:13], v46, s8, v[2:3]
	v_mad_u64_u32 v[48:49], s[12:13], v48, s8, v[2:3]
	v_mad_u64_u32 v[50:51], s[12:13], v50, s8, v[2:3]
	v_mad_u64_u32 v[52:53], s[12:13], v52, s8, v[2:3]
	v_mad_u64_u32 v[54:55], s[12:13], v54, s8, v[2:3]
	s_waitcnt vmcnt(15)
	ds_write_b32 v22, v5
	s_waitcnt vmcnt(14)
	ds_write_b32 v24, v7
	s_waitcnt vmcnt(13)
	ds_write_b32 v26, v21
	s_waitcnt vmcnt(12)
	ds_write_b32 v28, v31
	s_waitcnt vmcnt(11)
	ds_write_b32 v32, v56
	s_waitcnt vmcnt(10)
	ds_write_b32 v34, v57
	s_waitcnt vmcnt(9)
	ds_write_b32 v36, v58
	s_waitcnt vmcnt(8)
	ds_write_b32 v38, v59
	s_waitcnt vmcnt(7)
	ds_write_b32 v40, v60
	s_waitcnt vmcnt(6)
	ds_write_b32 v42, v61
	s_waitcnt vmcnt(5)
	ds_write_b32 v44, v62
	s_waitcnt vmcnt(4)
	ds_write_b32 v46, v63
	s_waitcnt vmcnt(3)
	ds_write_b32 v48, v64
	s_waitcnt vmcnt(2)
	ds_write_b32 v50, v65
	s_waitcnt vmcnt(1)
	ds_write_b32 v52, v66
	s_waitcnt vmcnt(0)
	ds_write_b32 v54, v67
	s_cbranch_scc1 .LBB0_22
	s_waitcnt lgkmcnt(0)
	v_or_b32_e32 v26, s0, v16
	ds_read2_b32 v[12:13], v17 offset1:33
	s_ashr_i32 s7, s6, 31
	v_ashrrev_i32_e32 v27, 31, v26
	s_waitcnt lgkmcnt(0)
	v_cvt_pk_bf16_f32 v22, v12, v13
	ds_read2_b32 v[12:13], v17 offset0:66 offset1:99
	v_lshl_add_u64 v[28:29], s[6:7], 1, v[10:11]
	v_lshlrev_b64 v[26:27], 12, v[26:27]
	s_waitcnt lgkmcnt(0)
	v_cvt_pk_bf16_f32 v23, v12, v13
	ds_read2_b32 v[12:13], v17 offset0:132 offset1:165
	v_lshl_add_u64 v[26:27], v[28:29], 0, v[26:27]
	s_waitcnt lgkmcnt(0)
	v_cvt_pk_bf16_f32 v24, v12, v13
	ds_read2_b32 v[12:13], v17 offset0:198 offset1:231
	s_waitcnt lgkmcnt(0)
	v_cvt_pk_bf16_f32 v25, v12, v13
	global_store_dwordx4 v[26:27], v[22:25], off
	v_or_b32_e32 v26, s0, v18
	ds_read2_b32 v[12:13], v17 offset0:8 offset1:41
	v_ashrrev_i32_e32 v27, 31, v26
	s_waitcnt lgkmcnt(0)
	v_cvt_pk_bf16_f32 v22, v12, v13
	ds_read2_b32 v[12:13], v17 offset0:74 offset1:107
	v_lshlrev_b64 v[26:27], 12, v[26:27]
	s_waitcnt lgkmcnt(0)
	v_cvt_pk_bf16_f32 v23, v12, v13
	ds_read2_b32 v[12:13], v17 offset0:140 offset1:173
	v_lshl_add_u64 v[26:27], v[28:29], 0, v[26:27]
	s_waitcnt lgkmcnt(0)
	v_cvt_pk_bf16_f32 v24, v12, v13
	ds_read2_b32 v[12:13], v17 offset0:206 offset1:239
	s_waitcnt lgkmcnt(0)
	v_cvt_pk_bf16_f32 v25, v12, v13
	global_store_dwordx4 v[26:27], v[22:25], off
	v_or_b32_e32 v26, s0, v19
	ds_read2_b32 v[12:13], v17 offset0:16 offset1:49
	v_ashrrev_i32_e32 v27, 31, v26
	s_waitcnt lgkmcnt(0)
	v_cvt_pk_bf16_f32 v22, v12, v13
	ds_read2_b32 v[12:13], v17 offset0:82 offset1:115
	v_lshlrev_b64 v[26:27], 12, v[26:27]
	s_waitcnt lgkmcnt(0)
	v_cvt_pk_bf16_f32 v23, v12, v13
	ds_read2_b32 v[12:13], v17 offset0:148 offset1:181
	v_lshl_add_u64 v[26:27], v[28:29], 0, v[26:27]
	s_waitcnt lgkmcnt(0)
	v_cvt_pk_bf16_f32 v24, v12, v13
	ds_read2_b32 v[12:13], v17 offset0:214 offset1:247
	s_waitcnt lgkmcnt(0)
	v_cvt_pk_bf16_f32 v25, v12, v13
	global_store_dwordx4 v[26:27], v[22:25], off
	v_or_b32_e32 v26, s0, v20
	ds_read2_b32 v[12:13], v17 offset0:24 offset1:57
	v_ashrrev_i32_e32 v27, 31, v26
	s_waitcnt lgkmcnt(0)
	v_cvt_pk_bf16_f32 v22, v12, v13
	ds_read2_b32 v[12:13], v17 offset0:90 offset1:123
	v_lshlrev_b64 v[26:27], 12, v[26:27]
	s_waitcnt lgkmcnt(0)
	v_cvt_pk_bf16_f32 v23, v12, v13
	ds_read2_b32 v[12:13], v17 offset0:156 offset1:189
	v_lshl_add_u64 v[26:27], v[28:29], 0, v[26:27]
	s_waitcnt lgkmcnt(0)
	v_cvt_pk_bf16_f32 v24, v12, v13
	ds_read2_b32 v[12:13], v17 offset0:222 offset1:255
	s_waitcnt lgkmcnt(0)
	v_cvt_pk_bf16_f32 v25, v12, v13
	global_store_dwordx4 v[26:27], v[22:25], off
	s_waitcnt lgkmcnt(0)
	s_add_i32 s9, s9, s52
	s_cmpk_lt_i32 s9, 0x440
	s_cbranch_scc1 .LBB0_21

; #define LAS __attribute__((address_space(3)))
; #define LDS_WAIT() asm volatile("s_waitcnt lgkmcnt(0)" ::: "memory")
; __device__ __forceinline__ unsigned pk2(float lo, float hi) { return pg8::cvt_pk_bf16(lo, hi); }
; template <int MAP> __device__ __forceinline__ void conv_matrix(const float* W, int K, int N, bf16* WT, LAS float* scr, int gw, int NGW, int lane) {
;     ...
;     for (int it = gw; it < nitems; it += NGW) {
;         const int kb = it / nblk, nb = it % nblk, k0 = 64 * kb, n0 = 32 * nb;
; #pragma unroll 8
;         for (int i = 0; i < 32; ++i) { const int kk = 2 * i + (lane >> 5); scr[kk * 33 + (lane & 31)] = W[(size_t)(k0 + kk) * N + n0 + (lane & 31)]; }
;         LDS_WAIT(); asm volatile("" ::: "memory");
;         const int c = lane & 7; const int r0 = map_row<MAP>(n0);
; #pragma unroll
;         for (int j = 0; j < 4; ++j) { const int n = (lane >> 3) + 8 * j; const LAS float* s = scr + (8 * c) * 33 + n;
;             v4u o; o.x = pk2(s[0 * 33], s[1 * 33]); o.y = pk2(s[2 * 33], s[3 * 33]); o.z = pk2(s[4 * 33], s[5 * 33]); o.w = pk2(s[6 * 33], s[7 * 33]);
;             *(v4u*)(WT + (size_t)(r0 + n) * K + k0 + 8 * c) = o; }
;         LDS_WAIT(); asm volatile("" ::: "memory");
;     }
.LBB0_27:
	s_lshl_b32 s11, s10, 1
	s_lshl_b32 s14, s7, 1
	v_or_b32_e32 v5, s11, v3
	v_or_b32_e32 v7, s14, v14
	s_add_i32 s15, s11, 4
	s_add_i32 s16, s14, 4
	s_add_i32 s17, s11, 8
	s_add_i32 s18, s14, 8
	s_add_i32 s19, s11, 12
	s_add_i32 s20, s14, 12
	s_add_i32 s21, s11, 16
	s_add_i32 s22, s14, 16
	s_add_i32 s23, s11, 20
	s_add_i32 s27, s14, 20
	s_add_i32 s28, s11, 24
	s_add_i32 s29, s14, 24
	s_add_i32 s30, s11, 28
	s_add_i32 s31, s14, 28
	v_mad_i64_i32 v[22:23], s[12:13], v7, s3, v[12:13]
	v_mad_i64_i32 v[24:25], s[12:13], v5, s3, v[12:13]
	v_or_b32_e32 v5, s15, v3
	v_or_b32_e32 v7, s16, v14
	v_or_b32_e32 v21, s17, v3
	v_or_b32_e32 v31, s18, v14
	v_or_b32_e32 v38, s19, v3
	v_or_b32_e32 v36, s20, v14
	v_or_b32_e32 v42, s21, v3
	v_or_b32_e32 v40, s22, v14
	v_or_b32_e32 v46, s23, v3
	v_or_b32_e32 v44, s27, v14
	v_or_b32_e32 v50, s28, v3
	v_or_b32_e32 v48, s29, v14
	v_or_b32_e32 v54, s30, v3
	v_or_b32_e32 v52, s31, v14
	v_mad_i64_i32 v[26:27], s[12:13], v7, s3, v[12:13]
	v_mad_i64_i32 v[28:29], s[12:13], v5, s3, v[12:13]
	v_mad_i64_i32 v[32:33], s[12:13], v31, s3, v[12:13]
	v_mad_i64_i32 v[34:35], s[12:13], v21, s3, v[12:13]
	v_mad_i64_i32 v[36:37], s[12:13], v36, s3, v[12:13]
	v_mad_i64_i32 v[38:39], s[12:13], v38, s3, v[12:13]
	v_mad_i64_i32 v[40:41], s[12:13], v40, s3, v[12:13]
	v_mad_i64_i32 v[42:43], s[12:13], v42, s3, v[12:13]
	v_mad_i64_i32 v[44:45], s[12:13], v44, s3, v[12:13]
	v_mad_i64_i32 v[46:47], s[12:13], v46, s3, v[12:13]
	v_mad_i64_i32 v[48:49], s[12:13], v48, s3, v[12:13]
	v_mad_i64_i32 v[50:51], s[12:13], v50, s3, v[12:13]
	v_mad_i64_i32 v[52:53], s[12:13], v52, s3, v[12:13]
	v_mad_i64_i32 v[54:55], s[12:13], v54, s3, v[12:13]
	global_load_dword v5, v[22:23], off nt
	global_load_dword v7, v[24:25], off nt
	global_load_dword v21, v[26:27], off nt
	global_load_dword v31, v[28:29], off nt
	global_load_dword v56, v[32:33], off nt
	global_load_dword v57, v[34:35], off nt
	global_load_dword v58, v[36:37], off nt
	global_load_dword v59, v[38:39], off nt
	global_load_dword v60, v[40:41], off nt
	global_load_dword v61, v[42:43], off nt
	global_load_dword v62, v[44:45], off nt
	global_load_dword v63, v[46:47], off nt
	global_load_dword v64, v[48:49], off nt
	global_load_dword v65, v[50:51], off nt
	global_load_dword v66, v[52:53], off nt
	global_load_dword v67, v[54:55], off nt
	v_or_b32_e32 v24, s11, v1
	v_or_b32_e32 v22, s14, v0
	s_add_i32 s7, s7, 16
	s_add_i32 s10, s10, 16
	s_add_i32 s1, s1, -16
	v_mad_u64_u32 v[22:23], s[12:13], v22, s8, v[2:3]
	v_mad_u64_u32 v[24:25], s[12:13], v24, s8, v[2:3]
	v_or_b32_e32 v23, s15, v1
	v_or_b32_e32 v25, s16, v0
	v_or_b32_e32 v34, s17, v1
	v_or_b32_e32 v32, s18, v0
	v_or_b32_e32 v38, s19, v1
	v_or_b32_e32 v36, s20, v0
	v_or_b32_e32 v42, s21, v1
	v_or_b32_e32 v40, s22, v0
	v_or_b32_e32 v46, s23, v1
	v_or_b32_e32 v44, s27, v0
	v_or_b32_e32 v50, s28, v1
	v_or_b32_e32 v48, s29, v0
	v_or_b32_e32 v54, s30, v1
	v_or_b32_e32 v52, s31, v0
	s_cmp_lg_u32 s1, 0
	v_mad_u64_u32 v[26:27], s[12:13], v25, s8, v[2:3]
	v_mad_u64_u32 v[28:29], s[12:13], v23, s8, v[2:3]
	v_mad_u64_u32 v[32:33], s[12:13], v32, s8, v[2:3]
	v_mad_u64_u32 v[34:35], s[12:13], v34, s8, v[2:3]
	v_mad_u64_u32 v[36:37], s[12:13], v36, s8, v[2:3]
	v_mad_u64_u32 v[38:39], s[12:13], v38, s8, v[2:3]
	v_mad_u64_u32 v[40:41], s[12:13], v40, s8, v[2:3]
	v_mad_u64_u32 v[42:43], s[12:13], v42, s8, v[2:3]
	v_mad_u64_u32 v[44:45], s[12:13], v44, s8, v[2:3]
	v_mad_u64_u32 v[46:47], s[12:13], v46, s8, v[2:3]
	v_mad_u64_u32 v[48:49], s[12:13], v48, s8, v[2:3]
	v_mad_u64_u32 v[50:51], s[12:13], v50, s8, v[2:3]
	v_mad_u64_u32 v[52:53], s[12:13], v52, s8, v[2:3]
	v_mad_u64_u32 v[54:55], s[12:13], v54, s8, v[2:3]
	s_waitcnt vmcnt(15)
	ds_write_b32 v22, v5
	s_waitcnt vmcnt(14)
	ds_write_b32 v24, v7
	s_waitcnt vmcnt(13)
	ds_write_b32 v26, v21
	s_waitcnt vmcnt(12)
	ds_write_b32 v28, v31
	s_waitcnt vmcnt(11)
	ds_write_b32 v32, v56
	s_waitcnt vmcnt(10)
	ds_write_b32 v34, v57
	s_waitcnt vmcnt(9)
	ds_write_b32 v36, v58
	s_waitcnt vmcnt(8)
	ds_write_b32 v38, v59
	s_waitcnt vmcnt(7)
	ds_write_b32 v40, v60
	s_waitcnt vmcnt(6)
	ds_write_b32 v42, v61
	s_waitcnt vmcnt(5)
	ds_write_b32 v44, v62
	s_waitcnt vmcnt(4)
	ds_write_b32 v46, v63
	s_waitcnt vmcnt(3)
	ds_write_b32 v48, v64
	s_waitcnt vmcnt(2)
	ds_write_b32 v50, v65
	s_waitcnt vmcnt(1)
	ds_write_b32 v52, v66
	s_waitcnt vmcnt(0)
	ds_write_b32 v54, v67
	s_cbranch_scc1 .LBB0_27
	s_waitcnt lgkmcnt(0)
	v_or_b32_e32 v26, s0, v16
	ds_read2_b32 v[12:13], v17 offset1:33
	s_ashr_i32 s7, s6, 31
	v_ashrrev_i32_e32 v27, 31, v26
	s_waitcnt lgkmcnt(0)
	v_cvt_pk_bf16_f32 v22, v12, v13
	ds_read2_b32 v[12:13], v17 offset0:66 offset1:99
	v_lshl_add_u64 v[28:29], s[6:7], 1, v[10:11]
	v_lshlrev_b64 v[26:27], 10, v[26:27]
	s_waitcnt lgkmcnt(0)
	v_cvt_pk_bf16_f32 v23, v12, v13
	ds_read2_b32 v[12:13], v17 offset0:132 offset1:165
	v_lshl_add_u64 v[26:27], v[28:29], 0, v[26:27]
	s_waitcnt lgkmcnt(0)
	v_cvt_pk_bf16_f32 v24, v12, v13
	ds_read2_b32 v[12:13], v17 offset0:198 offset1:231
	s_waitcnt lgkmcnt(0)
	v_cvt_pk_bf16_f32 v25, v12, v13
	global_store_dwordx4 v[26:27], v[22:25], off
	v_or_b32_e32 v26, s0, v18
	ds_read2_b32 v[12:13], v17 offset0:8 offset1:41
	v_ashrrev_i32_e32 v27, 31, v26
	s_waitcnt lgkmcnt(0)
	v_cvt_pk_bf16_f32 v22, v12, v13
	ds_read2_b32 v[12:13], v17 offset0:74 offset1:107
	v_lshlrev_b64 v[26:27], 10, v[26:27]
	s_waitcnt lgkmcnt(0)
	v_cvt_pk_bf16_f32 v23, v12, v13
	ds_read2_b32 v[12:13], v17 offset0:140 offset1:173
	v_lshl_add_u64 v[26:27], v[28:29], 0, v[26:27]
	s_waitcnt lgkmcnt(0)
	v_cvt_pk_bf16_f32 v24, v12, v13
	ds_read2_b32 v[12:13], v17 offset0:206 offset1:239
	s_waitcnt lgkmcnt(0)
	v_cvt_pk_bf16_f32 v25, v12, v13
	global_store_dwordx4 v[26:27], v[22:25], off
	v_or_b32_e32 v26, s0, v19
	ds_read2_b32 v[12:13], v17 offset0:16 offset1:49
	v_ashrrev_i32_e32 v27, 31, v26
	s_waitcnt lgkmcnt(0)
	v_cvt_pk_bf16_f32 v22, v12, v13
	ds_read2_b32 v[12:13], v17 offset0:82 offset1:115
	v_lshlrev_b64 v[26:27], 10, v[26:27]
	s_waitcnt lgkmcnt(0)
	v_cvt_pk_bf16_f32 v23, v12, v13
	ds_read2_b32 v[12:13], v17 offset0:148 offset1:181
	v_lshl_add_u64 v[26:27], v[28:29], 0, v[26:27]
	s_waitcnt lgkmcnt(0)
	v_cvt_pk_bf16_f32 v24, v12, v13
	ds_read2_b32 v[12:13], v17 offset0:214 offset1:247
	s_waitcnt lgkmcnt(0)
	v_cvt_pk_bf16_f32 v25, v12, v13
	global_store_dwordx4 v[26:27], v[22:25], off
	v_or_b32_e32 v26, s0, v20
	ds_read2_b32 v[12:13], v17 offset0:24 offset1:57
	v_ashrrev_i32_e32 v27, 31, v26
	s_waitcnt lgkmcnt(0)
	v_cvt_pk_bf16_f32 v22, v12, v13
	ds_read2_b32 v[12:13], v17 offset0:90 offset1:123
	v_lshlrev_b64 v[26:27], 10, v[26:27]
	s_waitcnt lgkmcnt(0)
	v_cvt_pk_bf16_f32 v23, v12, v13
	ds_read2_b32 v[12:13], v17 offset0:156 offset1:189
	v_lshl_add_u64 v[26:27], v[28:29], 0, v[26:27]
	s_waitcnt lgkmcnt(0)
	v_cvt_pk_bf16_f32 v24, v12, v13
	ds_read2_b32 v[12:13], v17 offset0:222 offset1:255
	s_waitcnt lgkmcnt(0)
	v_cvt_pk_bf16_f32 v25, v12, v13
	global_store_dwordx4 v[26:27], v[22:25], off
	s_waitcnt lgkmcnt(0)
	s_add_i32 s9, s9, s52
	s_cmpk_lt_i32 s9, 0x300
	s_cbranch_scc1 .LBB0_26

; #define LAS __attribute__((address_space(3)))
; template <int MAP> __device__ __forceinline__ void conv_matrix(const float* W, int K, int N, bf16* WT, LAS float* scr, int gw, int NGW, int lane) {
;     const int nblk = N / 32, nitems = (K / 64) * nblk;
;     for (int it = gw; it < nitems; it += NGW) {
;         const int kb = it / nblk, nb = it % nblk, k0 = 64 * kb, n0 = 32 * nb;
; #pragma unroll 8
;         for (int i = 0; i < 32; ++i) { const int kk = 2 * i + (lane >> 5); scr[kk * 33 + (lane & 31)] = W[(size_t)(k0 + kk) * N + n0 + (lane & 31)]; }
.LBB0_32:
	s_lshl_b32 s12, s11, 1
	s_lshl_b32 s13, s9, 1
	v_or_b32_e32 v24, s13, v14
	s_add_i32 s14, s12, 4
	s_add_i32 s15, s13, 4
	s_add_i32 s16, s12, 8
	s_add_i32 s17, s13, 8
	s_add_i32 s18, s12, 12
	s_add_i32 s19, s13, 12
	s_add_i32 s20, s12, 16
	s_add_i32 s21, s13, 16
	s_add_i32 s22, s12, 20
	s_add_i32 s23, s13, 20
	s_add_i32 s27, s12, 24
	s_add_i32 s28, s13, 24
	s_add_i32 s29, s12, 28
	s_add_i32 s30, s13, 28
	v_or_b32_e32 v22, s12, v3
	v_ashrrev_i32_e32 v25, 31, v24
	v_or_b32_e32 v26, s14, v3
	v_or_b32_e32 v28, s15, v14
	v_or_b32_e32 v32, s16, v3
	v_or_b32_e32 v34, s17, v14
	v_or_b32_e32 v36, s18, v3
	v_or_b32_e32 v38, s19, v14
	v_or_b32_e32 v40, s20, v3
	v_or_b32_e32 v42, s21, v14
	v_or_b32_e32 v44, s22, v3
	v_or_b32_e32 v46, s23, v14
	v_or_b32_e32 v48, s27, v3
	v_or_b32_e32 v50, s28, v14
	v_or_b32_e32 v52, s29, v3
	v_or_b32_e32 v54, s30, v14
	v_ashrrev_i32_e32 v23, 31, v22
	v_lshlrev_b64 v[24:25], 14, v[24:25]
	v_ashrrev_i32_e32 v29, 31, v28
	v_ashrrev_i32_e32 v27, 31, v26
	v_ashrrev_i32_e32 v35, 31, v34
	v_ashrrev_i32_e32 v33, 31, v32
	v_ashrrev_i32_e32 v39, 31, v38
	v_ashrrev_i32_e32 v37, 31, v36
	v_ashrrev_i32_e32 v43, 31, v42
	v_ashrrev_i32_e32 v41, 31, v40
	v_ashrrev_i32_e32 v47, 31, v46
	v_ashrrev_i32_e32 v45, 31, v44
	v_ashrrev_i32_e32 v51, 31, v50
	v_ashrrev_i32_e32 v49, 31, v48
	v_ashrrev_i32_e32 v55, 31, v54
	v_ashrrev_i32_e32 v53, 31, v52
	v_lshlrev_b64 v[22:23], 14, v[22:23]
	v_lshl_add_u64 v[24:25], v[12:13], 0, v[24:25]
	v_lshlrev_b64 v[26:27], 14, v[26:27]
	v_lshlrev_b64 v[28:29], 14, v[28:29]
	v_lshlrev_b64 v[32:33], 14, v[32:33]
	v_lshlrev_b64 v[34:35], 14, v[34:35]
	v_lshlrev_b64 v[36:37], 14, v[36:37]
	v_lshlrev_b64 v[38:39], 14, v[38:39]
	v_lshlrev_b64 v[40:41], 14, v[40:41]
	v_lshlrev_b64 v[42:43], 14, v[42:43]
	v_lshlrev_b64 v[44:45], 14, v[44:45]
	v_lshlrev_b64 v[46:47], 14, v[46:47]
	v_lshlrev_b64 v[48:49], 14, v[48:49]
	v_lshlrev_b64 v[50:51], 14, v[50:51]
	v_lshlrev_b64 v[52:53], 14, v[52:53]
	v_lshlrev_b64 v[54:55], 14, v[54:55]
	v_lshl_add_u64 v[22:23], v[12:13], 0, v[22:23]
	v_lshl_add_u64 v[28:29], v[12:13], 0, v[28:29]
	v_lshl_add_u64 v[26:27], v[12:13], 0, v[26:27]
	v_lshl_add_u64 v[34:35], v[12:13], 0, v[34:35]
	v_lshl_add_u64 v[32:33], v[12:13], 0, v[32:33]
	v_lshl_add_u64 v[38:39], v[12:13], 0, v[38:39]
	v_lshl_add_u64 v[36:37], v[12:13], 0, v[36:37]
	v_lshl_add_u64 v[42:43], v[12:13], 0, v[42:43]
	v_lshl_add_u64 v[40:41], v[12:13], 0, v[40:41]
	v_lshl_add_u64 v[46:47], v[12:13], 0, v[46:47]
	v_lshl_add_u64 v[44:45], v[12:13], 0, v[44:45]
	v_lshl_add_u64 v[50:51], v[12:13], 0, v[50:51]
	v_lshl_add_u64 v[48:49], v[12:13], 0, v[48:49]
	v_lshl_add_u64 v[54:55], v[12:13], 0, v[54:55]
	v_lshl_add_u64 v[52:53], v[12:13], 0, v[52:53]
	global_load_dword v5, v[24:25], off nt
	global_load_dword v7, v[22:23], off nt
	global_load_dword v21, v[28:29], off nt
	global_load_dword v31, v[26:27], off nt
	global_load_dword v56, v[34:35], off nt
	global_load_dword v57, v[32:33], off nt
	global_load_dword v58, v[38:39], off nt
	global_load_dword v59, v[36:37], off nt
	global_load_dword v60, v[42:43], off nt
	global_load_dword v61, v[40:41], off nt
	global_load_dword v62, v[46:47], off nt
	global_load_dword v63, v[44:45], off nt
	global_load_dword v64, v[50:51], off nt
	global_load_dword v65, v[48:49], off nt
	global_load_dword v66, v[54:55], off nt
	global_load_dword v67, v[52:53], off nt
	v_or_b32_e32 v24, s12, v1
	v_or_b32_e32 v22, s13, v0
	s_add_i32 s9, s9, 16
	s_add_i32 s11, s11, 16
	s_add_i32 s7, s7, -16
	v_mad_u64_u32 v[22:23], s[12:13], v22, s3, v[2:3]
	v_mad_u64_u32 v[24:25], s[12:13], v24, s3, v[2:3]
	v_or_b32_e32 v23, s14, v1
	v_or_b32_e32 v25, s15, v0
	v_or_b32_e32 v34, s16, v1
	v_or_b32_e32 v32, s17, v0
	v_or_b32_e32 v38, s18, v1
	v_or_b32_e32 v36, s19, v0
	v_or_b32_e32 v42, s20, v1
	v_or_b32_e32 v40, s21, v0
	v_or_b32_e32 v46, s22, v1
	v_or_b32_e32 v44, s23, v0
	v_or_b32_e32 v50, s27, v1
	v_or_b32_e32 v48, s28, v0
	v_or_b32_e32 v54, s29, v1
	v_or_b32_e32 v52, s30, v0
	s_cmp_lg_u32 s7, 0
	v_mad_u64_u32 v[26:27], s[12:13], v25, s3, v[2:3]
	v_mad_u64_u32 v[28:29], s[12:13], v23, s3, v[2:3]
	v_mad_u64_u32 v[32:33], s[12:13], v32, s3, v[2:3]
	v_mad_u64_u32 v[34:35], s[12:13], v34, s3, v[2:3]
	v_mad_u64_u32 v[36:37], s[12:13], v36, s3, v[2:3]
	v_mad_u64_u32 v[38:39], s[12:13], v38, s3, v[2:3]
	v_mad_u64_u32 v[40:41], s[12:13], v40, s3, v[2:3]
	v_mad_u64_u32 v[42:43], s[12:13], v42, s3, v[2:3]
	v_mad_u64_u32 v[44:45], s[12:13], v44, s3, v[2:3]
	v_mad_u64_u32 v[46:47], s[12:13], v46, s3, v[2:3]
	v_mad_u64_u32 v[48:49], s[12:13], v48, s3, v[2:3]
	v_mad_u64_u32 v[50:51], s[12:13], v50, s3, v[2:3]
	v_mad_u64_u32 v[52:53], s[12:13], v52, s3, v[2:3]
	v_mad_u64_u32 v[54:55], s[12:13], v54, s3, v[2:3]
	s_waitcnt vmcnt(15)
	ds_write_b32 v22, v5
	s_waitcnt vmcnt(14)
	ds_write_b32 v24, v7
	s_waitcnt vmcnt(13)
	ds_write_b32 v26, v21
	s_waitcnt vmcnt(12)
	ds_write_b32 v28, v31
	s_waitcnt vmcnt(11)
	ds_write_b32 v32, v56
	s_waitcnt vmcnt(10)
	ds_write_b32 v34, v57
	s_waitcnt vmcnt(9)
	ds_write_b32 v36, v58
	s_waitcnt vmcnt(8)
	ds_write_b32 v38, v59
	s_waitcnt vmcnt(7)
	ds_write_b32 v40, v60
	s_waitcnt vmcnt(6)
	ds_write_b32 v42, v61
	s_waitcnt vmcnt(5)
	ds_write_b32 v44, v62
	s_waitcnt vmcnt(4)
	ds_write_b32 v46, v63
	s_waitcnt vmcnt(3)
	ds_write_b32 v48, v64
	s_waitcnt vmcnt(2)
	ds_write_b32 v50, v65
	s_waitcnt vmcnt(1)
	ds_write_b32 v52, v66
	s_waitcnt vmcnt(0)
	ds_write_b32 v54, v67
	s_cbranch_scc1 .LBB0_32
; #define LAS __attribute__((address_space(3)))
; #define LDS_WAIT() asm volatile("s_waitcnt lgkmcnt(0)" ::: "memory")
; __device__ __forceinline__ unsigned pk2(float lo, float hi) { return pg8::cvt_pk_bf16(lo, hi); }
; template <int MAP> __device__ __forceinline__ void conv_matrix(const float* W, int K, int N, bf16* WT, LAS float* scr, int gw, int NGW, int lane) {
;     ...
;         const int kb = it / nblk, nb = it % nblk, k0 = 64 * kb, n0 = 32 * nb;
; #pragma unroll 8
;         for (int i = 0; i < 32; ++i) { const int kk = 2 * i + (lane >> 5); scr[kk * 33 + (lane & 31)] = W[(size_t)(k0 + kk) * N + n0 + (lane & 31)]; }
;         LDS_WAIT(); asm volatile("" ::: "memory");
;         const int c = lane & 7; const int r0 = map_row<MAP>(n0);
; #pragma unroll
;         for (int j = 0; j < 4; ++j) { const int n = (lane >> 3) + 8 * j; const LAS float* s = scr + (8 * c) * 33 + n;
;             v4u o; o.x = pk2(s[0 * 33], s[1 * 33]); o.y = pk2(s[2 * 33], s[3 * 33]); o.z = pk2(s[4 * 33], s[5 * 33]); o.w = pk2(s[6 * 33], s[7 * 33]);
;             *(v4u*)(WT + (size_t)(r0 + n) * K + k0 + 8 * c) = o; }
;         LDS_WAIT(); asm volatile("" ::: "memory");
;     }
	s_waitcnt lgkmcnt(0)
	v_or_b32_e32 v26, s6, v16
	ds_read2_b32 v[12:13], v17 offset1:33
	s_ashr_i32 s9, s8, 31
	v_ashrrev_i32_e32 v27, 31, v26
	s_waitcnt lgkmcnt(0)
	v_cvt_pk_bf16_f32 v22, v12, v13
	ds_read2_b32 v[12:13], v17 offset0:66 offset1:99
	v_lshl_add_u64 v[28:29], s[8:9], 1, v[10:11]
	v_lshlrev_b64 v[26:27], 10, v[26:27]
	s_waitcnt lgkmcnt(0)
	v_cvt_pk_bf16_f32 v23, v12, v13
	ds_read2_b32 v[12:13], v17 offset0:132 offset1:165
	v_lshl_add_u64 v[26:27], v[28:29], 0, v[26:27]
	s_waitcnt lgkmcnt(0)
	v_cvt_pk_bf16_f32 v24, v12, v13
	ds_read2_b32 v[12:13], v17 offset0:198 offset1:231
	s_waitcnt lgkmcnt(0)
	v_cvt_pk_bf16_f32 v25, v12, v13
	global_store_dwordx4 v[26:27], v[22:25], off
	v_or_b32_e32 v26, s6, v18
	ds_read2_b32 v[12:13], v17 offset0:8 offset1:41
	v_ashrrev_i32_e32 v27, 31, v26
	s_waitcnt lgkmcnt(0)
	v_cvt_pk_bf16_f32 v22, v12, v13
	ds_read2_b32 v[12:13], v17 offset0:74 offset1:107
	v_lshlrev_b64 v[26:27], 10, v[26:27]
	s_waitcnt lgkmcnt(0)
	v_cvt_pk_bf16_f32 v23, v12, v13
	ds_read2_b32 v[12:13], v17 offset0:140 offset1:173
	v_lshl_add_u64 v[26:27], v[28:29], 0, v[26:27]
	s_waitcnt lgkmcnt(0)
	v_cvt_pk_bf16_f32 v24, v12, v13
	ds_read2_b32 v[12:13], v17 offset0:206 offset1:239
	s_waitcnt lgkmcnt(0)
	v_cvt_pk_bf16_f32 v25, v12, v13
	global_store_dwordx4 v[26:27], v[22:25], off
	v_or_b32_e32 v26, s6, v19
	ds_read2_b32 v[12:13], v17 offset0:16 offset1:49
	v_ashrrev_i32_e32 v27, 31, v26
	s_waitcnt lgkmcnt(0)
	v_cvt_pk_bf16_f32 v22, v12, v13
	ds_read2_b32 v[12:13], v17 offset0:82 offset1:115
	v_lshlrev_b64 v[26:27], 10, v[26:27]
	s_waitcnt lgkmcnt(0)
	v_cvt_pk_bf16_f32 v23, v12, v13
	ds_read2_b32 v[12:13], v17 offset0:148 offset1:181
	v_lshl_add_u64 v[26:27], v[28:29], 0, v[26:27]
	s_waitcnt lgkmcnt(0)
	v_cvt_pk_bf16_f32 v24, v12, v13
	ds_read2_b32 v[12:13], v17 offset0:214 offset1:247
	s_waitcnt lgkmcnt(0)
	v_cvt_pk_bf16_f32 v25, v12, v13
	global_store_dwordx4 v[26:27], v[22:25], off
	v_or_b32_e32 v26, s6, v20
	ds_read2_b32 v[12:13], v17 offset0:24 offset1:57
	v_ashrrev_i32_e32 v27, 31, v26
	s_waitcnt lgkmcnt(0)
	v_cvt_pk_bf16_f32 v22, v12, v13
	ds_read2_b32 v[12:13], v17 offset0:90 offset1:123
	v_lshlrev_b64 v[26:27], 10, v[26:27]
	s_waitcnt lgkmcnt(0)
	v_cvt_pk_bf16_f32 v23, v12, v13
	ds_read2_b32 v[12:13], v17 offset0:156 offset1:189
	v_lshl_add_u64 v[26:27], v[28:29], 0, v[26:27]
	s_waitcnt lgkmcnt(0)
	v_cvt_pk_bf16_f32 v24, v12, v13
	ds_read2_b32 v[12:13], v17 offset0:222 offset1:255
	s_waitcnt lgkmcnt(0)
	v_cvt_pk_bf16_f32 v25, v12, v13
	global_store_dwordx4 v[26:27], v[22:25], off
	s_waitcnt lgkmcnt(0)
	s_add_i32 s10, s10, s52
	s_cmpk_lt_i32 s10, 0x400
	s_cbranch_scc1 .LBB0_31

; #define LAS __attribute__((address_space(3)))
; template <int MAP> __device__ __forceinline__ void conv_matrix(const float* W, int K, int N, bf16* WT, LAS float* scr, int gw, int NGW, int lane) {
;     const int nblk = N / 32, nitems = (K / 64) * nblk;
;     for (int it = gw; it < nitems; it += NGW) {
;         const int kb = it / nblk, nb = it % nblk, k0 = 64 * kb, n0 = 32 * nb;
; #pragma unroll 8
;         for (int i = 0; i < 32; ++i) { const int kk = 2 * i + (lane >> 5); scr[kk * 33 + (lane & 31)] = W[(size_t)(k0 + kk) * N + n0 + (lane & 31)]; }
.LBB0_37:
	s_lshl_b32 s12, s11, 1
	s_lshl_b32 s13, s9, 1
	v_or_b32_e32 v24, s13, v14
	s_add_i32 s14, s12, 4
	s_add_i32 s15, s13, 4
	s_add_i32 s16, s12, 8
	s_add_i32 s17, s13, 8
	s_add_i32 s18, s12, 12
	s_add_i32 s19, s13, 12
	s_add_i32 s20, s12, 16
	s_add_i32 s21, s13, 16
	s_add_i32 s22, s12, 20
	s_add_i32 s23, s13, 20
	s_add_i32 s27, s12, 24
	s_add_i32 s28, s13, 24
	s_add_i32 s29, s12, 28
	s_add_i32 s30, s13, 28
	v_or_b32_e32 v22, s12, v3
	v_ashrrev_i32_e32 v25, 31, v24
	v_or_b32_e32 v26, s14, v3
	v_or_b32_e32 v28, s15, v14
	v_or_b32_e32 v32, s16, v3
	v_or_b32_e32 v34, s17, v14
	v_or_b32_e32 v36, s18, v3
	v_or_b32_e32 v38, s19, v14
	v_or_b32_e32 v40, s20, v3
	v_or_b32_e32 v42, s21, v14
	v_or_b32_e32 v44, s22, v3
	v_or_b32_e32 v46, s23, v14
	v_or_b32_e32 v48, s27, v3
	v_or_b32_e32 v50, s28, v14
	v_or_b32_e32 v52, s29, v3
	v_or_b32_e32 v54, s30, v14
	v_ashrrev_i32_e32 v23, 31, v22
	v_lshlrev_b64 v[24:25], 13, v[24:25]
	v_ashrrev_i32_e32 v29, 31, v28
	v_ashrrev_i32_e32 v27, 31, v26
	v_ashrrev_i32_e32 v35, 31, v34
	v_ashrrev_i32_e32 v33, 31, v32
	v_ashrrev_i32_e32 v39, 31, v38
	v_ashrrev_i32_e32 v37, 31, v36
	v_ashrrev_i32_e32 v43, 31, v42
	v_ashrrev_i32_e32 v41, 31, v40
	v_ashrrev_i32_e32 v47, 31, v46
	v_ashrrev_i32_e32 v45, 31, v44
	v_ashrrev_i32_e32 v51, 31, v50
	v_ashrrev_i32_e32 v49, 31, v48
	v_ashrrev_i32_e32 v55, 31, v54
	v_ashrrev_i32_e32 v53, 31, v52
	v_lshlrev_b64 v[22:23], 13, v[22:23]
	v_lshl_add_u64 v[24:25], v[12:13], 0, v[24:25]
	v_lshlrev_b64 v[26:27], 13, v[26:27]
	v_lshlrev_b64 v[28:29], 13, v[28:29]
	v_lshlrev_b64 v[32:33], 13, v[32:33]
	v_lshlrev_b64 v[34:35], 13, v[34:35]
	v_lshlrev_b64 v[36:37], 13, v[36:37]
	v_lshlrev_b64 v[38:39], 13, v[38:39]
	v_lshlrev_b64 v[40:41], 13, v[40:41]
	v_lshlrev_b64 v[42:43], 13, v[42:43]
	v_lshlrev_b64 v[44:45], 13, v[44:45]
	v_lshlrev_b64 v[46:47], 13, v[46:47]
	v_lshlrev_b64 v[48:49], 13, v[48:49]
	v_lshlrev_b64 v[50:51], 13, v[50:51]
	v_lshlrev_b64 v[52:53], 13, v[52:53]
	v_lshlrev_b64 v[54:55], 13, v[54:55]
	v_lshl_add_u64 v[22:23], v[12:13], 0, v[22:23]
	v_lshl_add_u64 v[28:29], v[12:13], 0, v[28:29]
	v_lshl_add_u64 v[26:27], v[12:13], 0, v[26:27]
	v_lshl_add_u64 v[34:35], v[12:13], 0, v[34:35]
	v_lshl_add_u64 v[32:33], v[12:13], 0, v[32:33]
	v_lshl_add_u64 v[38:39], v[12:13], 0, v[38:39]
	v_lshl_add_u64 v[36:37], v[12:13], 0, v[36:37]
	v_lshl_add_u64 v[42:43], v[12:13], 0, v[42:43]
	v_lshl_add_u64 v[40:41], v[12:13], 0, v[40:41]
	v_lshl_add_u64 v[46:47], v[12:13], 0, v[46:47]
	v_lshl_add_u64 v[44:45], v[12:13], 0, v[44:45]
	v_lshl_add_u64 v[50:51], v[12:13], 0, v[50:51]
	v_lshl_add_u64 v[48:49], v[12:13], 0, v[48:49]
	v_lshl_add_u64 v[54:55], v[12:13], 0, v[54:55]
	v_lshl_add_u64 v[52:53], v[12:13], 0, v[52:53]
	global_load_dword v5, v[24:25], off nt
	global_load_dword v7, v[22:23], off nt
	global_load_dword v21, v[28:29], off nt
	global_load_dword v31, v[26:27], off nt
	global_load_dword v56, v[34:35], off nt
	global_load_dword v57, v[32:33], off nt
	global_load_dword v58, v[38:39], off nt
	global_load_dword v59, v[36:37], off nt
	global_load_dword v60, v[42:43], off nt
	global_load_dword v61, v[40:41], off nt
	global_load_dword v62, v[46:47], off nt
	global_load_dword v63, v[44:45], off nt
	global_load_dword v64, v[50:51], off nt
	global_load_dword v65, v[48:49], off nt
	global_load_dword v66, v[54:55], off nt
	global_load_dword v67, v[52:53], off nt
	v_or_b32_e32 v24, s12, v1
	v_or_b32_e32 v22, s13, v0
	s_add_i32 s9, s9, 16
	s_add_i32 s11, s11, 16
	s_add_i32 s7, s7, -16
	v_mad_u64_u32 v[22:23], s[12:13], v22, s3, v[2:3]
	v_mad_u64_u32 v[24:25], s[12:13], v24, s3, v[2:3]
	v_or_b32_e32 v23, s14, v1
	v_or_b32_e32 v25, s15, v0
	v_or_b32_e32 v34, s16, v1
	v_or_b32_e32 v32, s17, v0
	v_or_b32_e32 v38, s18, v1
	v_or_b32_e32 v36, s19, v0
	v_or_b32_e32 v42, s20, v1
	v_or_b32_e32 v40, s21, v0
	v_or_b32_e32 v46, s22, v1
	v_or_b32_e32 v44, s23, v0
	v_or_b32_e32 v50, s27, v1
	v_or_b32_e32 v48, s28, v0
	v_or_b32_e32 v54, s29, v1
	v_or_b32_e32 v52, s30, v0
	s_cmp_lg_u32 s7, 0
	v_mad_u64_u32 v[26:27], s[12:13], v25, s3, v[2:3]
	v_mad_u64_u32 v[28:29], s[12:13], v23, s3, v[2:3]
	v_mad_u64_u32 v[32:33], s[12:13], v32, s3, v[2:3]
	v_mad_u64_u32 v[34:35], s[12:13], v34, s3, v[2:3]
	v_mad_u64_u32 v[36:37], s[12:13], v36, s3, v[2:3]
	v_mad_u64_u32 v[38:39], s[12:13], v38, s3, v[2:3]
	v_mad_u64_u32 v[40:41], s[12:13], v40, s3, v[2:3]
	v_mad_u64_u32 v[42:43], s[12:13], v42, s3, v[2:3]
	v_mad_u64_u32 v[44:45], s[12:13], v44, s3, v[2:3]
	v_mad_u64_u32 v[46:47], s[12:13], v46, s3, v[2:3]
	v_mad_u64_u32 v[48:49], s[12:13], v48, s3, v[2:3]
	v_mad_u64_u32 v[50:51], s[12:13], v50, s3, v[2:3]
	v_mad_u64_u32 v[52:53], s[12:13], v52, s3, v[2:3]
	v_mad_u64_u32 v[54:55], s[12:13], v54, s3, v[2:3]
	s_waitcnt vmcnt(15)
	ds_write_b32 v22, v5
	s_waitcnt vmcnt(14)
	ds_write_b32 v24, v7
	s_waitcnt vmcnt(13)
	ds_write_b32 v26, v21
	s_waitcnt vmcnt(12)
	ds_write_b32 v28, v31
	s_waitcnt vmcnt(11)
	ds_write_b32 v32, v56
	s_waitcnt vmcnt(10)
	ds_write_b32 v34, v57
	s_waitcnt vmcnt(9)
	ds_write_b32 v36, v58
	s_waitcnt vmcnt(8)
	ds_write_b32 v38, v59
	s_waitcnt vmcnt(7)
	ds_write_b32 v40, v60
	s_waitcnt vmcnt(6)
	ds_write_b32 v42, v61
	s_waitcnt vmcnt(5)
	ds_write_b32 v44, v62
	s_waitcnt vmcnt(4)
	ds_write_b32 v46, v63
	s_waitcnt vmcnt(3)
	ds_write_b32 v48, v64
	s_waitcnt vmcnt(2)
	ds_write_b32 v50, v65
	s_waitcnt vmcnt(1)
	ds_write_b32 v52, v66
	s_waitcnt vmcnt(0)
	ds_write_b32 v54, v67
	s_cbranch_scc1 .LBB0_37
; #define LAS __attribute__((address_space(3)))
; #define LDS_WAIT() asm volatile("s_waitcnt lgkmcnt(0)" ::: "memory")
; __device__ __forceinline__ unsigned pk2(float lo, float hi) { return pg8::cvt_pk_bf16(lo, hi); }
; template <int MAP> __device__ __forceinline__ void conv_matrix(const float* W, int K, int N, bf16* WT, LAS float* scr, int gw, int NGW, int lane) {
;     ...
;         const int kb = it / nblk, nb = it % nblk, k0 = 64 * kb, n0 = 32 * nb;
; #pragma unroll 8
;         for (int i = 0; i < 32; ++i) { const int kk = 2 * i + (lane >> 5); scr[kk * 33 + (lane & 31)] = W[(size_t)(k0 + kk) * N + n0 + (lane & 31)]; }
;         LDS_WAIT(); asm volatile("" ::: "memory");
;         const int c = lane & 7; const int r0 = map_row<MAP>(n0);
; #pragma unroll
;         for (int j = 0; j < 4; ++j) { const int n = (lane >> 3) + 8 * j; const LAS float* s = scr + (8 * c) * 33 + n;
;             v4u o; o.x = pk2(s[0 * 33], s[1 * 33]); o.y = pk2(s[2 * 33], s[3 * 33]); o.z = pk2(s[4 * 33], s[5 * 33]); o.w = pk2(s[6 * 33], s[7 * 33]);
;             *(v4u*)(WT + (size_t)(r0 + n) * K + k0 + 8 * c) = o; }
;         LDS_WAIT(); asm volatile("" ::: "memory");
;     }
	s_waitcnt lgkmcnt(0)
	v_or_b32_e32 v26, s6, v16
	ds_read2_b32 v[12:13], v17 offset1:33
	s_ashr_i32 s9, s8, 31
	v_ashrrev_i32_e32 v27, 31, v26
	s_waitcnt lgkmcnt(0)
	v_cvt_pk_bf16_f32 v22, v12, v13
	ds_read2_b32 v[12:13], v17 offset0:66 offset1:99
	v_lshl_add_u64 v[28:29], s[8:9], 1, v[10:11]
	v_lshlrev_b64 v[26:27], 12, v[26:27]
	s_waitcnt lgkmcnt(0)
	v_cvt_pk_bf16_f32 v23, v12, v13
	ds_read2_b32 v[12:13], v17 offset0:132 offset1:165
	v_lshl_add_u64 v[26:27], v[28:29], 0, v[26:27]
	s_waitcnt lgkmcnt(0)
	v_cvt_pk_bf16_f32 v24, v12, v13
	ds_read2_b32 v[12:13], v17 offset0:198 offset1:231
	s_waitcnt lgkmcnt(0)
	v_cvt_pk_bf16_f32 v25, v12, v13
	global_store_dwordx4 v[26:27], v[22:25], off
	v_or_b32_e32 v26, s6, v18
	ds_read2_b32 v[12:13], v17 offset0:8 offset1:41
	v_ashrrev_i32_e32 v27, 31, v26
	s_waitcnt lgkmcnt(0)
	v_cvt_pk_bf16_f32 v22, v12, v13
	ds_read2_b32 v[12:13], v17 offset0:74 offset1:107
	v_lshlrev_b64 v[26:27], 12, v[26:27]
	s_waitcnt lgkmcnt(0)
	v_cvt_pk_bf16_f32 v23, v12, v13
	ds_read2_b32 v[12:13], v17 offset0:140 offset1:173
	v_lshl_add_u64 v[26:27], v[28:29], 0, v[26:27]
	s_waitcnt lgkmcnt(0)
	v_cvt_pk_bf16_f32 v24, v12, v13
	ds_read2_b32 v[12:13], v17 offset0:206 offset1:239
	s_waitcnt lgkmcnt(0)
	v_cvt_pk_bf16_f32 v25, v12, v13
	global_store_dwordx4 v[26:27], v[22:25], off
	v_or_b32_e32 v26, s6, v19
	ds_read2_b32 v[12:13], v17 offset0:16 offset1:49
	v_ashrrev_i32_e32 v27, 31, v26
	s_waitcnt lgkmcnt(0)
	v_cvt_pk_bf16_f32 v22, v12, v13
	ds_read2_b32 v[12:13], v17 offset0:82 offset1:115
	v_lshlrev_b64 v[26:27], 12, v[26:27]
	s_waitcnt lgkmcnt(0)
	v_cvt_pk_bf16_f32 v23, v12, v13
	ds_read2_b32 v[12:13], v17 offset0:148 offset1:181
	v_lshl_add_u64 v[26:27], v[28:29], 0, v[26:27]
	s_waitcnt lgkmcnt(0)
	v_cvt_pk_bf16_f32 v24, v12, v13
	ds_read2_b32 v[12:13], v17 offset0:214 offset1:247
	s_waitcnt lgkmcnt(0)
	v_cvt_pk_bf16_f32 v25, v12, v13
	global_store_dwordx4 v[26:27], v[22:25], off
	v_or_b32_e32 v26, s6, v20
	ds_read2_b32 v[12:13], v17 offset0:24 offset1:57
	v_ashrrev_i32_e32 v27, 31, v26
	s_waitcnt lgkmcnt(0)
	v_cvt_pk_bf16_f32 v22, v12, v13
	ds_read2_b32 v[12:13], v17 offset0:90 offset1:123
	v_lshlrev_b64 v[26:27], 12, v[26:27]
	s_waitcnt lgkmcnt(0)
	v_cvt_pk_bf16_f32 v23, v12, v13
	ds_read2_b32 v[12:13], v17 offset0:156 offset1:189
	v_lshl_add_u64 v[26:27], v[28:29], 0, v[26:27]
	s_waitcnt lgkmcnt(0)
	v_cvt_pk_bf16_f32 v24, v12, v13
	ds_read2_b32 v[12:13], v17 offset0:222 offset1:255
	s_waitcnt lgkmcnt(0)
	v_cvt_pk_bf16_f32 v25, v12, v13
	global_store_dwordx4 v[26:27], v[22:25], off
	s_waitcnt lgkmcnt(0)
	s_add_i32 s10, s10, s52
	s_cmpk_lt_i32 s10, 0x800
	s_cbranch_scc1 .LBB0_36

; #define LAS __attribute__((address_space(3)))
; #define LDS_WAIT() asm volatile("s_waitcnt lgkmcnt(0)" ::: "memory")
; __device__ __forceinline__ unsigned pk2(float lo, float hi) { return pg8::cvt_pk_bf16(lo, hi); }
; template <int MAP> __device__ __forceinline__ void conv_matrix(const float* W, int K, int N, bf16* WT, LAS float* scr, int gw, int NGW, int lane) {
;     ...
;     for (int it = gw; it < nitems; it += NGW) {
;         const int kb = it / nblk, nb = it % nblk, k0 = 64 * kb, n0 = 32 * nb;
; #pragma unroll 8
;         for (int i = 0; i < 32; ++i) { const int kk = 2 * i + (lane >> 5); scr[kk * 33 + (lane & 31)] = W[(size_t)(k0 + kk) * N + n0 + (lane & 31)]; }
;         LDS_WAIT(); asm volatile("" ::: "memory");
;         const int c = lane & 7; const int r0 = map_row<MAP>(n0);
; #pragma unroll
;         for (int j = 0; j < 4; ++j) { const int n = (lane >> 3) + 8 * j; const LAS float* s = scr + (8 * c) * 33 + n;
;             v4u o; o.x = pk2(s[0 * 33], s[1 * 33]); o.y = pk2(s[2 * 33], s[3 * 33]); o.z = pk2(s[4 * 33], s[5 * 33]); o.w = pk2(s[6 * 33], s[7 * 33]);
;             *(v4u*)(WT + (size_t)(r0 + n) * K + k0 + 8 * c) = o; }
;         LDS_WAIT(); asm volatile("" ::: "memory");
;     }
.LBB0_42:
	s_lshl_b32 s13, s12, 1
	s_lshl_b32 s16, s9, 1
	v_or_b32_e32 v5, s13, v3
	v_or_b32_e32 v7, s16, v14
	s_add_i32 s17, s13, 4
	s_add_i32 s18, s16, 4
	s_add_i32 s19, s13, 8
	s_add_i32 s20, s16, 8
	s_add_i32 s21, s13, 12
	s_add_i32 s22, s16, 12
	s_add_i32 s23, s13, 16
	s_add_i32 s27, s16, 16
	s_add_i32 s28, s13, 20
	s_add_i32 s29, s16, 20
	s_add_i32 s30, s13, 24
	s_add_i32 s31, s16, 24
	s_add_i32 s33, s13, 28
	s_add_i32 s34, s16, 28
	v_mad_i64_i32 v[22:23], s[14:15], v7, s3, v[12:13]
	v_mad_i64_i32 v[24:25], s[14:15], v5, s3, v[12:13]
	v_or_b32_e32 v5, s17, v3
	v_or_b32_e32 v7, s18, v14
	v_or_b32_e32 v21, s19, v3
	v_or_b32_e32 v31, s20, v14
	v_or_b32_e32 v38, s21, v3
	v_or_b32_e32 v36, s22, v14
	v_or_b32_e32 v42, s23, v3
	v_or_b32_e32 v40, s27, v14
	v_or_b32_e32 v46, s28, v3
	v_or_b32_e32 v44, s29, v14
	v_or_b32_e32 v50, s30, v3
	v_or_b32_e32 v48, s31, v14
	v_or_b32_e32 v54, s33, v3
	v_or_b32_e32 v52, s34, v14
	v_mad_i64_i32 v[26:27], s[14:15], v7, s3, v[12:13]
	v_mad_i64_i32 v[28:29], s[14:15], v5, s3, v[12:13]
	v_mad_i64_i32 v[32:33], s[14:15], v31, s3, v[12:13]
	v_mad_i64_i32 v[34:35], s[14:15], v21, s3, v[12:13]
	v_mad_i64_i32 v[36:37], s[14:15], v36, s3, v[12:13]
	v_mad_i64_i32 v[38:39], s[14:15], v38, s3, v[12:13]
	v_mad_i64_i32 v[40:41], s[14:15], v40, s3, v[12:13]
	v_mad_i64_i32 v[42:43], s[14:15], v42, s3, v[12:13]
	v_mad_i64_i32 v[44:45], s[14:15], v44, s3, v[12:13]
	v_mad_i64_i32 v[46:47], s[14:15], v46, s3, v[12:13]
	v_mad_i64_i32 v[48:49], s[14:15], v48, s3, v[12:13]
	v_mad_i64_i32 v[50:51], s[14:15], v50, s3, v[12:13]
	v_mad_i64_i32 v[52:53], s[14:15], v52, s3, v[12:13]
	v_mad_i64_i32 v[54:55], s[14:15], v54, s3, v[12:13]
	global_load_dword v5, v[22:23], off nt
	global_load_dword v7, v[24:25], off nt
	global_load_dword v21, v[26:27], off nt
	global_load_dword v31, v[28:29], off nt
	global_load_dword v56, v[32:33], off nt
	global_load_dword v57, v[34:35], off nt
	global_load_dword v58, v[36:37], off nt
	global_load_dword v59, v[38:39], off nt
	global_load_dword v60, v[40:41], off nt
	global_load_dword v61, v[42:43], off nt
	global_load_dword v62, v[44:45], off nt
	global_load_dword v63, v[46:47], off nt
	global_load_dword v64, v[48:49], off nt
	global_load_dword v65, v[50:51], off nt
	global_load_dword v66, v[52:53], off nt
	global_load_dword v67, v[54:55], off nt
	v_or_b32_e32 v24, s13, v1
	v_or_b32_e32 v22, s16, v0
	s_add_i32 s9, s9, 16
	s_add_i32 s12, s12, 16
	s_add_i32 s7, s7, -16
	v_mad_u64_u32 v[22:23], s[14:15], v22, s10, v[2:3]
	v_mad_u64_u32 v[24:25], s[14:15], v24, s10, v[2:3]
	v_or_b32_e32 v23, s17, v1
	v_or_b32_e32 v25, s18, v0
	v_or_b32_e32 v34, s19, v1
	v_or_b32_e32 v32, s20, v0
	v_or_b32_e32 v38, s21, v1
	v_or_b32_e32 v36, s22, v0
	v_or_b32_e32 v42, s23, v1
	v_or_b32_e32 v40, s27, v0
	v_or_b32_e32 v46, s28, v1
	v_or_b32_e32 v44, s29, v0
	v_or_b32_e32 v50, s30, v1
	v_or_b32_e32 v48, s31, v0
	v_or_b32_e32 v54, s33, v1
	v_or_b32_e32 v52, s34, v0
	s_cmp_lg_u32 s7, 0
	v_mad_u64_u32 v[26:27], s[14:15], v25, s10, v[2:3]
	v_mad_u64_u32 v[28:29], s[14:15], v23, s10, v[2:3]
	v_mad_u64_u32 v[32:33], s[14:15], v32, s10, v[2:3]
	v_mad_u64_u32 v[34:35], s[14:15], v34, s10, v[2:3]
	v_mad_u64_u32 v[36:37], s[14:15], v36, s10, v[2:3]
	v_mad_u64_u32 v[38:39], s[14:15], v38, s10, v[2:3]
	v_mad_u64_u32 v[40:41], s[14:15], v40, s10, v[2:3]
	v_mad_u64_u32 v[42:43], s[14:15], v42, s10, v[2:3]
	v_mad_u64_u32 v[44:45], s[14:15], v44, s10, v[2:3]
	v_mad_u64_u32 v[46:47], s[14:15], v46, s10, v[2:3]
	v_mad_u64_u32 v[48:49], s[14:15], v48, s10, v[2:3]
	v_mad_u64_u32 v[50:51], s[14:15], v50, s10, v[2:3]
	v_mad_u64_u32 v[52:53], s[14:15], v52, s10, v[2:3]
	v_mad_u64_u32 v[54:55], s[14:15], v54, s10, v[2:3]
	s_waitcnt vmcnt(15)
	ds_write_b32 v22, v5
	s_waitcnt vmcnt(14)
	ds_write_b32 v24, v7
	s_waitcnt vmcnt(13)
	ds_write_b32 v26, v21
	s_waitcnt vmcnt(12)
	ds_write_b32 v28, v31
	s_waitcnt vmcnt(11)
	ds_write_b32 v32, v56
	s_waitcnt vmcnt(10)
	ds_write_b32 v34, v57
	s_waitcnt vmcnt(9)
	ds_write_b32 v36, v58
	s_waitcnt vmcnt(8)
	ds_write_b32 v38, v59
	s_waitcnt vmcnt(7)
	ds_write_b32 v40, v60
	s_waitcnt vmcnt(6)
	ds_write_b32 v42, v61
	s_waitcnt vmcnt(5)
	ds_write_b32 v44, v62
	s_waitcnt vmcnt(4)
	ds_write_b32 v46, v63
	s_waitcnt vmcnt(3)
	ds_write_b32 v48, v64
	s_waitcnt vmcnt(2)
	ds_write_b32 v50, v65
	s_waitcnt vmcnt(1)
	ds_write_b32 v52, v66
	s_waitcnt vmcnt(0)
	ds_write_b32 v54, v67
	s_cbranch_scc1 .LBB0_42
	s_waitcnt lgkmcnt(0)
	v_or_b32_e32 v26, s6, v16
	ds_read2_b32 v[12:13], v17 offset1:33
	s_ashr_i32 s9, s8, 31
	v_ashrrev_i32_e32 v27, 31, v26
	s_waitcnt lgkmcnt(0)
	v_cvt_pk_bf16_f32 v22, v12, v13
	ds_read2_b32 v[12:13], v17 offset0:66 offset1:99
	v_lshl_add_u64 v[28:29], s[8:9], 1, v[10:11]
	v_lshlrev_b64 v[26:27], 12, v[26:27]
	s_waitcnt lgkmcnt(0)
	v_cvt_pk_bf16_f32 v23, v12, v13
	ds_read2_b32 v[12:13], v17 offset0:132 offset1:165
	v_lshl_add_u64 v[26:27], v[28:29], 0, v[26:27]
	s_waitcnt lgkmcnt(0)
	v_cvt_pk_bf16_f32 v24, v12, v13
	ds_read2_b32 v[12:13], v17 offset0:198 offset1:231
	s_waitcnt lgkmcnt(0)
	v_cvt_pk_bf16_f32 v25, v12, v13
	global_store_dwordx4 v[26:27], v[22:25], off
	v_or_b32_e32 v26, s6, v18
	ds_read2_b32 v[12:13], v17 offset0:8 offset1:41
	v_ashrrev_i32_e32 v27, 31, v26
	s_waitcnt lgkmcnt(0)
	v_cvt_pk_bf16_f32 v22, v12, v13
	ds_read2_b32 v[12:13], v17 offset0:74 offset1:107
	v_lshlrev_b64 v[26:27], 12, v[26:27]
	s_waitcnt lgkmcnt(0)
	v_cvt_pk_bf16_f32 v23, v12, v13
	ds_read2_b32 v[12:13], v17 offset0:140 offset1:173
	v_lshl_add_u64 v[26:27], v[28:29], 0, v[26:27]
	s_waitcnt lgkmcnt(0)
	v_cvt_pk_bf16_f32 v24, v12, v13
	ds_read2_b32 v[12:13], v17 offset0:206 offset1:239
	s_waitcnt lgkmcnt(0)
	v_cvt_pk_bf16_f32 v25, v12, v13
	global_store_dwordx4 v[26:27], v[22:25], off
	v_or_b32_e32 v26, s6, v19
	ds_read2_b32 v[12:13], v17 offset0:16 offset1:49
	v_ashrrev_i32_e32 v27, 31, v26
	s_waitcnt lgkmcnt(0)
	v_cvt_pk_bf16_f32 v22, v12, v13
	ds_read2_b32 v[12:13], v17 offset0:82 offset1:115
	v_lshlrev_b64 v[26:27], 12, v[26:27]
	s_waitcnt lgkmcnt(0)
	v_cvt_pk_bf16_f32 v23, v12, v13
	ds_read2_b32 v[12:13], v17 offset0:148 offset1:181
	v_lshl_add_u64 v[26:27], v[28:29], 0, v[26:27]
	s_waitcnt lgkmcnt(0)
	v_cvt_pk_bf16_f32 v24, v12, v13
	ds_read2_b32 v[12:13], v17 offset0:214 offset1:247
	s_waitcnt lgkmcnt(0)
	v_cvt_pk_bf16_f32 v25, v12, v13
	global_store_dwordx4 v[26:27], v[22:25], off
	v_or_b32_e32 v26, s6, v20
	ds_read2_b32 v[12:13], v17 offset0:24 offset1:57
	v_ashrrev_i32_e32 v27, 31, v26
	s_waitcnt lgkmcnt(0)
	v_cvt_pk_bf16_f32 v22, v12, v13
	ds_read2_b32 v[12:13], v17 offset0:90 offset1:123
	v_lshlrev_b64 v[26:27], 12, v[26:27]
	s_waitcnt lgkmcnt(0)
	v_cvt_pk_bf16_f32 v23, v12, v13
	ds_read2_b32 v[12:13], v17 offset0:156 offset1:189
	v_lshl_add_u64 v[26:27], v[28:29], 0, v[26:27]
	s_waitcnt lgkmcnt(0)
	v_cvt_pk_bf16_f32 v24, v12, v13
	ds_read2_b32 v[12:13], v17 offset0:222 offset1:255
	s_waitcnt lgkmcnt(0)
	v_cvt_pk_bf16_f32 v25, v12, v13
	global_store_dwordx4 v[26:27], v[22:25], off
	s_waitcnt lgkmcnt(0)
	s_add_i32 s11, s11, s52
	s_cmpk_lt_i32 s11, 0x2400
	s_cbranch_scc1 .LBB0_41

; #define LAS __attribute__((address_space(3)))
; template <int MAP> __device__ __forceinline__ void conv_matrix(const float* W, int K, int N, bf16* WT, LAS float* scr, int gw, int NGW, int lane) {
;     const int nblk = N / 32, nitems = (K / 64) * nblk;
;     for (int it = gw; it < nitems; it += NGW) {
;         const int kb = it / nblk, nb = it % nblk, k0 = 64 * kb, n0 = 32 * nb;
; #pragma unroll 8
;         for (int i = 0; i < 32; ++i) { const int kk = 2 * i + (lane >> 5); scr[kk * 33 + (lane & 31)] = W[(size_t)(k0 + kk) * N + n0 + (lane & 31)]; }
.LBB0_47:
	s_lshl_b32 s10, s1, 1
	s_lshl_b32 s11, s9, 1
	v_or_b32_e32 v22, s11, v10
	s_add_i32 s12, s10, 4
	s_add_i32 s13, s11, 4
	s_add_i32 s14, s10, 8
	s_add_i32 s15, s11, 8
	s_add_i32 s16, s10, 12
	s_add_i32 s17, s11, 12
	s_add_i32 s18, s10, 16
	s_add_i32 s19, s11, 16
	s_add_i32 s20, s10, 20
	s_add_i32 s21, s11, 20
	s_add_i32 s22, s10, 24
	s_add_i32 s23, s11, 24
	s_add_i32 s27, s10, 28
	s_add_i32 s28, s11, 28
	v_or_b32_e32 v12, s10, v3
	v_ashrrev_i32_e32 v23, 31, v22
	v_or_b32_e32 v24, s12, v3
	v_or_b32_e32 v26, s13, v10
	v_or_b32_e32 v28, s14, v3
	v_or_b32_e32 v32, s15, v10
	v_or_b32_e32 v34, s16, v3
	v_or_b32_e32 v36, s17, v10
	v_or_b32_e32 v38, s18, v3
	v_or_b32_e32 v40, s19, v10
	v_or_b32_e32 v42, s20, v3
	v_or_b32_e32 v44, s21, v10
	v_or_b32_e32 v46, s22, v3
	v_or_b32_e32 v48, s23, v10
	v_or_b32_e32 v50, s27, v3
	v_or_b32_e32 v52, s28, v10
	v_ashrrev_i32_e32 v13, 31, v12
	v_lshlrev_b64 v[22:23], 13, v[22:23]
	v_ashrrev_i32_e32 v27, 31, v26
	v_ashrrev_i32_e32 v25, 31, v24
	v_ashrrev_i32_e32 v33, 31, v32
	v_ashrrev_i32_e32 v29, 31, v28
	v_ashrrev_i32_e32 v37, 31, v36
	v_ashrrev_i32_e32 v35, 31, v34
	v_ashrrev_i32_e32 v41, 31, v40
	v_ashrrev_i32_e32 v39, 31, v38
	v_ashrrev_i32_e32 v45, 31, v44
	v_ashrrev_i32_e32 v43, 31, v42
	v_ashrrev_i32_e32 v49, 31, v48
	v_ashrrev_i32_e32 v47, 31, v46
	v_ashrrev_i32_e32 v53, 31, v52
	v_ashrrev_i32_e32 v51, 31, v50
	v_lshlrev_b64 v[12:13], 13, v[12:13]
	v_lshl_add_u64 v[22:23], v[6:7], 0, v[22:23]
	v_lshlrev_b64 v[24:25], 13, v[24:25]
	v_lshlrev_b64 v[26:27], 13, v[26:27]
	v_lshlrev_b64 v[28:29], 13, v[28:29]
	v_lshlrev_b64 v[32:33], 13, v[32:33]
	v_lshlrev_b64 v[34:35], 13, v[34:35]
	v_lshlrev_b64 v[36:37], 13, v[36:37]
	v_lshlrev_b64 v[38:39], 13, v[38:39]
	v_lshlrev_b64 v[40:41], 13, v[40:41]
	v_lshlrev_b64 v[42:43], 13, v[42:43]
	v_lshlrev_b64 v[44:45], 13, v[44:45]
	v_lshlrev_b64 v[46:47], 13, v[46:47]
	v_lshlrev_b64 v[48:49], 13, v[48:49]
	v_lshlrev_b64 v[50:51], 13, v[50:51]
	v_lshlrev_b64 v[52:53], 13, v[52:53]
	v_lshl_add_u64 v[12:13], v[6:7], 0, v[12:13]
	v_lshl_add_u64 v[26:27], v[6:7], 0, v[26:27]
	v_lshl_add_u64 v[24:25], v[6:7], 0, v[24:25]
	v_lshl_add_u64 v[32:33], v[6:7], 0, v[32:33]
	v_lshl_add_u64 v[28:29], v[6:7], 0, v[28:29]
	v_lshl_add_u64 v[36:37], v[6:7], 0, v[36:37]
	v_lshl_add_u64 v[34:35], v[6:7], 0, v[34:35]
	v_lshl_add_u64 v[40:41], v[6:7], 0, v[40:41]
	v_lshl_add_u64 v[38:39], v[6:7], 0, v[38:39]
	v_lshl_add_u64 v[44:45], v[6:7], 0, v[44:45]
	v_lshl_add_u64 v[42:43], v[6:7], 0, v[42:43]
	v_lshl_add_u64 v[48:49], v[6:7], 0, v[48:49]
	v_lshl_add_u64 v[46:47], v[6:7], 0, v[46:47]
	v_lshl_add_u64 v[52:53], v[6:7], 0, v[52:53]
	v_lshl_add_u64 v[50:51], v[6:7], 0, v[50:51]
	global_load_dword v11, v[22:23], off nt
	global_load_dword v14, v[12:13], off nt
	global_load_dword v21, v[26:27], off nt
	global_load_dword v31, v[24:25], off nt
	global_load_dword v54, v[32:33], off nt
	global_load_dword v55, v[28:29], off nt
	global_load_dword v56, v[36:37], off nt
	global_load_dword v57, v[34:35], off nt
	global_load_dword v58, v[40:41], off nt
	global_load_dword v59, v[38:39], off nt
	global_load_dword v60, v[44:45], off nt
	global_load_dword v61, v[42:43], off nt
	global_load_dword v62, v[48:49], off nt
	global_load_dword v63, v[46:47], off nt
	global_load_dword v64, v[52:53], off nt
	global_load_dword v65, v[50:51], off nt
	v_or_b32_e32 v22, s10, v1
	v_or_b32_e32 v12, s11, v0
	s_add_i32 s9, s9, 16
	s_add_i32 s1, s1, 16
	s_add_i32 s7, s7, -16
	v_mad_u64_u32 v[12:13], s[10:11], v12, s3, v[2:3]
	v_mad_u64_u32 v[22:23], s[10:11], v22, s3, v[2:3]
	v_or_b32_e32 v13, s12, v1
	v_or_b32_e32 v23, s13, v0
	v_or_b32_e32 v32, s14, v1
	v_or_b32_e32 v28, s15, v0
	v_or_b32_e32 v36, s16, v1
	v_or_b32_e32 v34, s17, v0
	v_or_b32_e32 v40, s18, v1
	v_or_b32_e32 v38, s19, v0
	v_or_b32_e32 v44, s20, v1
	v_or_b32_e32 v42, s21, v0
	v_or_b32_e32 v48, s22, v1
	v_or_b32_e32 v46, s23, v0
	v_or_b32_e32 v52, s27, v1
	v_or_b32_e32 v50, s28, v0
	s_cmp_lg_u32 s7, 0
	v_mad_u64_u32 v[24:25], s[10:11], v23, s3, v[2:3]
	v_mad_u64_u32 v[26:27], s[10:11], v13, s3, v[2:3]
	v_mad_u64_u32 v[28:29], s[10:11], v28, s3, v[2:3]
	v_mad_u64_u32 v[32:33], s[10:11], v32, s3, v[2:3]
	v_mad_u64_u32 v[34:35], s[10:11], v34, s3, v[2:3]
	v_mad_u64_u32 v[36:37], s[10:11], v36, s3, v[2:3]
	v_mad_u64_u32 v[38:39], s[10:11], v38, s3, v[2:3]
	v_mad_u64_u32 v[40:41], s[10:11], v40, s3, v[2:3]
	v_mad_u64_u32 v[42:43], s[10:11], v42, s3, v[2:3]
	v_mad_u64_u32 v[44:45], s[10:11], v44, s3, v[2:3]
	v_mad_u64_u32 v[46:47], s[10:11], v46, s3, v[2:3]
	v_mad_u64_u32 v[48:49], s[10:11], v48, s3, v[2:3]
	v_mad_u64_u32 v[50:51], s[10:11], v50, s3, v[2:3]
	v_mad_u64_u32 v[52:53], s[10:11], v52, s3, v[2:3]
	s_waitcnt vmcnt(15)
	ds_write_b32 v12, v11
	s_waitcnt vmcnt(14)
	ds_write_b32 v22, v14
	s_waitcnt vmcnt(13)
	ds_write_b32 v24, v21
	s_waitcnt vmcnt(12)
	ds_write_b32 v26, v31
	s_waitcnt vmcnt(11)
	ds_write_b32 v28, v54
	s_waitcnt vmcnt(10)
	ds_write_b32 v32, v55
	s_waitcnt vmcnt(9)
	ds_write_b32 v34, v56
	s_waitcnt vmcnt(8)
	ds_write_b32 v36, v57
	s_waitcnt vmcnt(7)
	ds_write_b32 v38, v58
	s_waitcnt vmcnt(6)
	ds_write_b32 v40, v59
	s_waitcnt vmcnt(5)
	ds_write_b32 v42, v60
	s_waitcnt vmcnt(4)
	ds_write_b32 v44, v61
	s_waitcnt vmcnt(3)
	ds_write_b32 v46, v62
	s_waitcnt vmcnt(2)
	ds_write_b32 v48, v63
	s_waitcnt vmcnt(1)
	ds_write_b32 v50, v64
	s_waitcnt vmcnt(0)
	ds_write_b32 v52, v65
	s_cbranch_scc1 .LBB0_47
; #define LAS __attribute__((address_space(3)))
; #define LDS_WAIT() asm volatile("s_waitcnt lgkmcnt(0)" ::: "memory")
; __device__ __forceinline__ unsigned pk2(float lo, float hi) { return pg8::cvt_pk_bf16(lo, hi); }
; template <int MAP> __device__ __forceinline__ void conv_matrix(const float* W, int K, int N, bf16* WT, LAS float* scr, int gw, int NGW, int lane) {
;     ...
;         const int kb = it / nblk, nb = it % nblk, k0 = 64 * kb, n0 = 32 * nb;
; #pragma unroll 8
;         for (int i = 0; i < 32; ++i) { const int kk = 2 * i + (lane >> 5); scr[kk * 33 + (lane & 31)] = W[(size_t)(k0 + kk) * N + n0 + (lane & 31)]; }
;         LDS_WAIT(); asm volatile("" ::: "memory");
;         const int c = lane & 7; const int r0 = map_row<MAP>(n0);
; #pragma unroll
;         for (int j = 0; j < 4; ++j) { const int n = (lane >> 3) + 8 * j; const LAS float* s = scr + (8 * c) * 33 + n;
;             v4u o; o.x = pk2(s[0 * 33], s[1 * 33]); o.y = pk2(s[2 * 33], s[3 * 33]); o.z = pk2(s[4 * 33], s[5 * 33]); o.w = pk2(s[6 * 33], s[7 * 33]);
;             *(v4u*)(WT + (size_t)(r0 + n) * K + k0 + 8 * c) = o; }
;         LDS_WAIT(); asm volatile("" ::: "memory");
;     }
	s_waitcnt lgkmcnt(0)
	v_or_b32_e32 v22, s0, v16
	ds_read2_b32 v[6:7], v17 offset1:33
	s_ashr_i32 s7, s6, 31
	v_ashrrev_i32_e32 v23, 31, v22
	s_waitcnt lgkmcnt(0)
	v_cvt_pk_bf16_f32 v10, v6, v7
	ds_read2_b32 v[6:7], v17 offset0:66 offset1:99
	v_lshl_add_u64 v[24:25], s[6:7], 1, v[4:5]
	v_lshlrev_b64 v[22:23], 11, v[22:23]
	s_waitcnt lgkmcnt(0)
	v_cvt_pk_bf16_f32 v11, v6, v7
	ds_read2_b32 v[6:7], v17 offset0:132 offset1:165
	v_lshl_add_u64 v[22:23], v[24:25], 0, v[22:23]
	s_waitcnt lgkmcnt(0)
	v_cvt_pk_bf16_f32 v12, v6, v7
	ds_read2_b32 v[6:7], v17 offset0:198 offset1:231
	s_waitcnt lgkmcnt(0)
	v_cvt_pk_bf16_f32 v13, v6, v7
	global_store_dwordx4 v[22:23], v[10:13], off
	v_or_b32_e32 v22, s0, v18
	ds_read2_b32 v[6:7], v17 offset0:8 offset1:41
	v_ashrrev_i32_e32 v23, 31, v22
	s_waitcnt lgkmcnt(0)
	v_cvt_pk_bf16_f32 v10, v6, v7
	ds_read2_b32 v[6:7], v17 offset0:74 offset1:107
	v_lshlrev_b64 v[22:23], 11, v[22:23]
	s_waitcnt lgkmcnt(0)
	v_cvt_pk_bf16_f32 v11, v6, v7
	ds_read2_b32 v[6:7], v17 offset0:140 offset1:173
	v_lshl_add_u64 v[22:23], v[24:25], 0, v[22:23]
	s_waitcnt lgkmcnt(0)
	v_cvt_pk_bf16_f32 v12, v6, v7
	ds_read2_b32 v[6:7], v17 offset0:206 offset1:239
	s_waitcnt lgkmcnt(0)
	v_cvt_pk_bf16_f32 v13, v6, v7
	global_store_dwordx4 v[22:23], v[10:13], off
	v_or_b32_e32 v22, s0, v19
	ds_read2_b32 v[6:7], v17 offset0:16 offset1:49
	v_ashrrev_i32_e32 v23, 31, v22
	s_waitcnt lgkmcnt(0)
	v_cvt_pk_bf16_f32 v10, v6, v7
	ds_read2_b32 v[6:7], v17 offset0:82 offset1:115
	v_lshlrev_b64 v[22:23], 11, v[22:23]
	s_waitcnt lgkmcnt(0)
	v_cvt_pk_bf16_f32 v11, v6, v7
	ds_read2_b32 v[6:7], v17 offset0:148 offset1:181
	v_lshl_add_u64 v[22:23], v[24:25], 0, v[22:23]
	s_waitcnt lgkmcnt(0)
	v_cvt_pk_bf16_f32 v12, v6, v7
	ds_read2_b32 v[6:7], v17 offset0:214 offset1:247
	s_waitcnt lgkmcnt(0)
	v_cvt_pk_bf16_f32 v13, v6, v7
	global_store_dwordx4 v[22:23], v[10:13], off
	v_or_b32_e32 v22, s0, v20
	ds_read2_b32 v[6:7], v17 offset0:24 offset1:57
	v_ashrrev_i32_e32 v23, 31, v22
	s_waitcnt lgkmcnt(0)
	v_cvt_pk_bf16_f32 v10, v6, v7
	ds_read2_b32 v[6:7], v17 offset0:90 offset1:123
	v_lshlrev_b64 v[22:23], 11, v[22:23]
	s_waitcnt lgkmcnt(0)
	v_cvt_pk_bf16_f32 v11, v6, v7
	ds_read2_b32 v[6:7], v17 offset0:156 offset1:189
	v_lshl_add_u64 v[22:23], v[24:25], 0, v[22:23]
	s_waitcnt lgkmcnt(0)
	v_cvt_pk_bf16_f32 v12, v6, v7
	ds_read2_b32 v[6:7], v17 offset0:222 offset1:255
	s_waitcnt lgkmcnt(0)
	v_cvt_pk_bf16_f32 v13, v6, v7
	global_store_dwordx4 v[22:23], v[10:13], off
	s_waitcnt lgkmcnt(0)
	s_add_i32 s8, s8, s52
	s_cmpk_lt_i32 s8, 0x400
	s_cbranch_scc1 .LBB0_46

; #define PG8_STAGE(bufoff, gbase, voff) do { _Pragma("unroll") for (int _i = 0; _i < 2; ++_i) \
;         __builtin_amdgcn_global_load_lds((const unsigned*)((const char*)(gbase) + (voff)[_i]), (PG8_LAS unsigned*)(lds + (bufoff) + ldsw + _i * 8192), 16, 0, 0); } while (0)
; #define PG8_LDA(dst, b, h) do { _Pragma("unroll") for (int m = 0; m < 4; ++m) _Pragma("unroll") for (int k = 0; k < 2; ++k) dst[m][k] = *(const PG8_LAS bf16x8*)(lds + PG8_SA(b, h) + aoff + m * 2048 + k * 1024); } while (0)
; #define PG8_LDB(dst, b, h) do { _Pragma("unroll") for (int n = 0; n < 2; ++n) _Pragma("unroll") for (int k = 0; k < 2; ++k) dst[n][k] = *(const PG8_LAS bf16x8*)(lds + PG8_SB(b, h) + boff + n * 2048 + k * 1024); } while (0)
; #define PG8_MMA(ai, bj, At, Bt) do { __builtin_amdgcn_s_setprio(1); _Pragma("unroll") for (int m = 0; m < 4; ++m) _Pragma("unroll") for (int n = 0; n < 2; ++n) _Pragma("unroll") for (int k = 0; k < 2; ++k) \
;         acc[ai][bj][m][n] = __builtin_amdgcn_mfma_f32_16x16x32_bf16(Bt[n][k], At[m][k], acc[ai][bj][m][n], 0, 0, 0); __builtin_amdgcn_s_setprio(0); } while (0)
; #define PG8_WAIT_V(n) asm volatile("s_waitcnt vmcnt(" #n ")" ::: "memory")
; #define PG8_WAIT_L(n) asm volatile("s_waitcnt lgkmcnt(" #n ")" ::: "memory")
; #define PG8_BAR __builtin_amdgcn_s_barrier()
; #define PG8_SCHED __builtin_amdgcn_sched_barrier(0)
; template <class Epi, class Sched, bool ALIGN_EPI = false, bool SP2 = false>
; __device__ __forceinline__ void gemm_phase(PG8_LAS unsigned char* lds, const Gemm g, const Sched S, const Epi E) {
;     ...
;             PG8_LDB(B0, 0, 0); PG8_LDB(B1, 0, 1); PG8_SCHED; PG8_LDA(At, 0, 0); PG8_STAGE(PG8_SA(1, 1), a1 + hstep, voffA);
;             PG8_WAIT_V(8); PG8_WAIT_L(0); PG8_BAR; PG8_MMA(0, 0, At, B0); PG8_MMA(0, 1, At, B1); PG8_BAR; PG8_SCHED;
;             PG8_LDA(At, 0, 1); PG8_STAGE(PG8_SB(0, 0), b2, voffB); PG8_STAGE(PG8_SB(0, 1), b2 + hstep, voffB); PG8_STAGE(PG8_SA(0, 0), a2, voffA);
;             PG8_WAIT_V(8); PG8_WAIT_L(0); PG8_BAR; PG8_MMA(1, 0, At, B0); PG8_MMA(1, 1, At, B1); PG8_BAR; PG8_SCHED;
.LBB0_193:
	s_add_u32 s25, s56, 0xfff80080
	s_addc_u32 s26, s57, -1
	s_add_i32 s27, 0, 0x10000
	s_cmp_eq_u32 s24, 28
	s_cselect_b32 s65, s45, s26
	s_cselect_b32 s64, vcc_lo, s25
	v_add_u32_e32 v140, s27, v143
	s_cselect_b32 s59, s43, s15
	s_cselect_b32 s58, vcc_hi, s14
	s_add_i32 s25, 0, 0x14000
	ds_read_b128 v[146:149], v140
	ds_read_b128 v[150:153], v140 offset:1024
	ds_read_b128 v[154:157], v140 offset:2048
	ds_read_b128 v[158:161], v140 offset:3072
	v_add_u32_e32 v140, s25, v143
	ds_read_b128 v[168:171], v140
	ds_read_b128 v[172:175], v140 offset:1024
	ds_read_b128 v[176:179], v140 offset:2048
	ds_read_b128 v[180:183], v140 offset:3072
	v_lshl_add_u64 v[140:141], s[56:57], 0, v[136:137]
	s_add_i32 m0, s75, 0xc000
	ds_read_b128 v[184:187], v145
	ds_read_b128 v[188:191], v145 offset:1024
	ds_read_b128 v[192:195], v145 offset:2048
	ds_read_b128 v[196:199], v145 offset:3072
	ds_read_b128 v[200:203], v145 offset:4096
	ds_read_b128 v[224:227], v145 offset:5120
	ds_read_b128 v[228:231], v145 offset:6144
	ds_read_b128 v[232:235], v145 offset:7168
	global_load_lds_dwordx4 v[140:141], off
	v_lshl_add_u64 v[140:141], s[56:57], 0, v[138:139]
	s_add_i32 m0, s75, 0xe000
	s_nop 0
	global_load_lds_dwordx4 v[140:141], off
	s_waitcnt vmcnt(8)
	s_waitcnt lgkmcnt(0)
	s_barrier
	s_setprio 1
	v_mfma_f32_16x16x32_bf16 v[126:129], v[146:149], v[184:187], v[126:129]
	v_mfma_f32_16x16x32_bf16 v[126:129], v[150:153], v[188:191], v[126:129]
	v_mfma_f32_16x16x32_bf16 v[118:121], v[154:157], v[184:187], v[118:121]
	v_mfma_f32_16x16x32_bf16 v[118:121], v[158:161], v[188:191], v[118:121]
	v_mfma_f32_16x16x32_bf16 v[110:113], v[146:149], v[192:195], v[110:113]
	v_mfma_f32_16x16x32_bf16 v[110:113], v[150:153], v[196:199], v[110:113]
	v_mfma_f32_16x16x32_bf16 v[102:105], v[154:157], v[192:195], v[102:105]
	v_mfma_f32_16x16x32_bf16 v[102:105], v[158:161], v[196:199], v[102:105]
	v_mfma_f32_16x16x32_bf16 v[94:97], v[146:149], v[200:203], v[94:97]
	v_mfma_f32_16x16x32_bf16 v[94:97], v[150:153], v[224:227], v[94:97]
	v_mfma_f32_16x16x32_bf16 v[86:89], v[154:157], v[200:203], v[86:89]
	v_mfma_f32_16x16x32_bf16 v[86:89], v[158:161], v[224:227], v[86:89]
	v_mfma_f32_16x16x32_bf16 v[78:81], v[146:149], v[228:231], v[78:81]
	v_mfma_f32_16x16x32_bf16 v[78:81], v[150:153], v[232:235], v[78:81]
	v_mfma_f32_16x16x32_bf16 v[70:73], v[154:157], v[228:231], v[70:73]
	v_mfma_f32_16x16x32_bf16 v[70:73], v[158:161], v[232:235], v[70:73]
	v_mfma_f32_16x16x32_bf16 v[122:125], v[168:171], v[184:187], v[122:125]
	v_mfma_f32_16x16x32_bf16 v[122:125], v[172:175], v[188:191], v[122:125]
	v_mfma_f32_16x16x32_bf16 v[114:117], v[176:179], v[184:187], v[114:117]
	v_mfma_f32_16x16x32_bf16 v[114:117], v[180:183], v[188:191], v[114:117]
	v_mfma_f32_16x16x32_bf16 v[106:109], v[168:171], v[192:195], v[106:109]
	v_mfma_f32_16x16x32_bf16 v[106:109], v[172:175], v[196:199], v[106:109]
	v_mfma_f32_16x16x32_bf16 v[98:101], v[176:179], v[192:195], v[98:101]
	v_mfma_f32_16x16x32_bf16 v[98:101], v[180:183], v[196:199], v[98:101]
	v_mfma_f32_16x16x32_bf16 v[90:93], v[168:171], v[200:203], v[90:93]
	v_mfma_f32_16x16x32_bf16 v[90:93], v[172:175], v[224:227], v[90:93]
	v_mfma_f32_16x16x32_bf16 v[82:85], v[176:179], v[200:203], v[82:85]
	v_mfma_f32_16x16x32_bf16 v[82:85], v[180:183], v[224:227], v[82:85]
	v_mfma_f32_16x16x32_bf16 v[74:77], v[168:171], v[228:231], v[74:77]
	v_mfma_f32_16x16x32_bf16 v[74:77], v[172:175], v[232:235], v[74:77]
	v_mfma_f32_16x16x32_bf16 v[66:69], v[176:179], v[228:231], v[66:69]
	v_mfma_f32_16x16x32_bf16 v[66:69], v[180:183], v[232:235], v[66:69]
	s_setprio 0
	s_barrier
	s_add_i32 s26, s27, s74
	v_lshl_add_u64 v[140:141], s[58:59], 0, v[0:1]
	s_mov_b32 m0, s26
	ds_read_b128 v[184:187], v145 offset:16384
	ds_read_b128 v[188:191], v145 offset:17408
	ds_read_b128 v[192:195], v145 offset:18432
	ds_read_b128 v[196:199], v145 offset:19456
	ds_read_b128 v[200:203], v145 offset:20480
	ds_read_b128 v[224:227], v145 offset:21504
	ds_read_b128 v[228:231], v145 offset:22528
	ds_read_b128 v[232:235], v145 offset:23552
	global_load_lds_dwordx4 v[140:141], off
	s_add_i32 m0, s26, 0x2000
	s_add_u32 s26, s58, 0x80000
	v_lshl_add_u64 v[236:237], s[58:59], 0, v[130:131]
	s_addc_u32 s27, s59, 0
	s_add_i32 s25, s25, s74
	global_load_lds_dwordx4 v[236:237], off
	v_lshl_add_u64 v[238:239], s[26:27], 0, v[0:1]
	s_mov_b32 m0, s25
	v_lshl_add_u64 v[240:241], s[64:65], 0, v[132:133]
	global_load_lds_dwordx4 v[238:239], off
	v_lshl_add_u64 v[238:239], s[26:27], 0, v[130:131]
	s_add_i32 m0, s25, 0x2000
	s_nop 0
	global_load_lds_dwordx4 v[238:239], off
	v_lshl_add_u64 v[238:239], s[64:65], 0, v[134:135]
	s_mov_b32 m0, s75
	s_nop 0
	global_load_lds_dwordx4 v[238:239], off
	s_mov_b32 m0, s21
	s_nop 0
	global_load_lds_dwordx4 v[240:241], off
	s_waitcnt vmcnt(8)
	s_waitcnt lgkmcnt(0)
	s_barrier
; #define PG8_STAGE(bufoff, gbase, voff) do { _Pragma("unroll") for (int _i = 0; _i < 2; ++_i) \
;         __builtin_amdgcn_global_load_lds((const unsigned*)((const char*)(gbase) + (voff)[_i]), (PG8_LAS unsigned*)(lds + (bufoff) + ldsw + _i * 8192), 16, 0, 0); } while (0)
; #define PG8_LDA(dst, b, h) do { _Pragma("unroll") for (int m = 0; m < 4; ++m) _Pragma("unroll") for (int k = 0; k < 2; ++k) dst[m][k] = *(const PG8_LAS bf16x8*)(lds + PG8_SA(b, h) + aoff + m * 2048 + k * 1024); } while (0)
; #define PG8_LDB(dst, b, h) do { _Pragma("unroll") for (int n = 0; n < 2; ++n) _Pragma("unroll") for (int k = 0; k < 2; ++k) dst[n][k] = *(const PG8_LAS bf16x8*)(lds + PG8_SB(b, h) + boff + n * 2048 + k * 1024); } while (0)
; #define PG8_MMA(ai, bj, At, Bt) do { __builtin_amdgcn_s_setprio(1); _Pragma("unroll") for (int m = 0; m < 4; ++m) _Pragma("unroll") for (int n = 0; n < 2; ++n) _Pragma("unroll") for (int k = 0; k < 2; ++k) \
;         acc[ai][bj][m][n] = __builtin_amdgcn_mfma_f32_16x16x32_bf16(Bt[n][k], At[m][k], acc[ai][bj][m][n], 0, 0, 0); __builtin_amdgcn_s_setprio(0); } while (0)
; #define PG8_WAIT_V(n) asm volatile("s_waitcnt vmcnt(" #n ")" ::: "memory")
; #define PG8_WAIT_L(n) asm volatile("s_waitcnt lgkmcnt(" #n ")" ::: "memory")
; #define PG8_BAR __builtin_amdgcn_s_barrier()
; #define PG8_SCHED __builtin_amdgcn_sched_barrier(0)
; template <class Epi, class Sched, bool ALIGN_EPI = false, bool SP2 = false>
; __device__ __forceinline__ void gemm_phase(PG8_LAS unsigned char* lds, const Gemm g, const Sched S, const Epi E) {
;     ...
;             PG8_WAIT_V(8); PG8_WAIT_L(0); PG8_BAR; PG8_MMA(1, 0, At, B0); PG8_MMA(1, 1, At, B1); PG8_BAR; PG8_SCHED;
;             PG8_LDB(B0, 1, 0); PG8_LDB(B1, 1, 1); PG8_SCHED; PG8_LDA(At, 1, 0); PG8_STAGE(PG8_SA(0, 1), a2 + hstep, voffA);
;             PG8_WAIT_V(8); PG8_WAIT_L(0); PG8_BAR; PG8_MMA(0, 0, At, B0); PG8_MMA(0, 1, At, B1); PG8_BAR; PG8_SCHED;
	s_setprio 1
	v_mfma_f32_16x16x32_bf16 v[62:65], v[146:149], v[184:187], v[62:65]
	v_mfma_f32_16x16x32_bf16 v[62:65], v[150:153], v[188:191], v[62:65]
	v_mfma_f32_16x16x32_bf16 v[54:57], v[154:157], v[184:187], v[54:57]
	v_mfma_f32_16x16x32_bf16 v[54:57], v[158:161], v[188:191], v[54:57]
	v_mfma_f32_16x16x32_bf16 v[46:49], v[146:149], v[192:195], v[46:49]
	v_mfma_f32_16x16x32_bf16 v[46:49], v[150:153], v[196:199], v[46:49]
	v_mfma_f32_16x16x32_bf16 v[38:41], v[154:157], v[192:195], v[38:41]
	v_mfma_f32_16x16x32_bf16 v[38:41], v[158:161], v[196:199], v[38:41]
	v_mfma_f32_16x16x32_bf16 v[30:33], v[146:149], v[200:203], v[30:33]
	v_mfma_f32_16x16x32_bf16 v[30:33], v[150:153], v[224:227], v[30:33]
	v_mfma_f32_16x16x32_bf16 v[22:25], v[154:157], v[200:203], v[22:25]
	v_mfma_f32_16x16x32_bf16 v[22:25], v[158:161], v[224:227], v[22:25]
	v_mfma_f32_16x16x32_bf16 v[14:17], v[146:149], v[228:231], v[14:17]
	v_mfma_f32_16x16x32_bf16 v[14:17], v[150:153], v[232:235], v[14:17]
	v_mfma_f32_16x16x32_bf16 v[6:9], v[154:157], v[228:231], v[6:9]
	v_mfma_f32_16x16x32_bf16 v[6:9], v[158:161], v[232:235], v[6:9]
	v_mfma_f32_16x16x32_bf16 v[58:61], v[168:171], v[184:187], v[58:61]
	v_mfma_f32_16x16x32_bf16 v[58:61], v[172:175], v[188:191], v[58:61]
	v_mfma_f32_16x16x32_bf16 v[50:53], v[176:179], v[184:187], v[50:53]
	v_mfma_f32_16x16x32_bf16 v[50:53], v[180:183], v[188:191], v[50:53]
	v_mfma_f32_16x16x32_bf16 v[42:45], v[168:171], v[192:195], v[42:45]
	v_mfma_f32_16x16x32_bf16 v[42:45], v[172:175], v[196:199], v[42:45]
	v_mfma_f32_16x16x32_bf16 v[34:37], v[176:179], v[192:195], v[34:37]
	v_mfma_f32_16x16x32_bf16 v[34:37], v[180:183], v[196:199], v[34:37]
	v_mfma_f32_16x16x32_bf16 v[26:29], v[168:171], v[200:203], v[26:29]
	v_mfma_f32_16x16x32_bf16 v[26:29], v[172:175], v[224:227], v[26:29]
	v_mfma_f32_16x16x32_bf16 v[18:21], v[176:179], v[200:203], v[18:21]
	v_mfma_f32_16x16x32_bf16 v[18:21], v[180:183], v[224:227], v[18:21]
	v_mfma_f32_16x16x32_bf16 v[10:13], v[168:171], v[228:231], v[10:13]
	v_mfma_f32_16x16x32_bf16 v[10:13], v[172:175], v[232:235], v[10:13]
	v_mfma_f32_16x16x32_bf16 v[2:5], v[176:179], v[228:231], v[2:5]
	v_mfma_f32_16x16x32_bf16 v[2:5], v[180:183], v[232:235], v[2:5]
	s_setprio 0
	s_barrier
	s_add_i32 s25, 0, 0x18000
	s_add_i32 s30, 0, 0x1c000
	v_add_u32_e32 v158, s25, v143
	v_add_u32_e32 v167, s30, v143
	ds_read_b128 v[146:149], v158
	ds_read_b128 v[150:153], v158 offset:1024
	ds_read_b128 v[154:157], v158 offset:2048
	ds_read_b128 v[158:161], v158 offset:3072
	ds_read_b128 v[168:171], v167
	ds_read_b128 v[172:175], v167 offset:1024
	ds_read_b128 v[176:179], v167 offset:2048
	ds_read_b128 v[180:183], v167 offset:3072
	s_add_u32 s26, s64, 0x80000
	s_addc_u32 s27, s65, 0
	s_mov_b32 m0, s47
	v_lshl_add_u64 v[242:243], s[26:27], 0, v[134:135]
	ds_read_b128 v[184:187], v145 offset:32768
	ds_read_b128 v[188:191], v145 offset:33792
	ds_read_b128 v[192:195], v145 offset:34816
	ds_read_b128 v[196:199], v145 offset:35840
	ds_read_b128 v[200:203], v145 offset:36864
	ds_read_b128 v[224:227], v145 offset:37888
	ds_read_b128 v[228:231], v145 offset:38912
	ds_read_b128 v[232:235], v145 offset:39936
	global_load_lds_dwordx4 v[242:243], off
	v_lshl_add_u64 v[242:243], s[26:27], 0, v[132:133]
	s_mov_b32 m0, s77
	s_nop 0
	global_load_lds_dwordx4 v[242:243], off
	s_waitcnt vmcnt(8)
	s_waitcnt lgkmcnt(0)
	s_barrier
	s_setprio 1
	v_mfma_f32_16x16x32_bf16 v[126:129], v[146:149], v[184:187], v[126:129]
	v_mfma_f32_16x16x32_bf16 v[126:129], v[150:153], v[188:191], v[126:129]
	v_mfma_f32_16x16x32_bf16 v[118:121], v[154:157], v[184:187], v[118:121]
	v_mfma_f32_16x16x32_bf16 v[118:121], v[158:161], v[188:191], v[118:121]
	v_mfma_f32_16x16x32_bf16 v[110:113], v[146:149], v[192:195], v[110:113]
	v_mfma_f32_16x16x32_bf16 v[110:113], v[150:153], v[196:199], v[110:113]
	v_mfma_f32_16x16x32_bf16 v[102:105], v[154:157], v[192:195], v[102:105]
	v_mfma_f32_16x16x32_bf16 v[102:105], v[158:161], v[196:199], v[102:105]
	v_mfma_f32_16x16x32_bf16 v[94:97], v[146:149], v[200:203], v[94:97]
	v_mfma_f32_16x16x32_bf16 v[94:97], v[150:153], v[224:227], v[94:97]
	v_mfma_f32_16x16x32_bf16 v[86:89], v[154:157], v[200:203], v[86:89]
	v_mfma_f32_16x16x32_bf16 v[86:89], v[158:161], v[224:227], v[86:89]
	v_mfma_f32_16x16x32_bf16 v[78:81], v[146:149], v[228:231], v[78:81]
	v_mfma_f32_16x16x32_bf16 v[78:81], v[150:153], v[232:235], v[78:81]
	v_mfma_f32_16x16x32_bf16 v[70:73], v[154:157], v[228:231], v[70:73]
	v_mfma_f32_16x16x32_bf16 v[70:73], v[158:161], v[232:235], v[70:73]
	v_mfma_f32_16x16x32_bf16 v[122:125], v[168:171], v[184:187], v[122:125]
	v_mfma_f32_16x16x32_bf16 v[122:125], v[172:175], v[188:191], v[122:125]
	v_mfma_f32_16x16x32_bf16 v[114:117], v[176:179], v[184:187], v[114:117]
	v_mfma_f32_16x16x32_bf16 v[114:117], v[180:183], v[188:191], v[114:117]
	v_mfma_f32_16x16x32_bf16 v[106:109], v[168:171], v[192:195], v[106:109]
	v_mfma_f32_16x16x32_bf16 v[106:109], v[172:175], v[196:199], v[106:109]
	v_mfma_f32_16x16x32_bf16 v[98:101], v[176:179], v[192:195], v[98:101]
	v_mfma_f32_16x16x32_bf16 v[98:101], v[180:183], v[196:199], v[98:101]
	v_mfma_f32_16x16x32_bf16 v[90:93], v[168:171], v[200:203], v[90:93]
	v_mfma_f32_16x16x32_bf16 v[90:93], v[172:175], v[224:227], v[90:93]
	v_mfma_f32_16x16x32_bf16 v[82:85], v[176:179], v[200:203], v[82:85]
	v_mfma_f32_16x16x32_bf16 v[82:85], v[180:183], v[224:227], v[82:85]
	v_mfma_f32_16x16x32_bf16 v[74:77], v[168:171], v[228:231], v[74:77]
	v_mfma_f32_16x16x32_bf16 v[74:77], v[172:175], v[232:235], v[74:77]
	v_mfma_f32_16x16x32_bf16 v[66:69], v[176:179], v[228:231], v[66:69]
	v_mfma_f32_16x16x32_bf16 v[66:69], v[180:183], v[232:235], v[66:69]
	s_setprio 0
	s_barrier
; #define PG8_STAGE(bufoff, gbase, voff) do { _Pragma("unroll") for (int _i = 0; _i < 2; ++_i) \
;         __builtin_amdgcn_global_load_lds((const unsigned*)((const char*)(gbase) + (voff)[_i]), (PG8_LAS unsigned*)(lds + (bufoff) + ldsw + _i * 8192), 16, 0, 0); } while (0)
; #define PG8_LDA(dst, b, h) do { _Pragma("unroll") for (int m = 0; m < 4; ++m) _Pragma("unroll") for (int k = 0; k < 2; ++k) dst[m][k] = *(const PG8_LAS bf16x8*)(lds + PG8_SA(b, h) + aoff + m * 2048 + k * 1024); } while (0)
; #define PG8_MMA(ai, bj, At, Bt) do { __builtin_amdgcn_s_setprio(1); _Pragma("unroll") for (int m = 0; m < 4; ++m) _Pragma("unroll") for (int n = 0; n < 2; ++n) _Pragma("unroll") for (int k = 0; k < 2; ++k) \
;         acc[ai][bj][m][n] = __builtin_amdgcn_mfma_f32_16x16x32_bf16(Bt[n][k], At[m][k], acc[ai][bj][m][n], 0, 0, 0); __builtin_amdgcn_s_setprio(0); } while (0)
; #define PG8_WAIT_V(n) asm volatile("s_waitcnt vmcnt(" #n ")" ::: "memory")
; #define PG8_WAIT_L(n) asm volatile("s_waitcnt lgkmcnt(" #n ")" ::: "memory")
; #define PG8_BAR __builtin_amdgcn_s_barrier()
; #define PG8_SCHED __builtin_amdgcn_sched_barrier(0)
; template <class Epi, class Sched, bool ALIGN_EPI = false, bool SP2 = false>
; __device__ __forceinline__ void gemm_phase(PG8_LAS unsigned char* lds, const Gemm g, const Sched S, const Epi E) {
;     ...
;         for (int t = 0; t < nt; t += 2) {
;             const bool last = (t == nt - 2);
;             const char* a1 = cA + (size_t)(t + 1) * kstep;
;             const char* a2 = last ? nA : cA + (size_t)(t + 2) * kstep; const char* b2 = last ? nB : cB + (size_t)(t + 2) * kstep;
;     ...
;             PG8_LDA(At, 1, 1); PG8_STAGE(PG8_SB(1, 0), b3, voffB); PG8_STAGE(PG8_SB(1, 1), b3 + hstep, voffB); PG8_STAGE(PG8_SA(1, 0), a3, voffA);
;             PG8_WAIT_V(8); PG8_WAIT_L(0); PG8_BAR; PG8_MMA(1, 0, At, B0); PG8_MMA(1, 1, At, B1); PG8_BAR; PG8_SCHED;
	s_add_i32 s25, s25, s74
	v_lshl_add_u64 v[140:141], v[140:141], 0, s[28:29]
	s_mov_b32 m0, s25
	ds_read_b128 v[184:187], v145 offset:49152
	ds_read_b128 v[188:191], v145 offset:50176
	ds_read_b128 v[192:195], v145 offset:51200
	ds_read_b128 v[196:199], v145 offset:52224
	ds_read_b128 v[200:203], v145 offset:53248
	ds_read_b128 v[224:227], v145 offset:54272
	ds_read_b128 v[228:231], v145 offset:55296
	ds_read_b128 v[232:235], v145 offset:56320
	global_load_lds_dwordx4 v[140:141], off
	s_add_i32 m0, s25, 0x2000
	s_add_u32 s26, s58, 0x80080
	v_lshl_add_u64 v[140:141], v[236:237], 0, s[28:29]
	s_addc_u32 s27, s59, 0
	s_add_i32 s25, s30, s74
	global_load_lds_dwordx4 v[140:141], off
	v_lshl_add_u64 v[140:141], s[26:27], 0, v[0:1]
	s_mov_b32 m0, s25
	s_nop 0
	global_load_lds_dwordx4 v[140:141], off
	v_lshl_add_u64 v[140:141], s[26:27], 0, v[130:131]
	s_add_i32 m0, s25, 0x2000
	s_nop 0
	global_load_lds_dwordx4 v[140:141], off
	v_lshl_add_u64 v[140:141], v[238:239], 0, s[28:29]
	s_mov_b32 m0, s62
	s_nop 0
	global_load_lds_dwordx4 v[140:141], off
	v_lshl_add_u64 v[140:141], v[240:241], 0, s[28:29]
	s_mov_b32 m0, s63
	s_nop 0
	global_load_lds_dwordx4 v[140:141], off
	s_waitcnt vmcnt(8)
	s_waitcnt lgkmcnt(0)
	s_barrier
	s_setprio 1
	v_mfma_f32_16x16x32_bf16 v[62:65], v[146:149], v[184:187], v[62:65]
	v_mfma_f32_16x16x32_bf16 v[62:65], v[150:153], v[188:191], v[62:65]
	v_mfma_f32_16x16x32_bf16 v[54:57], v[154:157], v[184:187], v[54:57]
	v_mfma_f32_16x16x32_bf16 v[54:57], v[158:161], v[188:191], v[54:57]
	v_mfma_f32_16x16x32_bf16 v[46:49], v[146:149], v[192:195], v[46:49]
	v_mfma_f32_16x16x32_bf16 v[46:49], v[150:153], v[196:199], v[46:49]
	v_mfma_f32_16x16x32_bf16 v[38:41], v[154:157], v[192:195], v[38:41]
	v_mfma_f32_16x16x32_bf16 v[38:41], v[158:161], v[196:199], v[38:41]
	v_mfma_f32_16x16x32_bf16 v[30:33], v[146:149], v[200:203], v[30:33]
	v_mfma_f32_16x16x32_bf16 v[30:33], v[150:153], v[224:227], v[30:33]
	v_mfma_f32_16x16x32_bf16 v[22:25], v[154:157], v[200:203], v[22:25]
	v_mfma_f32_16x16x32_bf16 v[22:25], v[158:161], v[224:227], v[22:25]
	v_mfma_f32_16x16x32_bf16 v[14:17], v[146:149], v[228:231], v[14:17]
	v_mfma_f32_16x16x32_bf16 v[14:17], v[150:153], v[232:235], v[14:17]
	v_mfma_f32_16x16x32_bf16 v[6:9], v[154:157], v[228:231], v[6:9]
	v_mfma_f32_16x16x32_bf16 v[6:9], v[158:161], v[232:235], v[6:9]
	v_mfma_f32_16x16x32_bf16 v[58:61], v[168:171], v[184:187], v[58:61]
	v_mfma_f32_16x16x32_bf16 v[58:61], v[172:175], v[188:191], v[58:61]
	v_mfma_f32_16x16x32_bf16 v[50:53], v[176:179], v[184:187], v[50:53]
	v_mfma_f32_16x16x32_bf16 v[50:53], v[180:183], v[188:191], v[50:53]
	v_mfma_f32_16x16x32_bf16 v[42:45], v[168:171], v[192:195], v[42:45]
	v_mfma_f32_16x16x32_bf16 v[42:45], v[172:175], v[196:199], v[42:45]
	v_mfma_f32_16x16x32_bf16 v[34:37], v[176:179], v[192:195], v[34:37]
	v_mfma_f32_16x16x32_bf16 v[34:37], v[180:183], v[196:199], v[34:37]
	v_mfma_f32_16x16x32_bf16 v[26:29], v[168:171], v[200:203], v[26:29]
	v_mfma_f32_16x16x32_bf16 v[26:29], v[172:175], v[224:227], v[26:29]
	v_mfma_f32_16x16x32_bf16 v[18:21], v[176:179], v[200:203], v[18:21]
	v_mfma_f32_16x16x32_bf16 v[18:21], v[180:183], v[224:227], v[18:21]
	v_mfma_f32_16x16x32_bf16 v[10:13], v[168:171], v[228:231], v[10:13]
	v_mfma_f32_16x16x32_bf16 v[10:13], v[172:175], v[232:235], v[10:13]
	v_mfma_f32_16x16x32_bf16 v[2:5], v[176:179], v[228:231], v[2:5]
	v_mfma_f32_16x16x32_bf16 v[2:5], v[180:183], v[232:235], v[2:5]
	s_setprio 0
	s_barrier
	s_add_i32 s24, s24, 2
	s_add_u32 s56, s56, 0x100
	s_addc_u32 s57, s57, 0
	s_add_u32 s14, s14, 0x100
	s_addc_u32 s15, s15, 0
	s_cmp_gt_u32 s24, 29
	s_cbranch_scc0 .LBB0_193
	s_and_b64 vcc, exec, s[40:41]
	s_cbranch_vccz .LBB0_196
	s_barrier

; #define PG8_STAGE(bufoff, gbase, voff) do { _Pragma("unroll") for (int _i = 0; _i < 2; ++_i) \
;         __builtin_amdgcn_global_load_lds((const unsigned*)((const char*)(gbase) + (voff)[_i]), (PG8_LAS unsigned*)(lds + (bufoff) + ldsw + _i * 8192), 16, 0, 0); } while (0)
; #define PG8_LDA(dst, b, h) do { _Pragma("unroll") for (int m = 0; m < 4; ++m) _Pragma("unroll") for (int k = 0; k < 2; ++k) dst[m][k] = *(const PG8_LAS bf16x8*)(lds + PG8_SA(b, h) + aoff + m * 2048 + k * 1024); } while (0)
; #define PG8_LDB(dst, b, h) do { _Pragma("unroll") for (int n = 0; n < 2; ++n) _Pragma("unroll") for (int k = 0; k < 2; ++k) dst[n][k] = *(const PG8_LAS bf16x8*)(lds + PG8_SB(b, h) + boff + n * 2048 + k * 1024); } while (0)
; #define PG8_MMA(ai, bj, At, Bt) do { __builtin_amdgcn_s_setprio(1); _Pragma("unroll") for (int m = 0; m < 4; ++m) _Pragma("unroll") for (int n = 0; n < 2; ++n) _Pragma("unroll") for (int k = 0; k < 2; ++k) \
;         acc[ai][bj][m][n] = __builtin_amdgcn_mfma_f32_16x16x32_bf16(Bt[n][k], At[m][k], acc[ai][bj][m][n], 0, 0, 0); __builtin_amdgcn_s_setprio(0); } while (0)
; #define PG8_WAIT_V(n) asm volatile("s_waitcnt vmcnt(" #n ")" ::: "memory")
; #define PG8_WAIT_L(n) asm volatile("s_waitcnt lgkmcnt(" #n ")" ::: "memory")
; #define PG8_BAR __builtin_amdgcn_s_barrier()
; #define PG8_SCHED __builtin_amdgcn_sched_barrier(0)
; template <class Epi, class Sched, bool ALIGN_EPI = false, bool SP2 = false>
; __device__ __forceinline__ void gemm_phase(PG8_LAS unsigned char* lds, const Gemm g, const Sched S, const Epi E) {
;     ...
;             PG8_LDB(B0, 0, 0); PG8_LDB(B1, 0, 1); PG8_SCHED; PG8_LDA(At, 0, 0); PG8_STAGE(PG8_SA(1, 1), a1 + hstep, voffA);
;             PG8_WAIT_V(8); PG8_WAIT_L(0); PG8_BAR; PG8_MMA(0, 0, At, B0); PG8_MMA(0, 1, At, B1); PG8_BAR; PG8_SCHED;
;             PG8_LDA(At, 0, 1); PG8_STAGE(PG8_SB(0, 0), b2, voffB); PG8_STAGE(PG8_SB(0, 1), b2 + hstep, voffB); PG8_STAGE(PG8_SA(0, 0), a2, voffA);
;             PG8_WAIT_V(8); PG8_WAIT_L(0); PG8_BAR; PG8_MMA(1, 0, At, B0); PG8_MMA(1, 1, At, B1); PG8_BAR; PG8_SCHED;
.LBB0_272:
	s_add_u32 s52, s50, 0x100
	s_addc_u32 s53, s51, 0
	s_add_i32 s24, 0, 0x10000
	s_cmpk_eq_i32 s15, 0x54
	s_cselect_b32 s59, s1, s53
	s_cselect_b32 s58, s0, s52
	v_add_u32_e32 v140, s24, v143
	s_cselect_b32 s57, s45, s14
	s_cselect_b32 s56, s44, s5
	s_add_i32 s26, 0, 0x14000
	ds_read_b128 v[136:139], v140
	ds_read_b128 v[146:149], v140 offset:1024
	ds_read_b128 v[150:153], v140 offset:2048
	ds_read_b128 v[154:157], v140 offset:3072
	v_add_u32_e32 v140, s26, v143
	ds_read_b128 v[158:161], v140
	ds_read_b128 v[168:171], v140 offset:1024
	ds_read_b128 v[172:175], v140 offset:2048
	ds_read_b128 v[176:179], v140 offset:3072
	v_lshl_add_u64 v[140:141], s[50:51], 0, v[132:133]
	s_add_i32 m0, s47, 0xc000
	ds_read_b128 v[180:183], v145
	ds_read_b128 v[184:187], v145 offset:1024
	ds_read_b128 v[188:191], v145 offset:2048
	ds_read_b128 v[192:195], v145 offset:3072
	ds_read_b128 v[196:199], v145 offset:4096
	ds_read_b128 v[200:203], v145 offset:5120
	ds_read_b128 v[224:227], v145 offset:6144
	ds_read_b128 v[228:231], v145 offset:7168
	global_load_lds_dwordx4 v[140:141], off
	v_lshl_add_u64 v[140:141], s[50:51], 0, v[134:135]
	s_add_i32 m0, s47, 0xe000
	s_nop 0
	global_load_lds_dwordx4 v[140:141], off
	s_waitcnt vmcnt(8)
	s_waitcnt lgkmcnt(0)
	s_barrier
	s_setprio 1
	v_mfma_f32_16x16x32_bf16 v[126:129], v[136:139], v[180:183], v[126:129]
	v_mfma_f32_16x16x32_bf16 v[126:129], v[146:149], v[184:187], v[126:129]
	v_mfma_f32_16x16x32_bf16 v[122:125], v[150:153], v[180:183], v[122:125]
	v_mfma_f32_16x16x32_bf16 v[122:125], v[154:157], v[184:187], v[122:125]
	v_mfma_f32_16x16x32_bf16 v[110:113], v[136:139], v[188:191], v[110:113]
	v_mfma_f32_16x16x32_bf16 v[110:113], v[146:149], v[192:195], v[110:113]
	v_mfma_f32_16x16x32_bf16 v[106:109], v[150:153], v[188:191], v[106:109]
	v_mfma_f32_16x16x32_bf16 v[106:109], v[154:157], v[192:195], v[106:109]
	v_mfma_f32_16x16x32_bf16 v[94:97], v[136:139], v[196:199], v[94:97]
	v_mfma_f32_16x16x32_bf16 v[94:97], v[146:149], v[200:203], v[94:97]
	v_mfma_f32_16x16x32_bf16 v[90:93], v[150:153], v[196:199], v[90:93]
	v_mfma_f32_16x16x32_bf16 v[90:93], v[154:157], v[200:203], v[90:93]
	v_mfma_f32_16x16x32_bf16 v[78:81], v[136:139], v[224:227], v[78:81]
	v_mfma_f32_16x16x32_bf16 v[78:81], v[146:149], v[228:231], v[78:81]
	v_mfma_f32_16x16x32_bf16 v[74:77], v[150:153], v[224:227], v[74:77]
	v_mfma_f32_16x16x32_bf16 v[74:77], v[154:157], v[228:231], v[74:77]
	v_mfma_f32_16x16x32_bf16 v[118:121], v[158:161], v[180:183], v[118:121]
	v_mfma_f32_16x16x32_bf16 v[118:121], v[168:171], v[184:187], v[118:121]
	v_mfma_f32_16x16x32_bf16 v[114:117], v[172:175], v[180:183], v[114:117]
	v_mfma_f32_16x16x32_bf16 v[114:117], v[176:179], v[184:187], v[114:117]
	v_mfma_f32_16x16x32_bf16 v[102:105], v[158:161], v[188:191], v[102:105]
	v_mfma_f32_16x16x32_bf16 v[102:105], v[168:171], v[192:195], v[102:105]
	v_mfma_f32_16x16x32_bf16 v[98:101], v[172:175], v[188:191], v[98:101]
	v_mfma_f32_16x16x32_bf16 v[98:101], v[176:179], v[192:195], v[98:101]
	v_mfma_f32_16x16x32_bf16 v[86:89], v[158:161], v[196:199], v[86:89]
	v_mfma_f32_16x16x32_bf16 v[86:89], v[168:171], v[200:203], v[86:89]
	v_mfma_f32_16x16x32_bf16 v[82:85], v[172:175], v[196:199], v[82:85]
	v_mfma_f32_16x16x32_bf16 v[82:85], v[176:179], v[200:203], v[82:85]
	v_mfma_f32_16x16x32_bf16 v[70:73], v[158:161], v[224:227], v[70:73]
	v_mfma_f32_16x16x32_bf16 v[70:73], v[168:171], v[228:231], v[70:73]
	v_mfma_f32_16x16x32_bf16 v[66:69], v[172:175], v[224:227], v[66:69]
	v_mfma_f32_16x16x32_bf16 v[66:69], v[176:179], v[228:231], v[66:69]
	s_setprio 0
	s_barrier
	s_add_i32 s24, s24, s22
	v_lshl_add_u64 v[140:141], s[56:57], 0, v[0:1]
	s_mov_b32 m0, s24
	ds_read_b128 v[180:183], v145 offset:16384
	ds_read_b128 v[184:187], v145 offset:17408
	ds_read_b128 v[188:191], v145 offset:18432
	ds_read_b128 v[192:195], v145 offset:19456
	ds_read_b128 v[196:199], v145 offset:20480
	ds_read_b128 v[200:203], v145 offset:21504
	ds_read_b128 v[224:227], v145 offset:22528
	ds_read_b128 v[228:231], v145 offset:23552
	global_load_lds_dwordx4 v[140:141], off
	s_add_i32 m0, s24, 0x2000
	s_add_u32 s24, s56, 0x160000
	v_lshl_add_u64 v[232:233], s[56:57], 0, v[130:131]
	s_addc_u32 s25, s57, 0
	s_add_i32 s26, s26, s22
	global_load_lds_dwordx4 v[232:233], off
	v_lshl_add_u64 v[234:235], s[24:25], 0, v[0:1]
	s_mov_b32 m0, s26
	v_lshl_add_u64 v[236:237], s[58:59], 0, v[130:131]
	global_load_lds_dwordx4 v[234:235], off
	v_lshl_add_u64 v[234:235], s[24:25], 0, v[130:131]
	s_add_i32 m0, s26, 0x2000
	s_nop 0
	global_load_lds_dwordx4 v[234:235], off
	v_lshl_add_u64 v[234:235], s[58:59], 0, v[0:1]
	s_mov_b32 m0, s47
	s_nop 0
	global_load_lds_dwordx4 v[234:235], off
	s_mov_b32 m0, s62
	s_nop 0
	global_load_lds_dwordx4 v[236:237], off
	s_waitcnt vmcnt(8)
	s_waitcnt lgkmcnt(0)
	s_barrier
; #define PG8_STAGE(bufoff, gbase, voff) do { _Pragma("unroll") for (int _i = 0; _i < 2; ++_i) \
;         __builtin_amdgcn_global_load_lds((const unsigned*)((const char*)(gbase) + (voff)[_i]), (PG8_LAS unsigned*)(lds + (bufoff) + ldsw + _i * 8192), 16, 0, 0); } while (0)
; #define PG8_LDA(dst, b, h) do { _Pragma("unroll") for (int m = 0; m < 4; ++m) _Pragma("unroll") for (int k = 0; k < 2; ++k) dst[m][k] = *(const PG8_LAS bf16x8*)(lds + PG8_SA(b, h) + aoff + m * 2048 + k * 1024); } while (0)
; #define PG8_LDB(dst, b, h) do { _Pragma("unroll") for (int n = 0; n < 2; ++n) _Pragma("unroll") for (int k = 0; k < 2; ++k) dst[n][k] = *(const PG8_LAS bf16x8*)(lds + PG8_SB(b, h) + boff + n * 2048 + k * 1024); } while (0)
; #define PG8_MMA(ai, bj, At, Bt) do { __builtin_amdgcn_s_setprio(1); _Pragma("unroll") for (int m = 0; m < 4; ++m) _Pragma("unroll") for (int n = 0; n < 2; ++n) _Pragma("unroll") for (int k = 0; k < 2; ++k) \
;         acc[ai][bj][m][n] = __builtin_amdgcn_mfma_f32_16x16x32_bf16(Bt[n][k], At[m][k], acc[ai][bj][m][n], 0, 0, 0); __builtin_amdgcn_s_setprio(0); } while (0)
; #define PG8_WAIT_V(n) asm volatile("s_waitcnt vmcnt(" #n ")" ::: "memory")
; #define PG8_WAIT_L(n) asm volatile("s_waitcnt lgkmcnt(" #n ")" ::: "memory")
; #define PG8_BAR __builtin_amdgcn_s_barrier()
; #define PG8_SCHED __builtin_amdgcn_sched_barrier(0)
; template <class Epi, class Sched, bool ALIGN_EPI = false, bool SP2 = false>
; __device__ __forceinline__ void gemm_phase(PG8_LAS unsigned char* lds, const Gemm g, const Sched S, const Epi E) {
;     ...
;             PG8_WAIT_V(8); PG8_WAIT_L(0); PG8_BAR; PG8_MMA(1, 0, At, B0); PG8_MMA(1, 1, At, B1); PG8_BAR; PG8_SCHED;
;             PG8_LDB(B0, 1, 0); PG8_LDB(B1, 1, 1); PG8_SCHED; PG8_LDA(At, 1, 0); PG8_STAGE(PG8_SA(0, 1), a2 + hstep, voffA);
;             PG8_WAIT_V(8); PG8_WAIT_L(0); PG8_BAR; PG8_MMA(0, 0, At, B0); PG8_MMA(0, 1, At, B1); PG8_BAR; PG8_SCHED;
	s_setprio 1
	v_mfma_f32_16x16x32_bf16 v[62:65], v[136:139], v[180:183], v[62:65]
	v_mfma_f32_16x16x32_bf16 v[62:65], v[146:149], v[184:187], v[62:65]
	v_mfma_f32_16x16x32_bf16 v[58:61], v[150:153], v[180:183], v[58:61]
	v_mfma_f32_16x16x32_bf16 v[58:61], v[154:157], v[184:187], v[58:61]
	v_mfma_f32_16x16x32_bf16 v[46:49], v[136:139], v[188:191], v[46:49]
	v_mfma_f32_16x16x32_bf16 v[46:49], v[146:149], v[192:195], v[46:49]
	v_mfma_f32_16x16x32_bf16 v[42:45], v[150:153], v[188:191], v[42:45]
	v_mfma_f32_16x16x32_bf16 v[42:45], v[154:157], v[192:195], v[42:45]
	v_mfma_f32_16x16x32_bf16 v[30:33], v[136:139], v[196:199], v[30:33]
	v_mfma_f32_16x16x32_bf16 v[30:33], v[146:149], v[200:203], v[30:33]
	v_mfma_f32_16x16x32_bf16 v[26:29], v[150:153], v[196:199], v[26:29]
	v_mfma_f32_16x16x32_bf16 v[26:29], v[154:157], v[200:203], v[26:29]
	v_mfma_f32_16x16x32_bf16 v[14:17], v[136:139], v[224:227], v[14:17]
	v_mfma_f32_16x16x32_bf16 v[14:17], v[146:149], v[228:231], v[14:17]
	v_mfma_f32_16x16x32_bf16 v[10:13], v[150:153], v[224:227], v[10:13]
	v_mfma_f32_16x16x32_bf16 v[10:13], v[154:157], v[228:231], v[10:13]
	v_mfma_f32_16x16x32_bf16 v[54:57], v[158:161], v[180:183], v[54:57]
	v_mfma_f32_16x16x32_bf16 v[54:57], v[168:171], v[184:187], v[54:57]
	v_mfma_f32_16x16x32_bf16 v[50:53], v[172:175], v[180:183], v[50:53]
	v_mfma_f32_16x16x32_bf16 v[50:53], v[176:179], v[184:187], v[50:53]
	v_mfma_f32_16x16x32_bf16 v[38:41], v[158:161], v[188:191], v[38:41]
	v_mfma_f32_16x16x32_bf16 v[38:41], v[168:171], v[192:195], v[38:41]
	v_mfma_f32_16x16x32_bf16 v[34:37], v[172:175], v[188:191], v[34:37]
	v_mfma_f32_16x16x32_bf16 v[34:37], v[176:179], v[192:195], v[34:37]
	v_mfma_f32_16x16x32_bf16 v[22:25], v[158:161], v[196:199], v[22:25]
	v_mfma_f32_16x16x32_bf16 v[22:25], v[168:171], v[200:203], v[22:25]
	v_mfma_f32_16x16x32_bf16 v[18:21], v[172:175], v[196:199], v[18:21]
	v_mfma_f32_16x16x32_bf16 v[18:21], v[176:179], v[200:203], v[18:21]
	v_mfma_f32_16x16x32_bf16 v[6:9], v[158:161], v[224:227], v[6:9]
	v_mfma_f32_16x16x32_bf16 v[6:9], v[168:171], v[228:231], v[6:9]
	v_mfma_f32_16x16x32_bf16 v[2:5], v[172:175], v[224:227], v[2:5]
	v_mfma_f32_16x16x32_bf16 v[2:5], v[176:179], v[228:231], v[2:5]
	s_setprio 0
	s_barrier
	s_add_i32 s26, 0, 0x18000
	s_add_i32 s27, 0, 0x1c000
	v_add_u32_e32 v154, s26, v143
	v_add_u32_e32 v167, s27, v143
	ds_read_b128 v[136:139], v154
	ds_read_b128 v[146:149], v154 offset:1024
	ds_read_b128 v[150:153], v154 offset:2048
	ds_read_b128 v[154:157], v154 offset:3072
	ds_read_b128 v[158:161], v167
	ds_read_b128 v[168:171], v167 offset:1024
	ds_read_b128 v[172:175], v167 offset:2048
	ds_read_b128 v[176:179], v167 offset:3072
	s_add_u32 s24, s58, 0x160000
	s_addc_u32 s25, s59, 0
	s_mov_b32 m0, s63
	v_lshl_add_u64 v[238:239], s[24:25], 0, v[0:1]
	ds_read_b128 v[180:183], v145 offset:32768
	ds_read_b128 v[184:187], v145 offset:33792
	ds_read_b128 v[188:191], v145 offset:34816
	ds_read_b128 v[192:195], v145 offset:35840
	ds_read_b128 v[196:199], v145 offset:36864
	ds_read_b128 v[200:203], v145 offset:37888
	ds_read_b128 v[224:227], v145 offset:38912
	ds_read_b128 v[228:231], v145 offset:39936
	global_load_lds_dwordx4 v[238:239], off
	v_lshl_add_u64 v[238:239], s[24:25], 0, v[130:131]
	s_mov_b32 m0, s64
	s_nop 0
	global_load_lds_dwordx4 v[238:239], off
	s_waitcnt vmcnt(8)
	s_waitcnt lgkmcnt(0)
	s_barrier
	s_setprio 1
	v_mfma_f32_16x16x32_bf16 v[126:129], v[136:139], v[180:183], v[126:129]
	v_mfma_f32_16x16x32_bf16 v[126:129], v[146:149], v[184:187], v[126:129]
	v_mfma_f32_16x16x32_bf16 v[122:125], v[150:153], v[180:183], v[122:125]
	v_mfma_f32_16x16x32_bf16 v[122:125], v[154:157], v[184:187], v[122:125]
	v_mfma_f32_16x16x32_bf16 v[110:113], v[136:139], v[188:191], v[110:113]
	v_mfma_f32_16x16x32_bf16 v[110:113], v[146:149], v[192:195], v[110:113]
	v_mfma_f32_16x16x32_bf16 v[106:109], v[150:153], v[188:191], v[106:109]
	v_mfma_f32_16x16x32_bf16 v[106:109], v[154:157], v[192:195], v[106:109]
	v_mfma_f32_16x16x32_bf16 v[94:97], v[136:139], v[196:199], v[94:97]
	v_mfma_f32_16x16x32_bf16 v[94:97], v[146:149], v[200:203], v[94:97]
	v_mfma_f32_16x16x32_bf16 v[90:93], v[150:153], v[196:199], v[90:93]
	v_mfma_f32_16x16x32_bf16 v[90:93], v[154:157], v[200:203], v[90:93]
	v_mfma_f32_16x16x32_bf16 v[78:81], v[136:139], v[224:227], v[78:81]
	v_mfma_f32_16x16x32_bf16 v[78:81], v[146:149], v[228:231], v[78:81]
	v_mfma_f32_16x16x32_bf16 v[74:77], v[150:153], v[224:227], v[74:77]
	v_mfma_f32_16x16x32_bf16 v[74:77], v[154:157], v[228:231], v[74:77]
	v_mfma_f32_16x16x32_bf16 v[118:121], v[158:161], v[180:183], v[118:121]
	v_mfma_f32_16x16x32_bf16 v[118:121], v[168:171], v[184:187], v[118:121]
	v_mfma_f32_16x16x32_bf16 v[114:117], v[172:175], v[180:183], v[114:117]
	v_mfma_f32_16x16x32_bf16 v[114:117], v[176:179], v[184:187], v[114:117]
	v_mfma_f32_16x16x32_bf16 v[102:105], v[158:161], v[188:191], v[102:105]
	v_mfma_f32_16x16x32_bf16 v[102:105], v[168:171], v[192:195], v[102:105]
	v_mfma_f32_16x16x32_bf16 v[98:101], v[172:175], v[188:191], v[98:101]
	v_mfma_f32_16x16x32_bf16 v[98:101], v[176:179], v[192:195], v[98:101]
	v_mfma_f32_16x16x32_bf16 v[86:89], v[158:161], v[196:199], v[86:89]
	v_mfma_f32_16x16x32_bf16 v[86:89], v[168:171], v[200:203], v[86:89]
	v_mfma_f32_16x16x32_bf16 v[82:85], v[172:175], v[196:199], v[82:85]
	v_mfma_f32_16x16x32_bf16 v[82:85], v[176:179], v[200:203], v[82:85]
	v_mfma_f32_16x16x32_bf16 v[70:73], v[158:161], v[224:227], v[70:73]
	v_mfma_f32_16x16x32_bf16 v[70:73], v[168:171], v[228:231], v[70:73]
	v_mfma_f32_16x16x32_bf16 v[66:69], v[172:175], v[224:227], v[66:69]
	v_mfma_f32_16x16x32_bf16 v[66:69], v[176:179], v[228:231], v[66:69]
	s_setprio 0
	s_barrier
; #define PG8_STAGE(bufoff, gbase, voff) do { _Pragma("unroll") for (int _i = 0; _i < 2; ++_i) \
;         __builtin_amdgcn_global_load_lds((const unsigned*)((const char*)(gbase) + (voff)[_i]), (PG8_LAS unsigned*)(lds + (bufoff) + ldsw + _i * 8192), 16, 0, 0); } while (0)
; #define PG8_LDA(dst, b, h) do { _Pragma("unroll") for (int m = 0; m < 4; ++m) _Pragma("unroll") for (int k = 0; k < 2; ++k) dst[m][k] = *(const PG8_LAS bf16x8*)(lds + PG8_SA(b, h) + aoff + m * 2048 + k * 1024); } while (0)
; #define PG8_MMA(ai, bj, At, Bt) do { __builtin_amdgcn_s_setprio(1); _Pragma("unroll") for (int m = 0; m < 4; ++m) _Pragma("unroll") for (int n = 0; n < 2; ++n) _Pragma("unroll") for (int k = 0; k < 2; ++k) \
;         acc[ai][bj][m][n] = __builtin_amdgcn_mfma_f32_16x16x32_bf16(Bt[n][k], At[m][k], acc[ai][bj][m][n], 0, 0, 0); __builtin_amdgcn_s_setprio(0); } while (0)
; #define PG8_WAIT_V(n) asm volatile("s_waitcnt vmcnt(" #n ")" ::: "memory")
; #define PG8_WAIT_L(n) asm volatile("s_waitcnt lgkmcnt(" #n ")" ::: "memory")
; #define PG8_BAR __builtin_amdgcn_s_barrier()
; #define PG8_SCHED __builtin_amdgcn_sched_barrier(0)
; template <class Epi, class Sched, bool ALIGN_EPI = false, bool SP2 = false>
; __device__ __forceinline__ void gemm_phase(PG8_LAS unsigned char* lds, const Gemm g, const Sched S, const Epi E) {
;     ...
;         for (int t = 0; t < nt; t += 2) {
;             const bool last = (t == nt - 2);
;             const char* a1 = cA + (size_t)(t + 1) * kstep;
;             const char* a2 = last ? nA : cA + (size_t)(t + 2) * kstep; const char* b2 = last ? nB : cB + (size_t)(t + 2) * kstep;
;     ...
;             PG8_LDA(At, 1, 1); PG8_STAGE(PG8_SB(1, 0), b3, voffB); PG8_STAGE(PG8_SB(1, 1), b3 + hstep, voffB); PG8_STAGE(PG8_SA(1, 0), a3, voffA);
;             PG8_WAIT_V(8); PG8_WAIT_L(0); PG8_BAR; PG8_MMA(1, 0, At, B0); PG8_MMA(1, 1, At, B1); PG8_BAR; PG8_SCHED;
	s_add_i32 s24, s26, s22
	v_lshl_add_u64 v[140:141], v[140:141], 0, s[28:29]
	s_mov_b32 m0, s24
	ds_read_b128 v[180:183], v145 offset:49152
	ds_read_b128 v[184:187], v145 offset:50176
	ds_read_b128 v[188:191], v145 offset:51200
	ds_read_b128 v[192:195], v145 offset:52224
	ds_read_b128 v[196:199], v145 offset:53248
	ds_read_b128 v[200:203], v145 offset:54272
	ds_read_b128 v[224:227], v145 offset:55296
	ds_read_b128 v[228:231], v145 offset:56320
	global_load_lds_dwordx4 v[140:141], off
	s_add_i32 m0, s24, 0x2000
	s_add_u32 s24, s56, 0x160080
	v_lshl_add_u64 v[140:141], v[232:233], 0, s[28:29]
	s_addc_u32 s25, s57, 0
	s_add_i32 s26, s27, s22
	global_load_lds_dwordx4 v[140:141], off
	v_lshl_add_u64 v[140:141], s[24:25], 0, v[0:1]
	s_mov_b32 m0, s26
	s_nop 0
	global_load_lds_dwordx4 v[140:141], off
	v_lshl_add_u64 v[140:141], s[24:25], 0, v[130:131]
	s_add_i32 m0, s26, 0x2000
	s_nop 0
	global_load_lds_dwordx4 v[140:141], off
	v_lshl_add_u64 v[140:141], v[234:235], 0, s[28:29]
	s_mov_b32 m0, s65
	s_nop 0
	global_load_lds_dwordx4 v[140:141], off
	v_lshl_add_u64 v[140:141], v[236:237], 0, s[28:29]
	s_mov_b32 m0, s66
	s_nop 0
	global_load_lds_dwordx4 v[140:141], off
	s_waitcnt vmcnt(8)
	s_waitcnt lgkmcnt(0)
	s_barrier
	s_setprio 1
	v_mfma_f32_16x16x32_bf16 v[62:65], v[136:139], v[180:183], v[62:65]
	v_mfma_f32_16x16x32_bf16 v[62:65], v[146:149], v[184:187], v[62:65]
	v_mfma_f32_16x16x32_bf16 v[58:61], v[150:153], v[180:183], v[58:61]
	v_mfma_f32_16x16x32_bf16 v[58:61], v[154:157], v[184:187], v[58:61]
	v_mfma_f32_16x16x32_bf16 v[46:49], v[136:139], v[188:191], v[46:49]
	v_mfma_f32_16x16x32_bf16 v[46:49], v[146:149], v[192:195], v[46:49]
	v_mfma_f32_16x16x32_bf16 v[42:45], v[150:153], v[188:191], v[42:45]
	v_mfma_f32_16x16x32_bf16 v[42:45], v[154:157], v[192:195], v[42:45]
	v_mfma_f32_16x16x32_bf16 v[30:33], v[136:139], v[196:199], v[30:33]
	v_mfma_f32_16x16x32_bf16 v[30:33], v[146:149], v[200:203], v[30:33]
	v_mfma_f32_16x16x32_bf16 v[26:29], v[150:153], v[196:199], v[26:29]
	v_mfma_f32_16x16x32_bf16 v[26:29], v[154:157], v[200:203], v[26:29]
	v_mfma_f32_16x16x32_bf16 v[14:17], v[136:139], v[224:227], v[14:17]
	v_mfma_f32_16x16x32_bf16 v[14:17], v[146:149], v[228:231], v[14:17]
	v_mfma_f32_16x16x32_bf16 v[10:13], v[150:153], v[224:227], v[10:13]
	v_mfma_f32_16x16x32_bf16 v[10:13], v[154:157], v[228:231], v[10:13]
	v_mfma_f32_16x16x32_bf16 v[54:57], v[158:161], v[180:183], v[54:57]
	v_mfma_f32_16x16x32_bf16 v[54:57], v[168:171], v[184:187], v[54:57]
	v_mfma_f32_16x16x32_bf16 v[50:53], v[172:175], v[180:183], v[50:53]
	v_mfma_f32_16x16x32_bf16 v[50:53], v[176:179], v[184:187], v[50:53]
	v_mfma_f32_16x16x32_bf16 v[38:41], v[158:161], v[188:191], v[38:41]
	v_mfma_f32_16x16x32_bf16 v[38:41], v[168:171], v[192:195], v[38:41]
	v_mfma_f32_16x16x32_bf16 v[34:37], v[172:175], v[188:191], v[34:37]
	v_mfma_f32_16x16x32_bf16 v[34:37], v[176:179], v[192:195], v[34:37]
	v_mfma_f32_16x16x32_bf16 v[22:25], v[158:161], v[196:199], v[22:25]
	v_mfma_f32_16x16x32_bf16 v[22:25], v[168:171], v[200:203], v[22:25]
	v_mfma_f32_16x16x32_bf16 v[18:21], v[172:175], v[196:199], v[18:21]
	v_mfma_f32_16x16x32_bf16 v[18:21], v[176:179], v[200:203], v[18:21]
	v_mfma_f32_16x16x32_bf16 v[6:9], v[158:161], v[224:227], v[6:9]
	v_mfma_f32_16x16x32_bf16 v[6:9], v[168:171], v[228:231], v[6:9]
	v_mfma_f32_16x16x32_bf16 v[2:5], v[172:175], v[224:227], v[2:5]
	v_mfma_f32_16x16x32_bf16 v[2:5], v[176:179], v[228:231], v[2:5]
	s_setprio 0
	s_barrier
	s_add_i32 s15, s15, 2
	s_add_u32 s5, s5, 0x100
	s_addc_u32 s14, s14, 0
	s_cmpk_gt_u32 s15, 0x55
	s_mov_b64 s[50:51], s[52:53]
	s_cbranch_scc0 .LBB0_272
	s_and_b64 vcc, exec, s[42:43]
	s_cbranch_vccz .LBB0_275
	s_barrier

; #define PG8_STAGE(bufoff, gbase, voff) do { _Pragma("unroll") for (int _i = 0; _i < 2; ++_i) \
;         __builtin_amdgcn_global_load_lds((const unsigned*)((const char*)(gbase) + (voff)[_i]), (PG8_LAS unsigned*)(lds + (bufoff) + ldsw + _i * 8192), 16, 0, 0); } while (0)
; #define PG8_LDA(dst, b, h) do { _Pragma("unroll") for (int m = 0; m < 4; ++m) _Pragma("unroll") for (int k = 0; k < 2; ++k) dst[m][k] = *(const PG8_LAS bf16x8*)(lds + PG8_SA(b, h) + aoff + m * 2048 + k * 1024); } while (0)
; #define PG8_LDB(dst, b, h) do { _Pragma("unroll") for (int n = 0; n < 2; ++n) _Pragma("unroll") for (int k = 0; k < 2; ++k) dst[n][k] = *(const PG8_LAS bf16x8*)(lds + PG8_SB(b, h) + boff + n * 2048 + k * 1024); } while (0)
; #define PG8_MMA(ai, bj, At, Bt) do { __builtin_amdgcn_s_setprio(1); _Pragma("unroll") for (int m = 0; m < 4; ++m) _Pragma("unroll") for (int n = 0; n < 2; ++n) _Pragma("unroll") for (int k = 0; k < 2; ++k) \
;         acc[ai][bj][m][n] = __builtin_amdgcn_mfma_f32_16x16x32_bf16(Bt[n][k], At[m][k], acc[ai][bj][m][n], 0, 0, 0); __builtin_amdgcn_s_setprio(0); } while (0)
; #define PG8_WAIT_V(n) asm volatile("s_waitcnt vmcnt(" #n ")" ::: "memory")
; #define PG8_WAIT_L(n) asm volatile("s_waitcnt lgkmcnt(" #n ")" ::: "memory")
; #define PG8_BAR __builtin_amdgcn_s_barrier()
; #define PG8_SCHED __builtin_amdgcn_sched_barrier(0)
; template <class Epi, class Sched, bool ALIGN_EPI = false, bool SP2 = false>
; __device__ __forceinline__ void gemm_phase(PG8_LAS unsigned char* lds, const Gemm g, const Sched S, const Epi E) {
;     ...
;             PG8_LDB(B0, 0, 0); PG8_LDB(B1, 0, 1); PG8_SCHED; PG8_LDA(At, 0, 0); PG8_STAGE(PG8_SA(1, 1), a1 + hstep, voffA);
;             PG8_WAIT_V(8); PG8_WAIT_L(0); PG8_BAR; PG8_MMA(0, 0, At, B0); PG8_MMA(0, 1, At, B1); PG8_BAR; PG8_SCHED;
;             PG8_LDA(At, 0, 1); PG8_STAGE(PG8_SB(0, 0), b2, voffB); PG8_STAGE(PG8_SB(0, 1), b2 + hstep, voffB); PG8_STAGE(PG8_SA(0, 0), a2, voffA);
;             PG8_WAIT_V(8); PG8_WAIT_L(0); PG8_BAR; PG8_MMA(1, 0, At, B0); PG8_MMA(1, 1, At, B1); PG8_BAR; PG8_SCHED;
.LBB0_404:
	s_add_u32 s25, s0, 0xfff80080
	s_addc_u32 s26, s1, -1
	s_add_i32 s27, 0, 0x10000
	s_cmp_eq_u32 s24, 28
	s_cselect_b32 s67, s53, s26
	s_cselect_b32 s66, vcc_lo, s25
	v_add_u32_e32 v152, s27, v155
	s_cselect_b32 s65, s45, s15
	s_cselect_b32 s64, vcc_hi, s14
	s_add_i32 s25, 0, 0x14000
	ds_read_b128 v[130:133], v152
	ds_read_b128 v[134:137], v152 offset:1024
	ds_read_b128 v[148:151], v152 offset:2048
	ds_read_b128 v[174:177], v152 offset:3072
	v_add_u32_e32 v152, s25, v155
	ds_read_b128 v[178:181], v152
	ds_read_b128 v[182:185], v152 offset:1024
	ds_read_b128 v[186:189], v152 offset:2048
	ds_read_b128 v[190:193], v152 offset:3072
	v_lshl_add_u64 v[152:153], s[0:1], 0, v[144:145]
	s_add_i32 m0, s21, 0xc000
	ds_read_b128 v[194:197], v171
	ds_read_b128 v[198:201], v171 offset:1024
	ds_read_b128 v[224:227], v171 offset:2048
	ds_read_b128 v[228:231], v171 offset:3072
	ds_read_b128 v[232:235], v171 offset:4096
	ds_read_b128 v[236:239], v171 offset:5120
	ds_read_b128 v[240:243], v171 offset:6144
	ds_read_b128 v[244:247], v171 offset:7168
	global_load_lds_dwordx4 v[152:153], off
	v_lshl_add_u64 v[152:153], s[0:1], 0, v[146:147]
	s_add_i32 m0, s21, 0xe000
	s_nop 0
	global_load_lds_dwordx4 v[152:153], off
	s_waitcnt vmcnt(8)
	s_waitcnt lgkmcnt(0)
	s_barrier
	s_setprio 1
	v_mfma_f32_16x16x32_bf16 v[126:129], v[130:133], v[194:197], v[126:129]
	v_mfma_f32_16x16x32_bf16 v[126:129], v[134:137], v[198:201], v[126:129]
	v_mfma_f32_16x16x32_bf16 v[122:125], v[148:151], v[194:197], v[122:125]
	v_mfma_f32_16x16x32_bf16 v[122:125], v[174:177], v[198:201], v[122:125]
	v_mfma_f32_16x16x32_bf16 v[118:121], v[130:133], v[224:227], v[118:121]
	v_mfma_f32_16x16x32_bf16 v[118:121], v[134:137], v[228:231], v[118:121]
	v_mfma_f32_16x16x32_bf16 v[110:113], v[148:151], v[224:227], v[110:113]
	v_mfma_f32_16x16x32_bf16 v[110:113], v[174:177], v[228:231], v[110:113]
	v_mfma_f32_16x16x32_bf16 v[102:105], v[130:133], v[232:235], v[102:105]
	v_mfma_f32_16x16x32_bf16 v[102:105], v[134:137], v[236:239], v[102:105]
	v_mfma_f32_16x16x32_bf16 v[94:97], v[148:151], v[232:235], v[94:97]
	v_mfma_f32_16x16x32_bf16 v[94:97], v[174:177], v[236:239], v[94:97]
	v_mfma_f32_16x16x32_bf16 v[86:89], v[130:133], v[240:243], v[86:89]
	v_mfma_f32_16x16x32_bf16 v[86:89], v[134:137], v[244:247], v[86:89]
	v_mfma_f32_16x16x32_bf16 v[78:81], v[148:151], v[240:243], v[78:81]
	v_mfma_f32_16x16x32_bf16 v[78:81], v[174:177], v[244:247], v[78:81]
	v_mfma_f32_16x16x32_bf16 v[114:117], v[178:181], v[194:197], v[114:117]
	v_mfma_f32_16x16x32_bf16 v[114:117], v[182:185], v[198:201], v[114:117]
	v_mfma_f32_16x16x32_bf16 v[106:109], v[186:189], v[194:197], v[106:109]
	v_mfma_f32_16x16x32_bf16 v[106:109], v[190:193], v[198:201], v[106:109]
	v_mfma_f32_16x16x32_bf16 v[98:101], v[178:181], v[224:227], v[98:101]
	v_mfma_f32_16x16x32_bf16 v[98:101], v[182:185], v[228:231], v[98:101]
	v_mfma_f32_16x16x32_bf16 v[90:93], v[186:189], v[224:227], v[90:93]
	v_mfma_f32_16x16x32_bf16 v[90:93], v[190:193], v[228:231], v[90:93]
	v_mfma_f32_16x16x32_bf16 v[82:85], v[178:181], v[232:235], v[82:85]
	v_mfma_f32_16x16x32_bf16 v[82:85], v[182:185], v[236:239], v[82:85]
	v_mfma_f32_16x16x32_bf16 v[74:77], v[186:189], v[232:235], v[74:77]
	v_mfma_f32_16x16x32_bf16 v[74:77], v[190:193], v[236:239], v[74:77]
	v_mfma_f32_16x16x32_bf16 v[70:73], v[178:181], v[240:243], v[70:73]
	v_mfma_f32_16x16x32_bf16 v[70:73], v[182:185], v[244:247], v[70:73]
	v_mfma_f32_16x16x32_bf16 v[66:69], v[186:189], v[240:243], v[66:69]
	v_mfma_f32_16x16x32_bf16 v[66:69], v[190:193], v[244:247], v[66:69]
	s_setprio 0
	s_barrier
	s_add_i32 s26, s27, s16
	v_lshl_add_u64 v[152:153], s[64:65], 0, v[0:1]
	s_mov_b32 m0, s26
	ds_read_b128 v[194:197], v171 offset:16384
	ds_read_b128 v[198:201], v171 offset:17408
	ds_read_b128 v[224:227], v171 offset:18432
	ds_read_b128 v[228:231], v171 offset:19456
	ds_read_b128 v[232:235], v171 offset:20480
	ds_read_b128 v[236:239], v171 offset:21504
	ds_read_b128 v[240:243], v171 offset:22528
	ds_read_b128 v[244:247], v171 offset:23552
	global_load_lds_dwordx4 v[152:153], off
	s_add_i32 m0, s26, 0x2000
	s_add_u32 s26, s64, 0x80000
	v_lshl_add_u64 v[202:203], s[64:65], 0, v[138:139]
	s_addc_u32 s27, s65, 0
	s_add_i32 s25, s25, s16
	global_load_lds_dwordx4 v[202:203], off
	v_lshl_add_u64 v[248:249], s[26:27], 0, v[0:1]
	s_mov_b32 m0, s25
	v_lshl_add_u64 v[250:251], s[66:67], 0, v[140:141]
	global_load_lds_dwordx4 v[248:249], off
	v_lshl_add_u64 v[248:249], s[26:27], 0, v[138:139]
	s_add_i32 m0, s25, 0x2000
	s_nop 0
	global_load_lds_dwordx4 v[248:249], off
	v_lshl_add_u64 v[248:249], s[66:67], 0, v[142:143]
	s_mov_b32 m0, s21
	s_nop 0
	global_load_lds_dwordx4 v[248:249], off
	s_mov_b32 m0, s22
	s_nop 0
	global_load_lds_dwordx4 v[250:251], off
	s_waitcnt vmcnt(8)
	s_waitcnt lgkmcnt(0)
	s_barrier
; #define PG8_STAGE(bufoff, gbase, voff) do { _Pragma("unroll") for (int _i = 0; _i < 2; ++_i) \
;         __builtin_amdgcn_global_load_lds((const unsigned*)((const char*)(gbase) + (voff)[_i]), (PG8_LAS unsigned*)(lds + (bufoff) + ldsw + _i * 8192), 16, 0, 0); } while (0)
; #define PG8_LDA(dst, b, h) do { _Pragma("unroll") for (int m = 0; m < 4; ++m) _Pragma("unroll") for (int k = 0; k < 2; ++k) dst[m][k] = *(const PG8_LAS bf16x8*)(lds + PG8_SA(b, h) + aoff + m * 2048 + k * 1024); } while (0)
; #define PG8_LDB(dst, b, h) do { _Pragma("unroll") for (int n = 0; n < 2; ++n) _Pragma("unroll") for (int k = 0; k < 2; ++k) dst[n][k] = *(const PG8_LAS bf16x8*)(lds + PG8_SB(b, h) + boff + n * 2048 + k * 1024); } while (0)
; #define PG8_MMA(ai, bj, At, Bt) do { __builtin_amdgcn_s_setprio(1); _Pragma("unroll") for (int m = 0; m < 4; ++m) _Pragma("unroll") for (int n = 0; n < 2; ++n) _Pragma("unroll") for (int k = 0; k < 2; ++k) \
;         acc[ai][bj][m][n] = __builtin_amdgcn_mfma_f32_16x16x32_bf16(Bt[n][k], At[m][k], acc[ai][bj][m][n], 0, 0, 0); __builtin_amdgcn_s_setprio(0); } while (0)
; #define PG8_WAIT_V(n) asm volatile("s_waitcnt vmcnt(" #n ")" ::: "memory")
; #define PG8_WAIT_L(n) asm volatile("s_waitcnt lgkmcnt(" #n ")" ::: "memory")
; #define PG8_BAR __builtin_amdgcn_s_barrier()
; #define PG8_SCHED __builtin_amdgcn_sched_barrier(0)
; template <class Epi, class Sched, bool ALIGN_EPI = false, bool SP2 = false>
; __device__ __forceinline__ void gemm_phase(PG8_LAS unsigned char* lds, const Gemm g, const Sched S, const Epi E) {
;     ...
;             PG8_WAIT_V(8); PG8_WAIT_L(0); PG8_BAR; PG8_MMA(1, 0, At, B0); PG8_MMA(1, 1, At, B1); PG8_BAR; PG8_SCHED;
;             PG8_LDB(B0, 1, 0); PG8_LDB(B1, 1, 1); PG8_SCHED; PG8_LDA(At, 1, 0); PG8_STAGE(PG8_SA(0, 1), a2 + hstep, voffA);
;             PG8_WAIT_V(8); PG8_WAIT_L(0); PG8_BAR; PG8_MMA(0, 0, At, B0); PG8_MMA(0, 1, At, B1); PG8_BAR; PG8_SCHED;
	s_setprio 1
	v_mfma_f32_16x16x32_bf16 v[62:65], v[130:133], v[194:197], v[62:65]
	v_mfma_f32_16x16x32_bf16 v[62:65], v[134:137], v[198:201], v[62:65]
	v_mfma_f32_16x16x32_bf16 v[58:61], v[148:151], v[194:197], v[58:61]
	v_mfma_f32_16x16x32_bf16 v[58:61], v[174:177], v[198:201], v[58:61]
	v_mfma_f32_16x16x32_bf16 v[54:57], v[130:133], v[224:227], v[54:57]
	v_mfma_f32_16x16x32_bf16 v[54:57], v[134:137], v[228:231], v[54:57]
	v_mfma_f32_16x16x32_bf16 v[46:49], v[148:151], v[224:227], v[46:49]
	v_mfma_f32_16x16x32_bf16 v[46:49], v[174:177], v[228:231], v[46:49]
	v_mfma_f32_16x16x32_bf16 v[38:41], v[130:133], v[232:235], v[38:41]
	v_mfma_f32_16x16x32_bf16 v[38:41], v[134:137], v[236:239], v[38:41]
	v_mfma_f32_16x16x32_bf16 v[30:33], v[148:151], v[232:235], v[30:33]
	v_mfma_f32_16x16x32_bf16 v[30:33], v[174:177], v[236:239], v[30:33]
	v_mfma_f32_16x16x32_bf16 v[22:25], v[130:133], v[240:243], v[22:25]
	v_mfma_f32_16x16x32_bf16 v[22:25], v[134:137], v[244:247], v[22:25]
	v_mfma_f32_16x16x32_bf16 v[14:17], v[148:151], v[240:243], v[14:17]
	v_mfma_f32_16x16x32_bf16 v[14:17], v[174:177], v[244:247], v[14:17]
	v_mfma_f32_16x16x32_bf16 v[50:53], v[178:181], v[194:197], v[50:53]
	v_mfma_f32_16x16x32_bf16 v[50:53], v[182:185], v[198:201], v[50:53]
	v_mfma_f32_16x16x32_bf16 v[42:45], v[186:189], v[194:197], v[42:45]
	v_mfma_f32_16x16x32_bf16 v[42:45], v[190:193], v[198:201], v[42:45]
	v_mfma_f32_16x16x32_bf16 v[34:37], v[178:181], v[224:227], v[34:37]
	v_mfma_f32_16x16x32_bf16 v[34:37], v[182:185], v[228:231], v[34:37]
	v_mfma_f32_16x16x32_bf16 v[26:29], v[186:189], v[224:227], v[26:29]
	v_mfma_f32_16x16x32_bf16 v[26:29], v[190:193], v[228:231], v[26:29]
	v_mfma_f32_16x16x32_bf16 v[18:21], v[178:181], v[232:235], v[18:21]
	v_mfma_f32_16x16x32_bf16 v[18:21], v[182:185], v[236:239], v[18:21]
	v_mfma_f32_16x16x32_bf16 v[10:13], v[186:189], v[232:235], v[10:13]
	v_mfma_f32_16x16x32_bf16 v[10:13], v[190:193], v[236:239], v[10:13]
	v_mfma_f32_16x16x32_bf16 v[6:9], v[178:181], v[240:243], v[6:9]
	v_mfma_f32_16x16x32_bf16 v[6:9], v[182:185], v[244:247], v[6:9]
	v_mfma_f32_16x16x32_bf16 v[2:5], v[186:189], v[240:243], v[2:5]
	v_mfma_f32_16x16x32_bf16 v[2:5], v[190:193], v[244:247], v[2:5]
	s_setprio 0
	s_barrier
	s_add_i32 s25, 0, 0x18000
	v_add_u32_e32 v173, s25, v155
	s_add_i32 s30, 0, 0x1c000
	ds_read_b128 v[130:133], v173
	ds_read_b128 v[134:137], v173 offset:1024
	ds_read_b128 v[148:151], v173 offset:2048
	ds_read_b128 v[174:177], v173 offset:3072
	v_add_u32_e32 v173, s30, v155
	ds_read_b128 v[178:181], v173
	ds_read_b128 v[182:185], v173 offset:1024
	ds_read_b128 v[186:189], v173 offset:2048
	ds_read_b128 v[190:193], v173 offset:3072
	s_add_u32 s26, s66, 0x80000
	s_addc_u32 s27, s67, 0
	s_mov_b32 m0, s47
	v_lshl_add_u64 v[214:215], s[26:27], 0, v[142:143]
	ds_read_b128 v[194:197], v171 offset:32768
	ds_read_b128 v[198:201], v171 offset:33792
	ds_read_b128 v[224:227], v171 offset:34816
	ds_read_b128 v[228:231], v171 offset:35840
	ds_read_b128 v[232:235], v171 offset:36864
	ds_read_b128 v[236:239], v171 offset:37888
	ds_read_b128 v[240:243], v171 offset:38912
	ds_read_b128 v[244:247], v171 offset:39936
	global_load_lds_dwordx4 v[214:215], off
	v_lshl_add_u64 v[214:215], s[26:27], 0, v[140:141]
	s_mov_b32 m0, s62
	s_nop 0
	global_load_lds_dwordx4 v[214:215], off
	s_waitcnt vmcnt(8)
	s_waitcnt lgkmcnt(0)
	s_barrier
	s_setprio 1
	v_mfma_f32_16x16x32_bf16 v[126:129], v[130:133], v[194:197], v[126:129]
	v_mfma_f32_16x16x32_bf16 v[126:129], v[134:137], v[198:201], v[126:129]
	v_mfma_f32_16x16x32_bf16 v[122:125], v[148:151], v[194:197], v[122:125]
	v_mfma_f32_16x16x32_bf16 v[122:125], v[174:177], v[198:201], v[122:125]
	v_mfma_f32_16x16x32_bf16 v[118:121], v[130:133], v[224:227], v[118:121]
	v_mfma_f32_16x16x32_bf16 v[118:121], v[134:137], v[228:231], v[118:121]
	v_mfma_f32_16x16x32_bf16 v[110:113], v[148:151], v[224:227], v[110:113]
	v_mfma_f32_16x16x32_bf16 v[110:113], v[174:177], v[228:231], v[110:113]
	v_mfma_f32_16x16x32_bf16 v[102:105], v[130:133], v[232:235], v[102:105]
	v_mfma_f32_16x16x32_bf16 v[102:105], v[134:137], v[236:239], v[102:105]
	v_mfma_f32_16x16x32_bf16 v[94:97], v[148:151], v[232:235], v[94:97]
	v_mfma_f32_16x16x32_bf16 v[94:97], v[174:177], v[236:239], v[94:97]
	v_mfma_f32_16x16x32_bf16 v[86:89], v[130:133], v[240:243], v[86:89]
	v_mfma_f32_16x16x32_bf16 v[86:89], v[134:137], v[244:247], v[86:89]
	v_mfma_f32_16x16x32_bf16 v[78:81], v[148:151], v[240:243], v[78:81]
	v_mfma_f32_16x16x32_bf16 v[78:81], v[174:177], v[244:247], v[78:81]
	v_mfma_f32_16x16x32_bf16 v[114:117], v[178:181], v[194:197], v[114:117]
	v_mfma_f32_16x16x32_bf16 v[114:117], v[182:185], v[198:201], v[114:117]
	v_mfma_f32_16x16x32_bf16 v[106:109], v[186:189], v[194:197], v[106:109]
	v_mfma_f32_16x16x32_bf16 v[106:109], v[190:193], v[198:201], v[106:109]
	v_mfma_f32_16x16x32_bf16 v[98:101], v[178:181], v[224:227], v[98:101]
	v_mfma_f32_16x16x32_bf16 v[98:101], v[182:185], v[228:231], v[98:101]
	v_mfma_f32_16x16x32_bf16 v[90:93], v[186:189], v[224:227], v[90:93]
	v_mfma_f32_16x16x32_bf16 v[90:93], v[190:193], v[228:231], v[90:93]
	v_mfma_f32_16x16x32_bf16 v[82:85], v[178:181], v[232:235], v[82:85]
	v_mfma_f32_16x16x32_bf16 v[82:85], v[182:185], v[236:239], v[82:85]
	v_mfma_f32_16x16x32_bf16 v[74:77], v[186:189], v[232:235], v[74:77]
	v_mfma_f32_16x16x32_bf16 v[74:77], v[190:193], v[236:239], v[74:77]
	v_mfma_f32_16x16x32_bf16 v[70:73], v[178:181], v[240:243], v[70:73]
	v_mfma_f32_16x16x32_bf16 v[70:73], v[182:185], v[244:247], v[70:73]
	v_mfma_f32_16x16x32_bf16 v[66:69], v[186:189], v[240:243], v[66:69]
	v_mfma_f32_16x16x32_bf16 v[66:69], v[190:193], v[244:247], v[66:69]
	s_setprio 0
	s_barrier
; #define PG8_STAGE(bufoff, gbase, voff) do { _Pragma("unroll") for (int _i = 0; _i < 2; ++_i) \
;         __builtin_amdgcn_global_load_lds((const unsigned*)((const char*)(gbase) + (voff)[_i]), (PG8_LAS unsigned*)(lds + (bufoff) + ldsw + _i * 8192), 16, 0, 0); } while (0)
; #define PG8_LDA(dst, b, h) do { _Pragma("unroll") for (int m = 0; m < 4; ++m) _Pragma("unroll") for (int k = 0; k < 2; ++k) dst[m][k] = *(const PG8_LAS bf16x8*)(lds + PG8_SA(b, h) + aoff + m * 2048 + k * 1024); } while (0)
; #define PG8_MMA(ai, bj, At, Bt) do { __builtin_amdgcn_s_setprio(1); _Pragma("unroll") for (int m = 0; m < 4; ++m) _Pragma("unroll") for (int n = 0; n < 2; ++n) _Pragma("unroll") for (int k = 0; k < 2; ++k) \
;         acc[ai][bj][m][n] = __builtin_amdgcn_mfma_f32_16x16x32_bf16(Bt[n][k], At[m][k], acc[ai][bj][m][n], 0, 0, 0); __builtin_amdgcn_s_setprio(0); } while (0)
; #define PG8_WAIT_V(n) asm volatile("s_waitcnt vmcnt(" #n ")" ::: "memory")
; #define PG8_WAIT_L(n) asm volatile("s_waitcnt lgkmcnt(" #n ")" ::: "memory")
; #define PG8_BAR __builtin_amdgcn_s_barrier()
; #define PG8_SCHED __builtin_amdgcn_sched_barrier(0)
; template <class Epi, class Sched, bool ALIGN_EPI = false, bool SP2 = false>
; __device__ __forceinline__ void gemm_phase(PG8_LAS unsigned char* lds, const Gemm g, const Sched S, const Epi E) {
;     ...
;         for (int t = 0; t < nt; t += 2) {
;             const bool last = (t == nt - 2);
;             const char* a1 = cA + (size_t)(t + 1) * kstep;
;             const char* a2 = last ? nA : cA + (size_t)(t + 2) * kstep; const char* b2 = last ? nB : cB + (size_t)(t + 2) * kstep;
;     ...
;             PG8_LDA(At, 1, 1); PG8_STAGE(PG8_SB(1, 0), b3, voffB); PG8_STAGE(PG8_SB(1, 1), b3 + hstep, voffB); PG8_STAGE(PG8_SA(1, 0), a3, voffA);
;             PG8_WAIT_V(8); PG8_WAIT_L(0); PG8_BAR; PG8_MMA(1, 0, At, B0); PG8_MMA(1, 1, At, B1); PG8_BAR; PG8_SCHED;
	s_add_i32 s25, s25, s16
	v_lshl_add_u64 v[152:153], v[152:153], 0, s[28:29]
	s_mov_b32 m0, s25
	ds_read_b128 v[194:197], v171 offset:49152
	ds_read_b128 v[198:201], v171 offset:50176
	ds_read_b128 v[224:227], v171 offset:51200
	ds_read_b128 v[228:231], v171 offset:52224
	ds_read_b128 v[232:235], v171 offset:53248
	ds_read_b128 v[236:239], v171 offset:54272
	ds_read_b128 v[240:243], v171 offset:55296
	ds_read_b128 v[244:247], v171 offset:56320
	global_load_lds_dwordx4 v[152:153], off
	s_add_i32 m0, s25, 0x2000
	s_add_u32 s26, s64, 0x80080
	v_lshl_add_u64 v[152:153], v[202:203], 0, s[28:29]
	s_addc_u32 s27, s65, 0
	s_add_i32 s25, s30, s16
	global_load_lds_dwordx4 v[152:153], off
	v_lshl_add_u64 v[152:153], s[26:27], 0, v[0:1]
	s_mov_b32 m0, s25
	s_nop 0
	global_load_lds_dwordx4 v[152:153], off
	v_lshl_add_u64 v[152:153], s[26:27], 0, v[138:139]
	s_add_i32 m0, s25, 0x2000
	s_nop 0
	global_load_lds_dwordx4 v[152:153], off
	v_lshl_add_u64 v[152:153], v[248:249], 0, s[28:29]
	s_mov_b32 m0, s63
	s_nop 0
	global_load_lds_dwordx4 v[152:153], off
	v_lshl_add_u64 v[152:153], v[250:251], 0, s[28:29]
	s_mov_b32 m0, s74
	s_nop 0
	global_load_lds_dwordx4 v[152:153], off
	s_waitcnt vmcnt(8)
	s_waitcnt lgkmcnt(0)
	s_barrier
	s_setprio 1
	v_mfma_f32_16x16x32_bf16 v[62:65], v[130:133], v[194:197], v[62:65]
	v_mfma_f32_16x16x32_bf16 v[62:65], v[134:137], v[198:201], v[62:65]
	v_mfma_f32_16x16x32_bf16 v[58:61], v[148:151], v[194:197], v[58:61]
	v_mfma_f32_16x16x32_bf16 v[58:61], v[174:177], v[198:201], v[58:61]
	v_mfma_f32_16x16x32_bf16 v[54:57], v[130:133], v[224:227], v[54:57]
	v_mfma_f32_16x16x32_bf16 v[54:57], v[134:137], v[228:231], v[54:57]
	v_mfma_f32_16x16x32_bf16 v[46:49], v[148:151], v[224:227], v[46:49]
	v_mfma_f32_16x16x32_bf16 v[46:49], v[174:177], v[228:231], v[46:49]
	v_mfma_f32_16x16x32_bf16 v[38:41], v[130:133], v[232:235], v[38:41]
	v_mfma_f32_16x16x32_bf16 v[38:41], v[134:137], v[236:239], v[38:41]
	v_mfma_f32_16x16x32_bf16 v[30:33], v[148:151], v[232:235], v[30:33]
	v_mfma_f32_16x16x32_bf16 v[30:33], v[174:177], v[236:239], v[30:33]
	v_mfma_f32_16x16x32_bf16 v[22:25], v[130:133], v[240:243], v[22:25]
	v_mfma_f32_16x16x32_bf16 v[22:25], v[134:137], v[244:247], v[22:25]
	v_mfma_f32_16x16x32_bf16 v[14:17], v[148:151], v[240:243], v[14:17]
	v_mfma_f32_16x16x32_bf16 v[14:17], v[174:177], v[244:247], v[14:17]
	v_mfma_f32_16x16x32_bf16 v[50:53], v[178:181], v[194:197], v[50:53]
	v_mfma_f32_16x16x32_bf16 v[50:53], v[182:185], v[198:201], v[50:53]
	v_mfma_f32_16x16x32_bf16 v[42:45], v[186:189], v[194:197], v[42:45]
	v_mfma_f32_16x16x32_bf16 v[42:45], v[190:193], v[198:201], v[42:45]
	v_mfma_f32_16x16x32_bf16 v[34:37], v[178:181], v[224:227], v[34:37]
	v_mfma_f32_16x16x32_bf16 v[34:37], v[182:185], v[228:231], v[34:37]
	v_mfma_f32_16x16x32_bf16 v[26:29], v[186:189], v[224:227], v[26:29]
	v_mfma_f32_16x16x32_bf16 v[26:29], v[190:193], v[228:231], v[26:29]
	v_mfma_f32_16x16x32_bf16 v[18:21], v[178:181], v[232:235], v[18:21]
	v_mfma_f32_16x16x32_bf16 v[18:21], v[182:185], v[236:239], v[18:21]
	v_mfma_f32_16x16x32_bf16 v[10:13], v[186:189], v[232:235], v[10:13]
	v_mfma_f32_16x16x32_bf16 v[10:13], v[190:193], v[236:239], v[10:13]
	v_mfma_f32_16x16x32_bf16 v[6:9], v[178:181], v[240:243], v[6:9]
	v_mfma_f32_16x16x32_bf16 v[6:9], v[182:185], v[244:247], v[6:9]
	v_mfma_f32_16x16x32_bf16 v[2:5], v[186:189], v[240:243], v[2:5]
	v_mfma_f32_16x16x32_bf16 v[2:5], v[190:193], v[244:247], v[2:5]
	s_setprio 0
	s_barrier
	s_add_i32 s24, s24, 2
	s_add_u32 s0, s0, 0x100
	s_addc_u32 s1, s1, 0
	s_add_u32 s14, s14, 0x100
	s_addc_u32 s15, s15, 0
	s_cmp_gt_u32 s24, 29
	s_cbranch_scc0 .LBB0_404
	s_and_b64 vcc, exec, s[8:9]
	s_cbranch_vccz .LBB0_407
	s_barrier

; #define PG8_STAGE(bufoff, gbase, voff) do { _Pragma("unroll") for (int _i = 0; _i < 2; ++_i) \
;         __builtin_amdgcn_global_load_lds((const unsigned*)((const char*)(gbase) + (voff)[_i]), (PG8_LAS unsigned*)(lds + (bufoff) + ldsw + _i * 8192), 16, 0, 0); } while (0)
; #define PG8_LDA(dst, b, h) do { _Pragma("unroll") for (int m = 0; m < 4; ++m) _Pragma("unroll") for (int k = 0; k < 2; ++k) dst[m][k] = *(const PG8_LAS bf16x8*)(lds + PG8_SA(b, h) + aoff + m * 2048 + k * 1024); } while (0)
; #define PG8_LDB(dst, b, h) do { _Pragma("unroll") for (int n = 0; n < 2; ++n) _Pragma("unroll") for (int k = 0; k < 2; ++k) dst[n][k] = *(const PG8_LAS bf16x8*)(lds + PG8_SB(b, h) + boff + n * 2048 + k * 1024); } while (0)
; #define PG8_MMA(ai, bj, At, Bt) do { __builtin_amdgcn_s_setprio(1); _Pragma("unroll") for (int m = 0; m < 4; ++m) _Pragma("unroll") for (int n = 0; n < 2; ++n) _Pragma("unroll") for (int k = 0; k < 2; ++k) \
;         acc[ai][bj][m][n] = __builtin_amdgcn_mfma_f32_16x16x32_bf16(Bt[n][k], At[m][k], acc[ai][bj][m][n], 0, 0, 0); __builtin_amdgcn_s_setprio(0); } while (0)
; #define PG8_WAIT_V(n) asm volatile("s_waitcnt vmcnt(" #n ")" ::: "memory")
; #define PG8_WAIT_L(n) asm volatile("s_waitcnt lgkmcnt(" #n ")" ::: "memory")
; #define PG8_BAR __builtin_amdgcn_s_barrier()
; #define PG8_SCHED __builtin_amdgcn_sched_barrier(0)
; template <class Epi, class Sched, bool ALIGN_EPI = false, bool SP2 = false>
; __device__ __forceinline__ void gemm_phase(PG8_LAS unsigned char* lds, const Gemm g, const Sched S, const Epi E) {
;     ...
;             PG8_LDB(B0, 0, 0); PG8_LDB(B1, 0, 1); PG8_SCHED; PG8_LDA(At, 0, 0); PG8_STAGE(PG8_SA(1, 1), a1 + hstep, voffA);
;             PG8_WAIT_V(8); PG8_WAIT_L(0); PG8_BAR; PG8_MMA(0, 0, At, B0); PG8_MMA(0, 1, At, B1); PG8_BAR; PG8_SCHED;
;             PG8_LDA(At, 0, 1); PG8_STAGE(PG8_SB(0, 0), b2, voffB); PG8_STAGE(PG8_SB(0, 1), b2 + hstep, voffB); PG8_STAGE(PG8_SA(0, 0), a2, voffA);
;             PG8_WAIT_V(8); PG8_WAIT_L(0); PG8_BAR; PG8_MMA(1, 0, At, B0); PG8_MMA(1, 1, At, B1); PG8_BAR; PG8_SCHED;
.LBB0_654:
	s_add_u32 s64, s58, 0x100
	s_addc_u32 s65, s59, 0
	s_add_i32 s25, 0, 0x10000
	s_cmp_eq_u32 s24, 12
	s_cselect_b32 vcc_hi, s45, s65
	s_cselect_b32 vcc_lo, s77, s64
	v_add_u32_e32 v140, s25, v143
	s_cselect_b32 s67, s43, s15
	s_cselect_b32 s66, s36, s14
	s_add_i32 s30, 0, 0x14000
	ds_read_b128 v[136:139], v140
	ds_read_b128 v[146:149], v140 offset:1024
	ds_read_b128 v[150:153], v140 offset:2048
	ds_read_b128 v[154:157], v140 offset:3072
	v_add_u32_e32 v140, s30, v143
	ds_read_b128 v[158:161], v140
	ds_read_b128 v[168:171], v140 offset:1024
	ds_read_b128 v[172:175], v140 offset:2048
	ds_read_b128 v[176:179], v140 offset:3072
	v_lshl_add_u64 v[140:141], s[58:59], 0, v[132:133]
	s_add_i32 m0, s21, 0xc000
	ds_read_b128 v[180:183], v145
	ds_read_b128 v[184:187], v145 offset:1024
	ds_read_b128 v[188:191], v145 offset:2048
	ds_read_b128 v[192:195], v145 offset:3072
	ds_read_b128 v[196:199], v145 offset:4096
	ds_read_b128 v[200:203], v145 offset:5120
	ds_read_b128 v[224:227], v145 offset:6144
	ds_read_b128 v[228:231], v145 offset:7168
	global_load_lds_dwordx4 v[140:141], off
	v_lshl_add_u64 v[140:141], s[58:59], 0, v[134:135]
	s_add_i32 m0, s21, 0xe000
	s_nop 0
	global_load_lds_dwordx4 v[140:141], off
	s_waitcnt vmcnt(8)
	s_waitcnt lgkmcnt(0)
	s_barrier
	s_setprio 1
	v_mfma_f32_16x16x32_bf16 v[126:129], v[136:139], v[180:183], v[126:129]
	v_mfma_f32_16x16x32_bf16 v[126:129], v[146:149], v[184:187], v[126:129]
	v_mfma_f32_16x16x32_bf16 v[122:125], v[150:153], v[180:183], v[122:125]
	v_mfma_f32_16x16x32_bf16 v[122:125], v[154:157], v[184:187], v[122:125]
	v_mfma_f32_16x16x32_bf16 v[110:113], v[136:139], v[188:191], v[110:113]
	v_mfma_f32_16x16x32_bf16 v[110:113], v[146:149], v[192:195], v[110:113]
	v_mfma_f32_16x16x32_bf16 v[106:109], v[150:153], v[188:191], v[106:109]
	v_mfma_f32_16x16x32_bf16 v[106:109], v[154:157], v[192:195], v[106:109]
	v_mfma_f32_16x16x32_bf16 v[94:97], v[136:139], v[196:199], v[94:97]
	v_mfma_f32_16x16x32_bf16 v[94:97], v[146:149], v[200:203], v[94:97]
	v_mfma_f32_16x16x32_bf16 v[90:93], v[150:153], v[196:199], v[90:93]
	v_mfma_f32_16x16x32_bf16 v[90:93], v[154:157], v[200:203], v[90:93]
	v_mfma_f32_16x16x32_bf16 v[78:81], v[136:139], v[224:227], v[78:81]
	v_mfma_f32_16x16x32_bf16 v[78:81], v[146:149], v[228:231], v[78:81]
	v_mfma_f32_16x16x32_bf16 v[74:77], v[150:153], v[224:227], v[74:77]
	v_mfma_f32_16x16x32_bf16 v[74:77], v[154:157], v[228:231], v[74:77]
	v_mfma_f32_16x16x32_bf16 v[118:121], v[158:161], v[180:183], v[118:121]
	v_mfma_f32_16x16x32_bf16 v[118:121], v[168:171], v[184:187], v[118:121]
	v_mfma_f32_16x16x32_bf16 v[114:117], v[172:175], v[180:183], v[114:117]
	v_mfma_f32_16x16x32_bf16 v[114:117], v[176:179], v[184:187], v[114:117]
	v_mfma_f32_16x16x32_bf16 v[102:105], v[158:161], v[188:191], v[102:105]
	v_mfma_f32_16x16x32_bf16 v[102:105], v[168:171], v[192:195], v[102:105]
	v_mfma_f32_16x16x32_bf16 v[98:101], v[172:175], v[188:191], v[98:101]
	v_mfma_f32_16x16x32_bf16 v[98:101], v[176:179], v[192:195], v[98:101]
	v_mfma_f32_16x16x32_bf16 v[86:89], v[158:161], v[196:199], v[86:89]
	v_mfma_f32_16x16x32_bf16 v[86:89], v[168:171], v[200:203], v[86:89]
	v_mfma_f32_16x16x32_bf16 v[82:85], v[172:175], v[196:199], v[82:85]
	v_mfma_f32_16x16x32_bf16 v[82:85], v[176:179], v[200:203], v[82:85]
	v_mfma_f32_16x16x32_bf16 v[70:73], v[158:161], v[224:227], v[70:73]
	v_mfma_f32_16x16x32_bf16 v[70:73], v[168:171], v[228:231], v[70:73]
	v_mfma_f32_16x16x32_bf16 v[66:69], v[172:175], v[224:227], v[66:69]
	v_mfma_f32_16x16x32_bf16 v[66:69], v[176:179], v[228:231], v[66:69]
	s_setprio 0
	s_barrier
	s_add_i32 s25, s25, s16
	v_lshl_add_u64 v[140:141], s[66:67], 0, v[0:1]
	s_mov_b32 m0, s25
	ds_read_b128 v[180:183], v145 offset:16384
	ds_read_b128 v[184:187], v145 offset:17408
	ds_read_b128 v[188:191], v145 offset:18432
	ds_read_b128 v[192:195], v145 offset:19456
	ds_read_b128 v[196:199], v145 offset:20480
	ds_read_b128 v[200:203], v145 offset:21504
	ds_read_b128 v[224:227], v145 offset:22528
	ds_read_b128 v[228:231], v145 offset:23552
	global_load_lds_dwordx4 v[140:141], off
	s_add_i32 m0, s25, 0x2000
	s_add_u32 s26, s66, 0x40000
	v_lshl_add_u64 v[214:215], s[66:67], 0, v[130:131]
	s_addc_u32 s27, s67, 0
	s_add_i32 s25, s30, s16
	global_load_lds_dwordx4 v[214:215], off
	v_lshl_add_u64 v[232:233], s[26:27], 0, v[0:1]
	s_mov_b32 m0, s25
	v_lshl_add_u64 v[234:235], vcc, 0, v[130:131]
	global_load_lds_dwordx4 v[232:233], off
	v_lshl_add_u64 v[232:233], s[26:27], 0, v[130:131]
	s_add_i32 m0, s25, 0x2000
	s_nop 0
	global_load_lds_dwordx4 v[232:233], off
	v_lshl_add_u64 v[232:233], vcc, 0, v[0:1]
	s_mov_b32 m0, s21
	s_nop 0
	global_load_lds_dwordx4 v[232:233], off
	s_mov_b32 m0, s22
	s_nop 0
	global_load_lds_dwordx4 v[234:235], off
	s_waitcnt vmcnt(8)
	s_waitcnt lgkmcnt(0)
	s_barrier
; #define PG8_STAGE(bufoff, gbase, voff) do { _Pragma("unroll") for (int _i = 0; _i < 2; ++_i) \
;         __builtin_amdgcn_global_load_lds((const unsigned*)((const char*)(gbase) + (voff)[_i]), (PG8_LAS unsigned*)(lds + (bufoff) + ldsw + _i * 8192), 16, 0, 0); } while (0)
; #define PG8_LDA(dst, b, h) do { _Pragma("unroll") for (int m = 0; m < 4; ++m) _Pragma("unroll") for (int k = 0; k < 2; ++k) dst[m][k] = *(const PG8_LAS bf16x8*)(lds + PG8_SA(b, h) + aoff + m * 2048 + k * 1024); } while (0)
; #define PG8_LDB(dst, b, h) do { _Pragma("unroll") for (int n = 0; n < 2; ++n) _Pragma("unroll") for (int k = 0; k < 2; ++k) dst[n][k] = *(const PG8_LAS bf16x8*)(lds + PG8_SB(b, h) + boff + n * 2048 + k * 1024); } while (0)
; #define PG8_MMA(ai, bj, At, Bt) do { __builtin_amdgcn_s_setprio(1); _Pragma("unroll") for (int m = 0; m < 4; ++m) _Pragma("unroll") for (int n = 0; n < 2; ++n) _Pragma("unroll") for (int k = 0; k < 2; ++k) \
;         acc[ai][bj][m][n] = __builtin_amdgcn_mfma_f32_16x16x32_bf16(Bt[n][k], At[m][k], acc[ai][bj][m][n], 0, 0, 0); __builtin_amdgcn_s_setprio(0); } while (0)
; #define PG8_WAIT_V(n) asm volatile("s_waitcnt vmcnt(" #n ")" ::: "memory")
; #define PG8_WAIT_L(n) asm volatile("s_waitcnt lgkmcnt(" #n ")" ::: "memory")
; #define PG8_BAR __builtin_amdgcn_s_barrier()
; #define PG8_SCHED __builtin_amdgcn_sched_barrier(0)
; template <class Epi, class Sched, bool ALIGN_EPI = false, bool SP2 = false>
; __device__ __forceinline__ void gemm_phase(PG8_LAS unsigned char* lds, const Gemm g, const Sched S, const Epi E) {
;     ...
;             PG8_WAIT_V(8); PG8_WAIT_L(0); PG8_BAR; PG8_MMA(1, 0, At, B0); PG8_MMA(1, 1, At, B1); PG8_BAR; PG8_SCHED;
;             PG8_LDB(B0, 1, 0); PG8_LDB(B1, 1, 1); PG8_SCHED; PG8_LDA(At, 1, 0); PG8_STAGE(PG8_SA(0, 1), a2 + hstep, voffA);
;             PG8_WAIT_V(8); PG8_WAIT_L(0); PG8_BAR; PG8_MMA(0, 0, At, B0); PG8_MMA(0, 1, At, B1); PG8_BAR; PG8_SCHED;
	s_setprio 1
	v_mfma_f32_16x16x32_bf16 v[62:65], v[136:139], v[180:183], v[62:65]
	v_mfma_f32_16x16x32_bf16 v[62:65], v[146:149], v[184:187], v[62:65]
	v_mfma_f32_16x16x32_bf16 v[58:61], v[150:153], v[180:183], v[58:61]
	v_mfma_f32_16x16x32_bf16 v[58:61], v[154:157], v[184:187], v[58:61]
	v_mfma_f32_16x16x32_bf16 v[46:49], v[136:139], v[188:191], v[46:49]
	v_mfma_f32_16x16x32_bf16 v[46:49], v[146:149], v[192:195], v[46:49]
	v_mfma_f32_16x16x32_bf16 v[42:45], v[150:153], v[188:191], v[42:45]
	v_mfma_f32_16x16x32_bf16 v[42:45], v[154:157], v[192:195], v[42:45]
	v_mfma_f32_16x16x32_bf16 v[30:33], v[136:139], v[196:199], v[30:33]
	v_mfma_f32_16x16x32_bf16 v[30:33], v[146:149], v[200:203], v[30:33]
	v_mfma_f32_16x16x32_bf16 v[26:29], v[150:153], v[196:199], v[26:29]
	v_mfma_f32_16x16x32_bf16 v[26:29], v[154:157], v[200:203], v[26:29]
	v_mfma_f32_16x16x32_bf16 v[14:17], v[136:139], v[224:227], v[14:17]
	v_mfma_f32_16x16x32_bf16 v[14:17], v[146:149], v[228:231], v[14:17]
	v_mfma_f32_16x16x32_bf16 v[10:13], v[150:153], v[224:227], v[10:13]
	v_mfma_f32_16x16x32_bf16 v[10:13], v[154:157], v[228:231], v[10:13]
	v_mfma_f32_16x16x32_bf16 v[54:57], v[158:161], v[180:183], v[54:57]
	v_mfma_f32_16x16x32_bf16 v[54:57], v[168:171], v[184:187], v[54:57]
	v_mfma_f32_16x16x32_bf16 v[50:53], v[172:175], v[180:183], v[50:53]
	v_mfma_f32_16x16x32_bf16 v[50:53], v[176:179], v[184:187], v[50:53]
	v_mfma_f32_16x16x32_bf16 v[38:41], v[158:161], v[188:191], v[38:41]
	v_mfma_f32_16x16x32_bf16 v[38:41], v[168:171], v[192:195], v[38:41]
	v_mfma_f32_16x16x32_bf16 v[34:37], v[172:175], v[188:191], v[34:37]
	v_mfma_f32_16x16x32_bf16 v[34:37], v[176:179], v[192:195], v[34:37]
	v_mfma_f32_16x16x32_bf16 v[22:25], v[158:161], v[196:199], v[22:25]
	v_mfma_f32_16x16x32_bf16 v[22:25], v[168:171], v[200:203], v[22:25]
	v_mfma_f32_16x16x32_bf16 v[18:21], v[172:175], v[196:199], v[18:21]
	v_mfma_f32_16x16x32_bf16 v[18:21], v[176:179], v[200:203], v[18:21]
	v_mfma_f32_16x16x32_bf16 v[6:9], v[158:161], v[224:227], v[6:9]
	v_mfma_f32_16x16x32_bf16 v[6:9], v[168:171], v[228:231], v[6:9]
	v_mfma_f32_16x16x32_bf16 v[2:5], v[172:175], v[224:227], v[2:5]
	v_mfma_f32_16x16x32_bf16 v[2:5], v[176:179], v[228:231], v[2:5]
	s_setprio 0
	s_barrier
	s_add_i32 s25, 0, 0x18000
	s_add_i32 s30, 0, 0x1c000
	v_add_u32_e32 v154, s25, v143
	v_add_u32_e32 v167, s30, v143
	ds_read_b128 v[136:139], v154
	ds_read_b128 v[146:149], v154 offset:1024
	ds_read_b128 v[150:153], v154 offset:2048
	ds_read_b128 v[154:157], v154 offset:3072
	ds_read_b128 v[158:161], v167
	ds_read_b128 v[168:171], v167 offset:1024
	ds_read_b128 v[172:175], v167 offset:2048
	ds_read_b128 v[176:179], v167 offset:3072
	s_add_u32 s26, vcc_lo, 0x40000
	s_addc_u32 s27, vcc_hi, 0
	s_mov_b32 m0, s47
	v_lshl_add_u64 v[236:237], s[26:27], 0, v[0:1]
	ds_read_b128 v[180:183], v145 offset:32768
	ds_read_b128 v[184:187], v145 offset:33792
	ds_read_b128 v[188:191], v145 offset:34816
	ds_read_b128 v[192:195], v145 offset:35840
	ds_read_b128 v[196:199], v145 offset:36864
	ds_read_b128 v[200:203], v145 offset:37888
	ds_read_b128 v[224:227], v145 offset:38912
	ds_read_b128 v[228:231], v145 offset:39936
	global_load_lds_dwordx4 v[236:237], off
	v_lshl_add_u64 v[236:237], s[26:27], 0, v[130:131]
	s_mov_b32 m0, s62
	s_nop 0
	global_load_lds_dwordx4 v[236:237], off
	s_waitcnt vmcnt(8)
	s_waitcnt lgkmcnt(0)
	s_barrier
	s_setprio 1
	v_mfma_f32_16x16x32_bf16 v[126:129], v[136:139], v[180:183], v[126:129]
	v_mfma_f32_16x16x32_bf16 v[126:129], v[146:149], v[184:187], v[126:129]
	v_mfma_f32_16x16x32_bf16 v[122:125], v[150:153], v[180:183], v[122:125]
	v_mfma_f32_16x16x32_bf16 v[122:125], v[154:157], v[184:187], v[122:125]
	v_mfma_f32_16x16x32_bf16 v[110:113], v[136:139], v[188:191], v[110:113]
	v_mfma_f32_16x16x32_bf16 v[110:113], v[146:149], v[192:195], v[110:113]
	v_mfma_f32_16x16x32_bf16 v[106:109], v[150:153], v[188:191], v[106:109]
	v_mfma_f32_16x16x32_bf16 v[106:109], v[154:157], v[192:195], v[106:109]
	v_mfma_f32_16x16x32_bf16 v[94:97], v[136:139], v[196:199], v[94:97]
	v_mfma_f32_16x16x32_bf16 v[94:97], v[146:149], v[200:203], v[94:97]
	v_mfma_f32_16x16x32_bf16 v[90:93], v[150:153], v[196:199], v[90:93]
	v_mfma_f32_16x16x32_bf16 v[90:93], v[154:157], v[200:203], v[90:93]
	v_mfma_f32_16x16x32_bf16 v[78:81], v[136:139], v[224:227], v[78:81]
	v_mfma_f32_16x16x32_bf16 v[78:81], v[146:149], v[228:231], v[78:81]
	v_mfma_f32_16x16x32_bf16 v[74:77], v[150:153], v[224:227], v[74:77]
	v_mfma_f32_16x16x32_bf16 v[74:77], v[154:157], v[228:231], v[74:77]
	v_mfma_f32_16x16x32_bf16 v[118:121], v[158:161], v[180:183], v[118:121]
	v_mfma_f32_16x16x32_bf16 v[118:121], v[168:171], v[184:187], v[118:121]
	v_mfma_f32_16x16x32_bf16 v[114:117], v[172:175], v[180:183], v[114:117]
	v_mfma_f32_16x16x32_bf16 v[114:117], v[176:179], v[184:187], v[114:117]
	v_mfma_f32_16x16x32_bf16 v[102:105], v[158:161], v[188:191], v[102:105]
	v_mfma_f32_16x16x32_bf16 v[102:105], v[168:171], v[192:195], v[102:105]
	v_mfma_f32_16x16x32_bf16 v[98:101], v[172:175], v[188:191], v[98:101]
	v_mfma_f32_16x16x32_bf16 v[98:101], v[176:179], v[192:195], v[98:101]
	v_mfma_f32_16x16x32_bf16 v[86:89], v[158:161], v[196:199], v[86:89]
	v_mfma_f32_16x16x32_bf16 v[86:89], v[168:171], v[200:203], v[86:89]
	v_mfma_f32_16x16x32_bf16 v[82:85], v[172:175], v[196:199], v[82:85]
	v_mfma_f32_16x16x32_bf16 v[82:85], v[176:179], v[200:203], v[82:85]
	v_mfma_f32_16x16x32_bf16 v[70:73], v[158:161], v[224:227], v[70:73]
	v_mfma_f32_16x16x32_bf16 v[70:73], v[168:171], v[228:231], v[70:73]
	v_mfma_f32_16x16x32_bf16 v[66:69], v[172:175], v[224:227], v[66:69]
	v_mfma_f32_16x16x32_bf16 v[66:69], v[176:179], v[228:231], v[66:69]
	s_setprio 0
	s_barrier
; #define PG8_STAGE(bufoff, gbase, voff) do { _Pragma("unroll") for (int _i = 0; _i < 2; ++_i) \
;         __builtin_amdgcn_global_load_lds((const unsigned*)((const char*)(gbase) + (voff)[_i]), (PG8_LAS unsigned*)(lds + (bufoff) + ldsw + _i * 8192), 16, 0, 0); } while (0)
; #define PG8_LDA(dst, b, h) do { _Pragma("unroll") for (int m = 0; m < 4; ++m) _Pragma("unroll") for (int k = 0; k < 2; ++k) dst[m][k] = *(const PG8_LAS bf16x8*)(lds + PG8_SA(b, h) + aoff + m * 2048 + k * 1024); } while (0)
; #define PG8_MMA(ai, bj, At, Bt) do { __builtin_amdgcn_s_setprio(1); _Pragma("unroll") for (int m = 0; m < 4; ++m) _Pragma("unroll") for (int n = 0; n < 2; ++n) _Pragma("unroll") for (int k = 0; k < 2; ++k) \
;         acc[ai][bj][m][n] = __builtin_amdgcn_mfma_f32_16x16x32_bf16(Bt[n][k], At[m][k], acc[ai][bj][m][n], 0, 0, 0); __builtin_amdgcn_s_setprio(0); } while (0)
; #define PG8_WAIT_V(n) asm volatile("s_waitcnt vmcnt(" #n ")" ::: "memory")
; #define PG8_WAIT_L(n) asm volatile("s_waitcnt lgkmcnt(" #n ")" ::: "memory")
; #define PG8_BAR __builtin_amdgcn_s_barrier()
; #define PG8_SCHED __builtin_amdgcn_sched_barrier(0)
; template <class Epi, class Sched, bool ALIGN_EPI = false, bool SP2 = false>
; __device__ __forceinline__ void gemm_phase(PG8_LAS unsigned char* lds, const Gemm g, const Sched S, const Epi E) {
;     ...
;         for (int t = 0; t < nt; t += 2) {
;             const bool last = (t == nt - 2);
;             const char* a1 = cA + (size_t)(t + 1) * kstep;
;             const char* a2 = last ? nA : cA + (size_t)(t + 2) * kstep; const char* b2 = last ? nB : cB + (size_t)(t + 2) * kstep;
;     ...
;             PG8_LDA(At, 1, 1); PG8_STAGE(PG8_SB(1, 0), b3, voffB); PG8_STAGE(PG8_SB(1, 1), b3 + hstep, voffB); PG8_STAGE(PG8_SA(1, 0), a3, voffA);
;             PG8_WAIT_V(8); PG8_WAIT_L(0); PG8_BAR; PG8_MMA(1, 0, At, B0); PG8_MMA(1, 1, At, B1); PG8_BAR; PG8_SCHED;
	s_add_i32 s25, s25, s16
	v_lshl_add_u64 v[140:141], v[140:141], 0, s[28:29]
	s_mov_b32 m0, s25
	ds_read_b128 v[180:183], v145 offset:49152
	ds_read_b128 v[184:187], v145 offset:50176
	ds_read_b128 v[188:191], v145 offset:51200
	ds_read_b128 v[192:195], v145 offset:52224
	ds_read_b128 v[196:199], v145 offset:53248
	ds_read_b128 v[200:203], v145 offset:54272
	ds_read_b128 v[224:227], v145 offset:55296
	ds_read_b128 v[228:231], v145 offset:56320
	global_load_lds_dwordx4 v[140:141], off
	s_add_i32 m0, s25, 0x2000
	s_add_u32 s26, s66, 0x40080
	v_lshl_add_u64 v[140:141], v[214:215], 0, s[28:29]
	s_addc_u32 s27, s67, 0
	s_add_i32 s25, s30, s16
	global_load_lds_dwordx4 v[140:141], off
	v_lshl_add_u64 v[140:141], s[26:27], 0, v[0:1]
	s_mov_b32 m0, s25
	s_nop 0
	global_load_lds_dwordx4 v[140:141], off
	v_lshl_add_u64 v[140:141], s[26:27], 0, v[130:131]
	s_add_i32 m0, s25, 0x2000
	s_nop 0
	global_load_lds_dwordx4 v[140:141], off
	v_lshl_add_u64 v[140:141], v[232:233], 0, s[28:29]
	s_mov_b32 m0, s63
	s_nop 0
	global_load_lds_dwordx4 v[140:141], off
	v_lshl_add_u64 v[140:141], v[234:235], 0, s[28:29]
	s_mov_b32 m0, s74
	s_nop 0
	global_load_lds_dwordx4 v[140:141], off
	s_waitcnt vmcnt(8)
	s_waitcnt lgkmcnt(0)
	s_barrier
	s_setprio 1
	v_mfma_f32_16x16x32_bf16 v[62:65], v[136:139], v[180:183], v[62:65]
	v_mfma_f32_16x16x32_bf16 v[62:65], v[146:149], v[184:187], v[62:65]
	v_mfma_f32_16x16x32_bf16 v[58:61], v[150:153], v[180:183], v[58:61]
	v_mfma_f32_16x16x32_bf16 v[58:61], v[154:157], v[184:187], v[58:61]
	v_mfma_f32_16x16x32_bf16 v[46:49], v[136:139], v[188:191], v[46:49]
	v_mfma_f32_16x16x32_bf16 v[46:49], v[146:149], v[192:195], v[46:49]
	v_mfma_f32_16x16x32_bf16 v[42:45], v[150:153], v[188:191], v[42:45]
	v_mfma_f32_16x16x32_bf16 v[42:45], v[154:157], v[192:195], v[42:45]
	v_mfma_f32_16x16x32_bf16 v[30:33], v[136:139], v[196:199], v[30:33]
	v_mfma_f32_16x16x32_bf16 v[30:33], v[146:149], v[200:203], v[30:33]
	v_mfma_f32_16x16x32_bf16 v[26:29], v[150:153], v[196:199], v[26:29]
	v_mfma_f32_16x16x32_bf16 v[26:29], v[154:157], v[200:203], v[26:29]
	v_mfma_f32_16x16x32_bf16 v[14:17], v[136:139], v[224:227], v[14:17]
	v_mfma_f32_16x16x32_bf16 v[14:17], v[146:149], v[228:231], v[14:17]
	v_mfma_f32_16x16x32_bf16 v[10:13], v[150:153], v[224:227], v[10:13]
	v_mfma_f32_16x16x32_bf16 v[10:13], v[154:157], v[228:231], v[10:13]
	v_mfma_f32_16x16x32_bf16 v[54:57], v[158:161], v[180:183], v[54:57]
	v_mfma_f32_16x16x32_bf16 v[54:57], v[168:171], v[184:187], v[54:57]
	v_mfma_f32_16x16x32_bf16 v[50:53], v[172:175], v[180:183], v[50:53]
	v_mfma_f32_16x16x32_bf16 v[50:53], v[176:179], v[184:187], v[50:53]
	v_mfma_f32_16x16x32_bf16 v[38:41], v[158:161], v[188:191], v[38:41]
	v_mfma_f32_16x16x32_bf16 v[38:41], v[168:171], v[192:195], v[38:41]
	v_mfma_f32_16x16x32_bf16 v[34:37], v[172:175], v[188:191], v[34:37]
	v_mfma_f32_16x16x32_bf16 v[34:37], v[176:179], v[192:195], v[34:37]
	v_mfma_f32_16x16x32_bf16 v[22:25], v[158:161], v[196:199], v[22:25]
	v_mfma_f32_16x16x32_bf16 v[22:25], v[168:171], v[200:203], v[22:25]
	v_mfma_f32_16x16x32_bf16 v[18:21], v[172:175], v[196:199], v[18:21]
	v_mfma_f32_16x16x32_bf16 v[18:21], v[176:179], v[200:203], v[18:21]
	v_mfma_f32_16x16x32_bf16 v[6:9], v[158:161], v[224:227], v[6:9]
	v_mfma_f32_16x16x32_bf16 v[6:9], v[168:171], v[228:231], v[6:9]
	v_mfma_f32_16x16x32_bf16 v[2:5], v[172:175], v[224:227], v[2:5]
	v_mfma_f32_16x16x32_bf16 v[2:5], v[176:179], v[228:231], v[2:5]
	s_setprio 0
	s_barrier
	s_add_i32 s24, s24, 2
	s_add_u32 s14, s14, 0x100
	s_addc_u32 s15, s15, 0
	s_cmp_gt_u32 s24, 13
	s_mov_b64 s[58:59], s[64:65]
	s_cbranch_scc0 .LBB0_654
	s_and_b64 vcc, exec, s[8:9]
	s_cbranch_vccz .LBB0_657
	s_barrier

; #define PG8_STAGE(bufoff, gbase, voff) do { _Pragma("unroll") for (int _i = 0; _i < 2; ++_i) \
;         __builtin_amdgcn_global_load_lds((const unsigned*)((const char*)(gbase) + (voff)[_i]), (PG8_LAS unsigned*)(lds + (bufoff) + ldsw + _i * 8192), 16, 0, 0); } while (0)
; #define PG8_LDA(dst, b, h) do { _Pragma("unroll") for (int m = 0; m < 4; ++m) _Pragma("unroll") for (int k = 0; k < 2; ++k) dst[m][k] = *(const PG8_LAS bf16x8*)(lds + PG8_SA(b, h) + aoff + m * 2048 + k * 1024); } while (0)
; #define PG8_LDB(dst, b, h) do { _Pragma("unroll") for (int n = 0; n < 2; ++n) _Pragma("unroll") for (int k = 0; k < 2; ++k) dst[n][k] = *(const PG8_LAS bf16x8*)(lds + PG8_SB(b, h) + boff + n * 2048 + k * 1024); } while (0)
; #define PG8_MMA(ai, bj, At, Bt) do { __builtin_amdgcn_s_setprio(1); _Pragma("unroll") for (int m = 0; m < 4; ++m) _Pragma("unroll") for (int n = 0; n < 2; ++n) _Pragma("unroll") for (int k = 0; k < 2; ++k) \
;         acc[ai][bj][m][n] = __builtin_amdgcn_mfma_f32_16x16x32_bf16(Bt[n][k], At[m][k], acc[ai][bj][m][n], 0, 0, 0); __builtin_amdgcn_s_setprio(0); } while (0)
; #define PG8_WAIT_V(n) asm volatile("s_waitcnt vmcnt(" #n ")" ::: "memory")
; #define PG8_BAR __builtin_amdgcn_s_barrier()
; template <class Epi, class Sched, bool ALIGN_EPI = false, bool SP2 = false>
; __device__ __forceinline__ void gemm_phase(PG8_LAS unsigned char* lds, const Gemm g, const Sched S, const Epi E) {
;     ...
;         for (int t = 0; t < nt; t += 2) {
;             const bool last = (t == nt - 2);
;             const char* a1 = cA + (size_t)(t + 1) * kstep;
;             const char* a2 = last ? nA : cA + (size_t)(t + 2) * kstep; const char* b2 = last ? nB : cB + (size_t)(t + 2) * kstep;
;             const char* a3 = a2 + kstep; const char* b3 = b2 + kstep;
;             if (last && has_next) S.a_ready(nxt);
;             if constexpr (SP2) {
;             PG8_LDB(B0, 0, 0); PG8_LDB(B1, 0, 1); PG8_SCHED; PG8_LDA(At, 0, 0); PG8_STAGE(PG8_SA(1, 1), a1 + hstep, voffA);
;             PG8_WAIT_V(8); PG8_WAIT_L(0); PG8_BAR; PG8_MMA(0, 0, At, B0); PG8_MMA(0, 1, At, B1); PG8_BAR; PG8_SCHED;
;             PG8_LDA(At, 0, 1); PG8_STAGE(PG8_SB(0, 0), b2, voffB); PG8_STAGE(PG8_SB(0, 1), b2 + hstep, voffB); PG8_STAGE(PG8_SA(0, 0), a2, voffA);
;             PG8_WAIT_V(8); PG8_WAIT_L(0); PG8_BAR; PG8_MMA(1, 0, At, B0); PG8_MMA(1, 1, At, B1); PG8_BAR; PG8_SCHED;
.LBB0_726:
	s_add_u32 s25, s40, 0xfff80080
	s_addc_u32 s26, s41, -1
	s_add_i32 s27, 0, 0x10000
	s_cmp_eq_u32 s24, 28
	s_cselect_b32 s45, s57, s26
	s_cselect_b32 s44, s66, s25
	s_cselect_b32 s43, s53, s15
	s_cselect_b32 s42, s67, s14
	s_add_i32 s25, 0, 0x14000
	v_add_u32_e32 v152, s27, v141
	v_add_u32_e32 v160, s25, v141
	ds_read_b128 v[136:139], v152
	ds_read_b128 v[144:147], v152 offset:1024
	ds_read_b128 v[148:151], v152 offset:2048
	ds_read_b128 v[152:155], v152 offset:3072
	ds_read_b128 v[156:159], v160
	ds_read_b128 v[168:171], v160 offset:1024
	ds_read_b128 v[172:175], v160 offset:2048
	ds_read_b128 v[176:179], v160 offset:3072
	v_lshl_add_u64 v[160:161], s[40:41], 0, v[132:133]
	s_add_i32 m0, s21, 0xc000
	ds_read_b128 v[180:183], v143
	ds_read_b128 v[184:187], v143 offset:1024
	ds_read_b128 v[188:191], v143 offset:2048
	ds_read_b128 v[192:195], v143 offset:3072
	ds_read_b128 v[196:199], v143 offset:4096
	ds_read_b128 v[200:203], v143 offset:5120
	ds_read_b128 v[224:227], v143 offset:6144
	ds_read_b128 v[228:231], v143 offset:7168
	global_load_lds_dwordx4 v[160:161], off
	v_lshl_add_u64 v[160:161], s[40:41], 0, v[134:135]
	s_add_i32 m0, s21, 0xe000
	s_nop 0
	global_load_lds_dwordx4 v[160:161], off
	s_waitcnt vmcnt(8)
	s_waitcnt lgkmcnt(0)
	s_barrier
	s_setprio 1
	v_mfma_f32_16x16x32_bf16 v[126:129], v[136:139], v[180:183], v[126:129]
	v_mfma_f32_16x16x32_bf16 v[126:129], v[144:147], v[184:187], v[126:129]
	v_mfma_f32_16x16x32_bf16 v[122:125], v[148:151], v[180:183], v[122:125]
	v_mfma_f32_16x16x32_bf16 v[122:125], v[152:155], v[184:187], v[122:125]
	v_mfma_f32_16x16x32_bf16 v[114:117], v[136:139], v[188:191], v[114:117]
	v_mfma_f32_16x16x32_bf16 v[114:117], v[144:147], v[192:195], v[114:117]
	v_mfma_f32_16x16x32_bf16 v[106:109], v[148:151], v[188:191], v[106:109]
	v_mfma_f32_16x16x32_bf16 v[106:109], v[152:155], v[192:195], v[106:109]
	v_mfma_f32_16x16x32_bf16 v[98:101], v[136:139], v[196:199], v[98:101]
	v_mfma_f32_16x16x32_bf16 v[98:101], v[144:147], v[200:203], v[98:101]
	v_mfma_f32_16x16x32_bf16 v[90:93], v[148:151], v[196:199], v[90:93]
	v_mfma_f32_16x16x32_bf16 v[90:93], v[152:155], v[200:203], v[90:93]
	v_mfma_f32_16x16x32_bf16 v[82:85], v[136:139], v[224:227], v[82:85]
	v_mfma_f32_16x16x32_bf16 v[82:85], v[144:147], v[228:231], v[82:85]
	v_mfma_f32_16x16x32_bf16 v[74:77], v[148:151], v[224:227], v[74:77]
	v_mfma_f32_16x16x32_bf16 v[74:77], v[152:155], v[228:231], v[74:77]
	v_mfma_f32_16x16x32_bf16 v[118:121], v[156:159], v[180:183], v[118:121]
	v_mfma_f32_16x16x32_bf16 v[118:121], v[168:171], v[184:187], v[118:121]
	v_mfma_f32_16x16x32_bf16 v[110:113], v[172:175], v[180:183], v[110:113]
	v_mfma_f32_16x16x32_bf16 v[110:113], v[176:179], v[184:187], v[110:113]
	v_mfma_f32_16x16x32_bf16 v[102:105], v[156:159], v[188:191], v[102:105]
	v_mfma_f32_16x16x32_bf16 v[102:105], v[168:171], v[192:195], v[102:105]
	v_mfma_f32_16x16x32_bf16 v[94:97], v[172:175], v[188:191], v[94:97]
	v_mfma_f32_16x16x32_bf16 v[94:97], v[176:179], v[192:195], v[94:97]
	v_mfma_f32_16x16x32_bf16 v[86:89], v[156:159], v[196:199], v[86:89]
	v_mfma_f32_16x16x32_bf16 v[86:89], v[168:171], v[200:203], v[86:89]
	v_mfma_f32_16x16x32_bf16 v[78:81], v[172:175], v[196:199], v[78:81]
	v_mfma_f32_16x16x32_bf16 v[78:81], v[176:179], v[200:203], v[78:81]
	v_mfma_f32_16x16x32_bf16 v[70:73], v[156:159], v[224:227], v[70:73]
	v_mfma_f32_16x16x32_bf16 v[70:73], v[168:171], v[228:231], v[70:73]
	v_mfma_f32_16x16x32_bf16 v[66:69], v[172:175], v[224:227], v[66:69]
	v_mfma_f32_16x16x32_bf16 v[66:69], v[176:179], v[228:231], v[66:69]
	s_setprio 0
	s_barrier
	s_add_i32 s26, s27, s16
	v_lshl_add_u64 v[160:161], s[42:43], 0, v[0:1]
	s_mov_b32 m0, s26
	ds_read_b128 v[180:183], v143 offset:16384
	ds_read_b128 v[184:187], v143 offset:17408
	ds_read_b128 v[188:191], v143 offset:18432
	ds_read_b128 v[192:195], v143 offset:19456
	ds_read_b128 v[196:199], v143 offset:20480
	ds_read_b128 v[200:203], v143 offset:21504
	ds_read_b128 v[224:227], v143 offset:22528
	ds_read_b128 v[228:231], v143 offset:23552
	global_load_lds_dwordx4 v[160:161], off
	s_add_i32 m0, s26, 0x2000
	s_add_u32 s26, s42, 0x80000
	v_lshl_add_u64 v[232:233], s[42:43], 0, v[130:131]
	s_addc_u32 s27, s43, 0
	s_add_i32 s25, s25, s16
	global_load_lds_dwordx4 v[232:233], off
	v_lshl_add_u64 v[234:235], s[26:27], 0, v[0:1]
	s_mov_b32 m0, s25
	v_lshl_add_u64 v[236:237], s[44:45], 0, v[130:131]
	global_load_lds_dwordx4 v[234:235], off
	v_lshl_add_u64 v[234:235], s[26:27], 0, v[130:131]
	s_add_i32 m0, s25, 0x2000
	s_nop 0
	global_load_lds_dwordx4 v[234:235], off
	v_lshl_add_u64 v[234:235], s[44:45], 0, v[0:1]
	s_mov_b32 m0, s21
	s_nop 0
	global_load_lds_dwordx4 v[234:235], off
	s_mov_b32 m0, s22
	s_nop 0
	global_load_lds_dwordx4 v[236:237], off
	s_waitcnt vmcnt(8)
	s_waitcnt lgkmcnt(0)
	s_barrier
; #define PG8_STAGE(bufoff, gbase, voff) do { _Pragma("unroll") for (int _i = 0; _i < 2; ++_i) \
;         __builtin_amdgcn_global_load_lds((const unsigned*)((const char*)(gbase) + (voff)[_i]), (PG8_LAS unsigned*)(lds + (bufoff) + ldsw + _i * 8192), 16, 0, 0); } while (0)
; #define PG8_LDA(dst, b, h) do { _Pragma("unroll") for (int m = 0; m < 4; ++m) _Pragma("unroll") for (int k = 0; k < 2; ++k) dst[m][k] = *(const PG8_LAS bf16x8*)(lds + PG8_SA(b, h) + aoff + m * 2048 + k * 1024); } while (0)
; #define PG8_LDB(dst, b, h) do { _Pragma("unroll") for (int n = 0; n < 2; ++n) _Pragma("unroll") for (int k = 0; k < 2; ++k) dst[n][k] = *(const PG8_LAS bf16x8*)(lds + PG8_SB(b, h) + boff + n * 2048 + k * 1024); } while (0)
; #define PG8_MMA(ai, bj, At, Bt) do { __builtin_amdgcn_s_setprio(1); _Pragma("unroll") for (int m = 0; m < 4; ++m) _Pragma("unroll") for (int n = 0; n < 2; ++n) _Pragma("unroll") for (int k = 0; k < 2; ++k) \
;         acc[ai][bj][m][n] = __builtin_amdgcn_mfma_f32_16x16x32_bf16(Bt[n][k], At[m][k], acc[ai][bj][m][n], 0, 0, 0); __builtin_amdgcn_s_setprio(0); } while (0)
; #define PG8_WAIT_V(n) asm volatile("s_waitcnt vmcnt(" #n ")" ::: "memory")
; #define PG8_WAIT_L(n) asm volatile("s_waitcnt lgkmcnt(" #n ")" ::: "memory")
; #define PG8_BAR __builtin_amdgcn_s_barrier()
; #define PG8_SCHED __builtin_amdgcn_sched_barrier(0)
; template <class Epi, class Sched, bool ALIGN_EPI = false, bool SP2 = false>
; __device__ __forceinline__ void gemm_phase(PG8_LAS unsigned char* lds, const Gemm g, const Sched S, const Epi E) {
;     ...
;             PG8_WAIT_V(8); PG8_WAIT_L(0); PG8_BAR; PG8_MMA(1, 0, At, B0); PG8_MMA(1, 1, At, B1); PG8_BAR; PG8_SCHED;
;             PG8_LDB(B0, 1, 0); PG8_LDB(B1, 1, 1); PG8_SCHED; PG8_LDA(At, 1, 0); PG8_STAGE(PG8_SA(0, 1), a2 + hstep, voffA);
;             PG8_WAIT_V(8); PG8_WAIT_L(0); PG8_BAR; PG8_MMA(0, 0, At, B0); PG8_MMA(0, 1, At, B1); PG8_BAR; PG8_SCHED;
	s_setprio 1
	v_mfma_f32_16x16x32_bf16 v[62:65], v[136:139], v[180:183], v[62:65]
	v_mfma_f32_16x16x32_bf16 v[62:65], v[144:147], v[184:187], v[62:65]
	v_mfma_f32_16x16x32_bf16 v[58:61], v[148:151], v[180:183], v[58:61]
	v_mfma_f32_16x16x32_bf16 v[58:61], v[152:155], v[184:187], v[58:61]
	v_mfma_f32_16x16x32_bf16 v[50:53], v[136:139], v[188:191], v[50:53]
	v_mfma_f32_16x16x32_bf16 v[50:53], v[144:147], v[192:195], v[50:53]
	v_mfma_f32_16x16x32_bf16 v[42:45], v[148:151], v[188:191], v[42:45]
	v_mfma_f32_16x16x32_bf16 v[42:45], v[152:155], v[192:195], v[42:45]
	v_mfma_f32_16x16x32_bf16 v[34:37], v[136:139], v[196:199], v[34:37]
	v_mfma_f32_16x16x32_bf16 v[34:37], v[144:147], v[200:203], v[34:37]
	v_mfma_f32_16x16x32_bf16 v[26:29], v[148:151], v[196:199], v[26:29]
	v_mfma_f32_16x16x32_bf16 v[26:29], v[152:155], v[200:203], v[26:29]
	v_mfma_f32_16x16x32_bf16 v[18:21], v[136:139], v[224:227], v[18:21]
	v_mfma_f32_16x16x32_bf16 v[18:21], v[144:147], v[228:231], v[18:21]
	v_mfma_f32_16x16x32_bf16 v[10:13], v[148:151], v[224:227], v[10:13]
	v_mfma_f32_16x16x32_bf16 v[10:13], v[152:155], v[228:231], v[10:13]
	v_mfma_f32_16x16x32_bf16 v[54:57], v[156:159], v[180:183], v[54:57]
	v_mfma_f32_16x16x32_bf16 v[54:57], v[168:171], v[184:187], v[54:57]
	v_mfma_f32_16x16x32_bf16 v[46:49], v[172:175], v[180:183], v[46:49]
	v_mfma_f32_16x16x32_bf16 v[46:49], v[176:179], v[184:187], v[46:49]
	v_mfma_f32_16x16x32_bf16 v[38:41], v[156:159], v[188:191], v[38:41]
	v_mfma_f32_16x16x32_bf16 v[38:41], v[168:171], v[192:195], v[38:41]
	v_mfma_f32_16x16x32_bf16 v[30:33], v[172:175], v[188:191], v[30:33]
	v_mfma_f32_16x16x32_bf16 v[30:33], v[176:179], v[192:195], v[30:33]
	v_mfma_f32_16x16x32_bf16 v[22:25], v[156:159], v[196:199], v[22:25]
	v_mfma_f32_16x16x32_bf16 v[22:25], v[168:171], v[200:203], v[22:25]
	v_mfma_f32_16x16x32_bf16 v[14:17], v[172:175], v[196:199], v[14:17]
	v_mfma_f32_16x16x32_bf16 v[14:17], v[176:179], v[200:203], v[14:17]
	v_mfma_f32_16x16x32_bf16 v[6:9], v[156:159], v[224:227], v[6:9]
	v_mfma_f32_16x16x32_bf16 v[6:9], v[168:171], v[228:231], v[6:9]
	v_mfma_f32_16x16x32_bf16 v[2:5], v[172:175], v[224:227], v[2:5]
	v_mfma_f32_16x16x32_bf16 v[2:5], v[176:179], v[228:231], v[2:5]
	s_setprio 0
	s_barrier
	s_add_i32 s25, 0, 0x18000
	s_add_i32 s30, 0, 0x1c000
	v_add_u32_e32 v152, s25, v141
	v_add_u32_e32 v167, s30, v141
	ds_read_b128 v[136:139], v152
	ds_read_b128 v[144:147], v152 offset:1024
	ds_read_b128 v[148:151], v152 offset:2048
	ds_read_b128 v[152:155], v152 offset:3072
	ds_read_b128 v[156:159], v167
	ds_read_b128 v[168:171], v167 offset:1024
	ds_read_b128 v[172:175], v167 offset:2048
	ds_read_b128 v[176:179], v167 offset:3072
	s_add_u32 s26, s44, 0x80000
	s_addc_u32 s27, s45, 0
	s_mov_b32 m0, s47
	v_lshl_add_u64 v[238:239], s[26:27], 0, v[0:1]
	ds_read_b128 v[180:183], v143 offset:32768
	ds_read_b128 v[184:187], v143 offset:33792
	ds_read_b128 v[188:191], v143 offset:34816
	ds_read_b128 v[192:195], v143 offset:35840
	ds_read_b128 v[196:199], v143 offset:36864
	ds_read_b128 v[200:203], v143 offset:37888
	ds_read_b128 v[224:227], v143 offset:38912
	ds_read_b128 v[228:231], v143 offset:39936
	global_load_lds_dwordx4 v[238:239], off
	v_lshl_add_u64 v[238:239], s[26:27], 0, v[130:131]
	s_mov_b32 m0, s62
	s_nop 0
	global_load_lds_dwordx4 v[238:239], off
	s_waitcnt vmcnt(8)
	s_waitcnt lgkmcnt(0)
	s_barrier
	s_setprio 1
	v_mfma_f32_16x16x32_bf16 v[126:129], v[136:139], v[180:183], v[126:129]
	v_mfma_f32_16x16x32_bf16 v[126:129], v[144:147], v[184:187], v[126:129]
	v_mfma_f32_16x16x32_bf16 v[122:125], v[148:151], v[180:183], v[122:125]
	v_mfma_f32_16x16x32_bf16 v[122:125], v[152:155], v[184:187], v[122:125]
	v_mfma_f32_16x16x32_bf16 v[114:117], v[136:139], v[188:191], v[114:117]
	v_mfma_f32_16x16x32_bf16 v[114:117], v[144:147], v[192:195], v[114:117]
	v_mfma_f32_16x16x32_bf16 v[106:109], v[148:151], v[188:191], v[106:109]
	v_mfma_f32_16x16x32_bf16 v[106:109], v[152:155], v[192:195], v[106:109]
	v_mfma_f32_16x16x32_bf16 v[98:101], v[136:139], v[196:199], v[98:101]
	v_mfma_f32_16x16x32_bf16 v[98:101], v[144:147], v[200:203], v[98:101]
	v_mfma_f32_16x16x32_bf16 v[90:93], v[148:151], v[196:199], v[90:93]
	v_mfma_f32_16x16x32_bf16 v[90:93], v[152:155], v[200:203], v[90:93]
	v_mfma_f32_16x16x32_bf16 v[82:85], v[136:139], v[224:227], v[82:85]
	v_mfma_f32_16x16x32_bf16 v[82:85], v[144:147], v[228:231], v[82:85]
	v_mfma_f32_16x16x32_bf16 v[74:77], v[148:151], v[224:227], v[74:77]
	v_mfma_f32_16x16x32_bf16 v[74:77], v[152:155], v[228:231], v[74:77]
	v_mfma_f32_16x16x32_bf16 v[118:121], v[156:159], v[180:183], v[118:121]
	v_mfma_f32_16x16x32_bf16 v[118:121], v[168:171], v[184:187], v[118:121]
	v_mfma_f32_16x16x32_bf16 v[110:113], v[172:175], v[180:183], v[110:113]
	v_mfma_f32_16x16x32_bf16 v[110:113], v[176:179], v[184:187], v[110:113]
	v_mfma_f32_16x16x32_bf16 v[102:105], v[156:159], v[188:191], v[102:105]
	v_mfma_f32_16x16x32_bf16 v[102:105], v[168:171], v[192:195], v[102:105]
	v_mfma_f32_16x16x32_bf16 v[94:97], v[172:175], v[188:191], v[94:97]
	v_mfma_f32_16x16x32_bf16 v[94:97], v[176:179], v[192:195], v[94:97]
	v_mfma_f32_16x16x32_bf16 v[86:89], v[156:159], v[196:199], v[86:89]
	v_mfma_f32_16x16x32_bf16 v[86:89], v[168:171], v[200:203], v[86:89]
	v_mfma_f32_16x16x32_bf16 v[78:81], v[172:175], v[196:199], v[78:81]
	v_mfma_f32_16x16x32_bf16 v[78:81], v[176:179], v[200:203], v[78:81]
	v_mfma_f32_16x16x32_bf16 v[70:73], v[156:159], v[224:227], v[70:73]
	v_mfma_f32_16x16x32_bf16 v[70:73], v[168:171], v[228:231], v[70:73]
	v_mfma_f32_16x16x32_bf16 v[66:69], v[172:175], v[224:227], v[66:69]
	v_mfma_f32_16x16x32_bf16 v[66:69], v[176:179], v[228:231], v[66:69]
	s_setprio 0
	s_barrier
; #define PG8_STAGE(bufoff, gbase, voff) do { _Pragma("unroll") for (int _i = 0; _i < 2; ++_i) \
;         __builtin_amdgcn_global_load_lds((const unsigned*)((const char*)(gbase) + (voff)[_i]), (PG8_LAS unsigned*)(lds + (bufoff) + ldsw + _i * 8192), 16, 0, 0); } while (0)
; #define PG8_LDA(dst, b, h) do { _Pragma("unroll") for (int m = 0; m < 4; ++m) _Pragma("unroll") for (int k = 0; k < 2; ++k) dst[m][k] = *(const PG8_LAS bf16x8*)(lds + PG8_SA(b, h) + aoff + m * 2048 + k * 1024); } while (0)
; #define PG8_MMA(ai, bj, At, Bt) do { __builtin_amdgcn_s_setprio(1); _Pragma("unroll") for (int m = 0; m < 4; ++m) _Pragma("unroll") for (int n = 0; n < 2; ++n) _Pragma("unroll") for (int k = 0; k < 2; ++k) \
;         acc[ai][bj][m][n] = __builtin_amdgcn_mfma_f32_16x16x32_bf16(Bt[n][k], At[m][k], acc[ai][bj][m][n], 0, 0, 0); __builtin_amdgcn_s_setprio(0); } while (0)
; #define PG8_WAIT_V(n) asm volatile("s_waitcnt vmcnt(" #n ")" ::: "memory")
; #define PG8_WAIT_L(n) asm volatile("s_waitcnt lgkmcnt(" #n ")" ::: "memory")
; #define PG8_BAR __builtin_amdgcn_s_barrier()
; #define PG8_SCHED __builtin_amdgcn_sched_barrier(0)
; template <class Epi, class Sched, bool ALIGN_EPI = false, bool SP2 = false>
; __device__ __forceinline__ void gemm_phase(PG8_LAS unsigned char* lds, const Gemm g, const Sched S, const Epi E) {
;     ...
;             PG8_LDA(At, 1, 1); PG8_STAGE(PG8_SB(1, 0), b3, voffB); PG8_STAGE(PG8_SB(1, 1), b3 + hstep, voffB); PG8_STAGE(PG8_SA(1, 0), a3, voffA);
;             PG8_WAIT_V(8); PG8_WAIT_L(0); PG8_BAR; PG8_MMA(1, 0, At, B0); PG8_MMA(1, 1, At, B1); PG8_BAR; PG8_SCHED;
;     ...
;         if constexpr (ALIGN_EPI) { if (wr == 0) PG8_BAR; }
	s_add_i32 s25, s25, s16
	v_lshl_add_u64 v[160:161], v[160:161], 0, s[28:29]
	s_mov_b32 m0, s25
	ds_read_b128 v[180:183], v143 offset:49152
	ds_read_b128 v[184:187], v143 offset:50176
	ds_read_b128 v[188:191], v143 offset:51200
	ds_read_b128 v[192:195], v143 offset:52224
	ds_read_b128 v[196:199], v143 offset:53248
	ds_read_b128 v[200:203], v143 offset:54272
	ds_read_b128 v[224:227], v143 offset:55296
	ds_read_b128 v[228:231], v143 offset:56320
	global_load_lds_dwordx4 v[160:161], off
	s_add_i32 m0, s25, 0x2000
	s_add_u32 s26, s42, 0x80080
	v_lshl_add_u64 v[160:161], v[232:233], 0, s[28:29]
	s_addc_u32 s27, s43, 0
	s_add_i32 s25, s30, s16
	global_load_lds_dwordx4 v[160:161], off
	v_lshl_add_u64 v[160:161], s[26:27], 0, v[0:1]
	s_mov_b32 m0, s25
	s_nop 0
	global_load_lds_dwordx4 v[160:161], off
	v_lshl_add_u64 v[160:161], s[26:27], 0, v[130:131]
	s_add_i32 m0, s25, 0x2000
	s_nop 0
	global_load_lds_dwordx4 v[160:161], off
	v_lshl_add_u64 v[160:161], v[234:235], 0, s[28:29]
	s_mov_b32 m0, s63
	s_nop 0
	global_load_lds_dwordx4 v[160:161], off
	v_lshl_add_u64 v[160:161], v[236:237], 0, s[28:29]
	s_mov_b32 m0, s74
	s_nop 0
	global_load_lds_dwordx4 v[160:161], off
	s_waitcnt vmcnt(8)
	s_waitcnt lgkmcnt(0)
	s_barrier
	s_setprio 1
	v_mfma_f32_16x16x32_bf16 v[62:65], v[136:139], v[180:183], v[62:65]
	v_mfma_f32_16x16x32_bf16 v[62:65], v[144:147], v[184:187], v[62:65]
	v_mfma_f32_16x16x32_bf16 v[58:61], v[148:151], v[180:183], v[58:61]
	v_mfma_f32_16x16x32_bf16 v[58:61], v[152:155], v[184:187], v[58:61]
	v_mfma_f32_16x16x32_bf16 v[50:53], v[136:139], v[188:191], v[50:53]
	v_mfma_f32_16x16x32_bf16 v[50:53], v[144:147], v[192:195], v[50:53]
	v_mfma_f32_16x16x32_bf16 v[42:45], v[148:151], v[188:191], v[42:45]
	v_mfma_f32_16x16x32_bf16 v[42:45], v[152:155], v[192:195], v[42:45]
	v_mfma_f32_16x16x32_bf16 v[34:37], v[136:139], v[196:199], v[34:37]
	v_mfma_f32_16x16x32_bf16 v[34:37], v[144:147], v[200:203], v[34:37]
	v_mfma_f32_16x16x32_bf16 v[26:29], v[148:151], v[196:199], v[26:29]
	v_mfma_f32_16x16x32_bf16 v[26:29], v[152:155], v[200:203], v[26:29]
	v_mfma_f32_16x16x32_bf16 v[18:21], v[136:139], v[224:227], v[18:21]
	v_mfma_f32_16x16x32_bf16 v[18:21], v[144:147], v[228:231], v[18:21]
	v_mfma_f32_16x16x32_bf16 v[10:13], v[148:151], v[224:227], v[10:13]
	v_mfma_f32_16x16x32_bf16 v[10:13], v[152:155], v[228:231], v[10:13]
	v_mfma_f32_16x16x32_bf16 v[54:57], v[156:159], v[180:183], v[54:57]
	v_mfma_f32_16x16x32_bf16 v[54:57], v[168:171], v[184:187], v[54:57]
	v_mfma_f32_16x16x32_bf16 v[46:49], v[172:175], v[180:183], v[46:49]
	v_mfma_f32_16x16x32_bf16 v[46:49], v[176:179], v[184:187], v[46:49]
	v_mfma_f32_16x16x32_bf16 v[38:41], v[156:159], v[188:191], v[38:41]
	v_mfma_f32_16x16x32_bf16 v[38:41], v[168:171], v[192:195], v[38:41]
	v_mfma_f32_16x16x32_bf16 v[30:33], v[172:175], v[188:191], v[30:33]
	v_mfma_f32_16x16x32_bf16 v[30:33], v[176:179], v[192:195], v[30:33]
	v_mfma_f32_16x16x32_bf16 v[22:25], v[156:159], v[196:199], v[22:25]
	v_mfma_f32_16x16x32_bf16 v[22:25], v[168:171], v[200:203], v[22:25]
	v_mfma_f32_16x16x32_bf16 v[14:17], v[172:175], v[196:199], v[14:17]
	v_mfma_f32_16x16x32_bf16 v[14:17], v[176:179], v[200:203], v[14:17]
	v_mfma_f32_16x16x32_bf16 v[6:9], v[156:159], v[224:227], v[6:9]
	v_mfma_f32_16x16x32_bf16 v[6:9], v[168:171], v[228:231], v[6:9]
	v_mfma_f32_16x16x32_bf16 v[2:5], v[172:175], v[224:227], v[2:5]
	v_mfma_f32_16x16x32_bf16 v[2:5], v[176:179], v[228:231], v[2:5]
	s_setprio 0
	s_barrier
	s_add_i32 s24, s24, 2
	s_add_u32 s40, s40, 0x100
	s_addc_u32 s41, s41, 0
	s_add_u32 s14, s14, 0x100
	s_addc_u32 s15, s15, 0
	s_cmp_gt_u32 s24, 29
	s_cbranch_scc0 .LBB0_726
	s_and_b64 vcc, exec, s[8:9]
	s_cbranch_vccz .LBB0_729
	s_barrier

; #define PG8_STAGE(bufoff, gbase, voff) do { _Pragma("unroll") for (int _i = 0; _i < 2; ++_i) \
;         __builtin_amdgcn_global_load_lds((const unsigned*)((const char*)(gbase) + (voff)[_i]), (PG8_LAS unsigned*)(lds + (bufoff) + ldsw + _i * 8192), 16, 0, 0); } while (0)
; #define PG8_LDA(dst, b, h) do { _Pragma("unroll") for (int m = 0; m < 4; ++m) _Pragma("unroll") for (int k = 0; k < 2; ++k) dst[m][k] = *(const PG8_LAS bf16x8*)(lds + PG8_SA(b, h) + aoff + m * 2048 + k * 1024); } while (0)
; #define PG8_LDB(dst, b, h) do { _Pragma("unroll") for (int n = 0; n < 2; ++n) _Pragma("unroll") for (int k = 0; k < 2; ++k) dst[n][k] = *(const PG8_LAS bf16x8*)(lds + PG8_SB(b, h) + boff + n * 2048 + k * 1024); } while (0)
; #define PG8_MMA(ai, bj, At, Bt) do { __builtin_amdgcn_s_setprio(1); _Pragma("unroll") for (int m = 0; m < 4; ++m) _Pragma("unroll") for (int n = 0; n < 2; ++n) _Pragma("unroll") for (int k = 0; k < 2; ++k) \
;         acc[ai][bj][m][n] = __builtin_amdgcn_mfma_f32_16x16x32_bf16(Bt[n][k], At[m][k], acc[ai][bj][m][n], 0, 0, 0); __builtin_amdgcn_s_setprio(0); } while (0)
; #define PG8_WAIT_V(n) asm volatile("s_waitcnt vmcnt(" #n ")" ::: "memory")
; #define PG8_BAR __builtin_amdgcn_s_barrier()
; template <class Epi, class Sched, bool ALIGN_EPI = false, bool SP2 = false>
; __device__ __forceinline__ void gemm_phase(PG8_LAS unsigned char* lds, const Gemm g, const Sched S, const Epi E) {
;     ...
;         for (int t = 0; t < nt; t += 2) {
;             const bool last = (t == nt - 2);
;             const char* a1 = cA + (size_t)(t + 1) * kstep;
;             const char* a2 = last ? nA : cA + (size_t)(t + 2) * kstep; const char* b2 = last ? nB : cB + (size_t)(t + 2) * kstep;
;             const char* a3 = a2 + kstep; const char* b3 = b2 + kstep;
;             if (last && has_next) S.a_ready(nxt);
;             if constexpr (SP2) {
;             PG8_LDB(B0, 0, 0); PG8_LDB(B1, 0, 1); PG8_SCHED; PG8_LDA(At, 0, 0); PG8_STAGE(PG8_SA(1, 1), a1 + hstep, voffA);
;             PG8_WAIT_V(8); PG8_WAIT_L(0); PG8_BAR; PG8_MMA(0, 0, At, B0); PG8_MMA(0, 1, At, B1); PG8_BAR; PG8_SCHED;
;             PG8_LDA(At, 0, 1); PG8_STAGE(PG8_SB(0, 0), b2, voffB); PG8_STAGE(PG8_SB(0, 1), b2 + hstep, voffB); PG8_STAGE(PG8_SA(0, 0), a2, voffA);
;             PG8_WAIT_V(8); PG8_WAIT_L(0); PG8_BAR; PG8_MMA(1, 0, At, B0); PG8_MMA(1, 1, At, B1); PG8_BAR; PG8_SCHED;
.LBB0_922:
	s_add_u32 s25, s56, 0xfffe0080
	s_addc_u32 s26, s57, -1
	s_add_i32 s27, 0, 0x10000
	s_cmp_eq_u32 s24, 4
	s_cselect_b32 s65, s5, s26
	s_cselect_b32 s64, s41, s25
	v_add_u32_e32 v140, s27, v143
	s_cselect_b32 s59, s43, s15
	s_cselect_b32 s58, s75, s14
	s_add_i32 s25, 0, 0x14000
	ds_read_b128 v[146:149], v140
	ds_read_b128 v[150:153], v140 offset:1024
	ds_read_b128 v[154:157], v140 offset:2048
	ds_read_b128 v[158:161], v140 offset:3072
	v_add_u32_e32 v140, s25, v143
	ds_read_b128 v[168:171], v140
	ds_read_b128 v[172:175], v140 offset:1024
	ds_read_b128 v[176:179], v140 offset:2048
	ds_read_b128 v[180:183], v140 offset:3072
	v_lshl_add_u64 v[140:141], s[56:57], 0, v[136:137]
	s_add_i32 m0, s21, 0xc000
	ds_read_b128 v[184:187], v145
	ds_read_b128 v[188:191], v145 offset:1024
	ds_read_b128 v[192:195], v145 offset:2048
	ds_read_b128 v[196:199], v145 offset:3072
	ds_read_b128 v[200:203], v145 offset:4096
	ds_read_b128 v[224:227], v145 offset:5120
	ds_read_b128 v[228:231], v145 offset:6144
	ds_read_b128 v[232:235], v145 offset:7168
	global_load_lds_dwordx4 v[140:141], off
	v_lshl_add_u64 v[140:141], s[56:57], 0, v[138:139]
	s_add_i32 m0, s21, 0xe000
	s_nop 0
	global_load_lds_dwordx4 v[140:141], off
	s_waitcnt vmcnt(8)
	s_waitcnt lgkmcnt(0)
	s_barrier
	s_setprio 1
	v_mfma_f32_16x16x32_bf16 v[126:129], v[146:149], v[184:187], v[126:129]
	v_mfma_f32_16x16x32_bf16 v[126:129], v[150:153], v[188:191], v[126:129]
	v_mfma_f32_16x16x32_bf16 v[122:125], v[154:157], v[184:187], v[122:125]
	v_mfma_f32_16x16x32_bf16 v[122:125], v[158:161], v[188:191], v[122:125]
	v_mfma_f32_16x16x32_bf16 v[118:121], v[146:149], v[192:195], v[118:121]
	v_mfma_f32_16x16x32_bf16 v[118:121], v[150:153], v[196:199], v[118:121]
	v_mfma_f32_16x16x32_bf16 v[110:113], v[154:157], v[192:195], v[110:113]
	v_mfma_f32_16x16x32_bf16 v[110:113], v[158:161], v[196:199], v[110:113]
	v_mfma_f32_16x16x32_bf16 v[102:105], v[146:149], v[200:203], v[102:105]
	v_mfma_f32_16x16x32_bf16 v[102:105], v[150:153], v[224:227], v[102:105]
	v_mfma_f32_16x16x32_bf16 v[94:97], v[154:157], v[200:203], v[94:97]
	v_mfma_f32_16x16x32_bf16 v[94:97], v[158:161], v[224:227], v[94:97]
	v_mfma_f32_16x16x32_bf16 v[86:89], v[146:149], v[228:231], v[86:89]
	v_mfma_f32_16x16x32_bf16 v[86:89], v[150:153], v[232:235], v[86:89]
	v_mfma_f32_16x16x32_bf16 v[78:81], v[154:157], v[228:231], v[78:81]
	v_mfma_f32_16x16x32_bf16 v[78:81], v[158:161], v[232:235], v[78:81]
	v_mfma_f32_16x16x32_bf16 v[114:117], v[168:171], v[184:187], v[114:117]
	v_mfma_f32_16x16x32_bf16 v[114:117], v[172:175], v[188:191], v[114:117]
	v_mfma_f32_16x16x32_bf16 v[106:109], v[176:179], v[184:187], v[106:109]
	v_mfma_f32_16x16x32_bf16 v[106:109], v[180:183], v[188:191], v[106:109]
	v_mfma_f32_16x16x32_bf16 v[98:101], v[168:171], v[192:195], v[98:101]
	v_mfma_f32_16x16x32_bf16 v[98:101], v[172:175], v[196:199], v[98:101]
	v_mfma_f32_16x16x32_bf16 v[90:93], v[176:179], v[192:195], v[90:93]
	v_mfma_f32_16x16x32_bf16 v[90:93], v[180:183], v[196:199], v[90:93]
	v_mfma_f32_16x16x32_bf16 v[82:85], v[168:171], v[200:203], v[82:85]
	v_mfma_f32_16x16x32_bf16 v[82:85], v[172:175], v[224:227], v[82:85]
	v_mfma_f32_16x16x32_bf16 v[74:77], v[176:179], v[200:203], v[74:77]
	v_mfma_f32_16x16x32_bf16 v[74:77], v[180:183], v[224:227], v[74:77]
	v_mfma_f32_16x16x32_bf16 v[70:73], v[168:171], v[228:231], v[70:73]
	v_mfma_f32_16x16x32_bf16 v[70:73], v[172:175], v[232:235], v[70:73]
	v_mfma_f32_16x16x32_bf16 v[66:69], v[176:179], v[228:231], v[66:69]
	v_mfma_f32_16x16x32_bf16 v[66:69], v[180:183], v[232:235], v[66:69]
	s_setprio 0
	s_barrier
	s_add_i32 s26, s27, s16
	v_lshl_add_u64 v[140:141], s[58:59], 0, v[0:1]
	s_mov_b32 m0, s26
	ds_read_b128 v[184:187], v145 offset:16384
	ds_read_b128 v[188:191], v145 offset:17408
	ds_read_b128 v[192:195], v145 offset:18432
	ds_read_b128 v[196:199], v145 offset:19456
	ds_read_b128 v[200:203], v145 offset:20480
	ds_read_b128 v[224:227], v145 offset:21504
	ds_read_b128 v[228:231], v145 offset:22528
	ds_read_b128 v[232:235], v145 offset:23552
	global_load_lds_dwordx4 v[140:141], off
	s_add_i32 m0, s26, 0x2000
	s_add_u32 s26, s58, 0x20000
	v_lshl_add_u64 v[236:237], s[58:59], 0, v[130:131]
	s_addc_u32 s27, s59, 0
	s_add_i32 s25, s25, s16
	global_load_lds_dwordx4 v[236:237], off
	v_lshl_add_u64 v[238:239], s[26:27], 0, v[0:1]
	s_mov_b32 m0, s25
	v_lshl_add_u64 v[240:241], s[64:65], 0, v[132:133]
	global_load_lds_dwordx4 v[238:239], off
	v_lshl_add_u64 v[238:239], s[26:27], 0, v[130:131]
	s_add_i32 m0, s25, 0x2000
	s_nop 0
	global_load_lds_dwordx4 v[238:239], off
	v_lshl_add_u64 v[238:239], s[64:65], 0, v[134:135]
	s_mov_b32 m0, s21
	s_nop 0
	global_load_lds_dwordx4 v[238:239], off
	s_mov_b32 m0, s22
	s_nop 0
	global_load_lds_dwordx4 v[240:241], off
	s_waitcnt vmcnt(8)
	s_waitcnt lgkmcnt(0)
	s_barrier
; #define PG8_STAGE(bufoff, gbase, voff) do { _Pragma("unroll") for (int _i = 0; _i < 2; ++_i) \
;         __builtin_amdgcn_global_load_lds((const unsigned*)((const char*)(gbase) + (voff)[_i]), (PG8_LAS unsigned*)(lds + (bufoff) + ldsw + _i * 8192), 16, 0, 0); } while (0)
; #define PG8_LDA(dst, b, h) do { _Pragma("unroll") for (int m = 0; m < 4; ++m) _Pragma("unroll") for (int k = 0; k < 2; ++k) dst[m][k] = *(const PG8_LAS bf16x8*)(lds + PG8_SA(b, h) + aoff + m * 2048 + k * 1024); } while (0)
; #define PG8_LDB(dst, b, h) do { _Pragma("unroll") for (int n = 0; n < 2; ++n) _Pragma("unroll") for (int k = 0; k < 2; ++k) dst[n][k] = *(const PG8_LAS bf16x8*)(lds + PG8_SB(b, h) + boff + n * 2048 + k * 1024); } while (0)
; #define PG8_MMA(ai, bj, At, Bt) do { __builtin_amdgcn_s_setprio(1); _Pragma("unroll") for (int m = 0; m < 4; ++m) _Pragma("unroll") for (int n = 0; n < 2; ++n) _Pragma("unroll") for (int k = 0; k < 2; ++k) \
;         acc[ai][bj][m][n] = __builtin_amdgcn_mfma_f32_16x16x32_bf16(Bt[n][k], At[m][k], acc[ai][bj][m][n], 0, 0, 0); __builtin_amdgcn_s_setprio(0); } while (0)
; #define PG8_WAIT_V(n) asm volatile("s_waitcnt vmcnt(" #n ")" ::: "memory")
; #define PG8_WAIT_L(n) asm volatile("s_waitcnt lgkmcnt(" #n ")" ::: "memory")
; #define PG8_BAR __builtin_amdgcn_s_barrier()
; #define PG8_SCHED __builtin_amdgcn_sched_barrier(0)
; template <class Epi, class Sched, bool ALIGN_EPI = false, bool SP2 = false>
; __device__ __forceinline__ void gemm_phase(PG8_LAS unsigned char* lds, const Gemm g, const Sched S, const Epi E) {
;     ...
;             PG8_WAIT_V(8); PG8_WAIT_L(0); PG8_BAR; PG8_MMA(1, 0, At, B0); PG8_MMA(1, 1, At, B1); PG8_BAR; PG8_SCHED;
;             PG8_LDB(B0, 1, 0); PG8_LDB(B1, 1, 1); PG8_SCHED; PG8_LDA(At, 1, 0); PG8_STAGE(PG8_SA(0, 1), a2 + hstep, voffA);
;             PG8_WAIT_V(8); PG8_WAIT_L(0); PG8_BAR; PG8_MMA(0, 0, At, B0); PG8_MMA(0, 1, At, B1); PG8_BAR; PG8_SCHED;
	s_setprio 1
	v_mfma_f32_16x16x32_bf16 v[62:65], v[146:149], v[184:187], v[62:65]
	v_mfma_f32_16x16x32_bf16 v[62:65], v[150:153], v[188:191], v[62:65]
	v_mfma_f32_16x16x32_bf16 v[58:61], v[154:157], v[184:187], v[58:61]
	v_mfma_f32_16x16x32_bf16 v[58:61], v[158:161], v[188:191], v[58:61]
	v_mfma_f32_16x16x32_bf16 v[54:57], v[146:149], v[192:195], v[54:57]
	v_mfma_f32_16x16x32_bf16 v[54:57], v[150:153], v[196:199], v[54:57]
	v_mfma_f32_16x16x32_bf16 v[46:49], v[154:157], v[192:195], v[46:49]
	v_mfma_f32_16x16x32_bf16 v[46:49], v[158:161], v[196:199], v[46:49]
	v_mfma_f32_16x16x32_bf16 v[38:41], v[146:149], v[200:203], v[38:41]
	v_mfma_f32_16x16x32_bf16 v[38:41], v[150:153], v[224:227], v[38:41]
	v_mfma_f32_16x16x32_bf16 v[30:33], v[154:157], v[200:203], v[30:33]
	v_mfma_f32_16x16x32_bf16 v[30:33], v[158:161], v[224:227], v[30:33]
	v_mfma_f32_16x16x32_bf16 v[22:25], v[146:149], v[228:231], v[22:25]
	v_mfma_f32_16x16x32_bf16 v[22:25], v[150:153], v[232:235], v[22:25]
	v_mfma_f32_16x16x32_bf16 v[14:17], v[154:157], v[228:231], v[14:17]
	v_mfma_f32_16x16x32_bf16 v[14:17], v[158:161], v[232:235], v[14:17]
	v_mfma_f32_16x16x32_bf16 v[50:53], v[168:171], v[184:187], v[50:53]
	v_mfma_f32_16x16x32_bf16 v[50:53], v[172:175], v[188:191], v[50:53]
	v_mfma_f32_16x16x32_bf16 v[42:45], v[176:179], v[184:187], v[42:45]
	v_mfma_f32_16x16x32_bf16 v[42:45], v[180:183], v[188:191], v[42:45]
	v_mfma_f32_16x16x32_bf16 v[34:37], v[168:171], v[192:195], v[34:37]
	v_mfma_f32_16x16x32_bf16 v[34:37], v[172:175], v[196:199], v[34:37]
	v_mfma_f32_16x16x32_bf16 v[26:29], v[176:179], v[192:195], v[26:29]
	v_mfma_f32_16x16x32_bf16 v[26:29], v[180:183], v[196:199], v[26:29]
	v_mfma_f32_16x16x32_bf16 v[18:21], v[168:171], v[200:203], v[18:21]
	v_mfma_f32_16x16x32_bf16 v[18:21], v[172:175], v[224:227], v[18:21]
	v_mfma_f32_16x16x32_bf16 v[10:13], v[176:179], v[200:203], v[10:13]
	v_mfma_f32_16x16x32_bf16 v[10:13], v[180:183], v[224:227], v[10:13]
	v_mfma_f32_16x16x32_bf16 v[6:9], v[168:171], v[228:231], v[6:9]
	v_mfma_f32_16x16x32_bf16 v[6:9], v[172:175], v[232:235], v[6:9]
	v_mfma_f32_16x16x32_bf16 v[2:5], v[176:179], v[228:231], v[2:5]
	v_mfma_f32_16x16x32_bf16 v[2:5], v[180:183], v[232:235], v[2:5]
	s_setprio 0
	s_barrier
	s_add_i32 s25, 0, 0x18000
	s_add_i32 s30, 0, 0x1c000
	v_add_u32_e32 v158, s25, v143
	v_add_u32_e32 v167, s30, v143
	ds_read_b128 v[146:149], v158
	ds_read_b128 v[150:153], v158 offset:1024
	ds_read_b128 v[154:157], v158 offset:2048
	ds_read_b128 v[158:161], v158 offset:3072
	ds_read_b128 v[168:171], v167
	ds_read_b128 v[172:175], v167 offset:1024
	ds_read_b128 v[176:179], v167 offset:2048
	ds_read_b128 v[180:183], v167 offset:3072
	s_add_u32 s26, s64, 0x20000
	s_addc_u32 s27, s65, 0
	s_mov_b32 m0, s47
	v_lshl_add_u64 v[242:243], s[26:27], 0, v[134:135]
	ds_read_b128 v[184:187], v145 offset:32768
	ds_read_b128 v[188:191], v145 offset:33792
	ds_read_b128 v[192:195], v145 offset:34816
	ds_read_b128 v[196:199], v145 offset:35840
	ds_read_b128 v[200:203], v145 offset:36864
	ds_read_b128 v[224:227], v145 offset:37888
	ds_read_b128 v[228:231], v145 offset:38912
	ds_read_b128 v[232:235], v145 offset:39936
	global_load_lds_dwordx4 v[242:243], off
	v_lshl_add_u64 v[242:243], s[26:27], 0, v[132:133]
	s_mov_b32 m0, s62
	s_nop 0
	global_load_lds_dwordx4 v[242:243], off
	s_waitcnt vmcnt(8)
	s_waitcnt lgkmcnt(0)
	s_barrier
	s_setprio 1
	v_mfma_f32_16x16x32_bf16 v[126:129], v[146:149], v[184:187], v[126:129]
	v_mfma_f32_16x16x32_bf16 v[126:129], v[150:153], v[188:191], v[126:129]
	v_mfma_f32_16x16x32_bf16 v[122:125], v[154:157], v[184:187], v[122:125]
	v_mfma_f32_16x16x32_bf16 v[122:125], v[158:161], v[188:191], v[122:125]
	v_mfma_f32_16x16x32_bf16 v[118:121], v[146:149], v[192:195], v[118:121]
	v_mfma_f32_16x16x32_bf16 v[118:121], v[150:153], v[196:199], v[118:121]
	v_mfma_f32_16x16x32_bf16 v[110:113], v[154:157], v[192:195], v[110:113]
	v_mfma_f32_16x16x32_bf16 v[110:113], v[158:161], v[196:199], v[110:113]
	v_mfma_f32_16x16x32_bf16 v[102:105], v[146:149], v[200:203], v[102:105]
	v_mfma_f32_16x16x32_bf16 v[102:105], v[150:153], v[224:227], v[102:105]
	v_mfma_f32_16x16x32_bf16 v[94:97], v[154:157], v[200:203], v[94:97]
	v_mfma_f32_16x16x32_bf16 v[94:97], v[158:161], v[224:227], v[94:97]
	v_mfma_f32_16x16x32_bf16 v[86:89], v[146:149], v[228:231], v[86:89]
	v_mfma_f32_16x16x32_bf16 v[86:89], v[150:153], v[232:235], v[86:89]
	v_mfma_f32_16x16x32_bf16 v[78:81], v[154:157], v[228:231], v[78:81]
	v_mfma_f32_16x16x32_bf16 v[78:81], v[158:161], v[232:235], v[78:81]
	v_mfma_f32_16x16x32_bf16 v[114:117], v[168:171], v[184:187], v[114:117]
	v_mfma_f32_16x16x32_bf16 v[114:117], v[172:175], v[188:191], v[114:117]
	v_mfma_f32_16x16x32_bf16 v[106:109], v[176:179], v[184:187], v[106:109]
	v_mfma_f32_16x16x32_bf16 v[106:109], v[180:183], v[188:191], v[106:109]
	v_mfma_f32_16x16x32_bf16 v[98:101], v[168:171], v[192:195], v[98:101]
	v_mfma_f32_16x16x32_bf16 v[98:101], v[172:175], v[196:199], v[98:101]
	v_mfma_f32_16x16x32_bf16 v[90:93], v[176:179], v[192:195], v[90:93]
	v_mfma_f32_16x16x32_bf16 v[90:93], v[180:183], v[196:199], v[90:93]
	v_mfma_f32_16x16x32_bf16 v[82:85], v[168:171], v[200:203], v[82:85]
	v_mfma_f32_16x16x32_bf16 v[82:85], v[172:175], v[224:227], v[82:85]
	v_mfma_f32_16x16x32_bf16 v[74:77], v[176:179], v[200:203], v[74:77]
	v_mfma_f32_16x16x32_bf16 v[74:77], v[180:183], v[224:227], v[74:77]
	v_mfma_f32_16x16x32_bf16 v[70:73], v[168:171], v[228:231], v[70:73]
	v_mfma_f32_16x16x32_bf16 v[70:73], v[172:175], v[232:235], v[70:73]
	v_mfma_f32_16x16x32_bf16 v[66:69], v[176:179], v[228:231], v[66:69]
	v_mfma_f32_16x16x32_bf16 v[66:69], v[180:183], v[232:235], v[66:69]
	s_setprio 0
	s_barrier
; #define PG8_STAGE(bufoff, gbase, voff) do { _Pragma("unroll") for (int _i = 0; _i < 2; ++_i) \
;         __builtin_amdgcn_global_load_lds((const unsigned*)((const char*)(gbase) + (voff)[_i]), (PG8_LAS unsigned*)(lds + (bufoff) + ldsw + _i * 8192), 16, 0, 0); } while (0)
; #define PG8_LDA(dst, b, h) do { _Pragma("unroll") for (int m = 0; m < 4; ++m) _Pragma("unroll") for (int k = 0; k < 2; ++k) dst[m][k] = *(const PG8_LAS bf16x8*)(lds + PG8_SA(b, h) + aoff + m * 2048 + k * 1024); } while (0)
; #define PG8_MMA(ai, bj, At, Bt) do { __builtin_amdgcn_s_setprio(1); _Pragma("unroll") for (int m = 0; m < 4; ++m) _Pragma("unroll") for (int n = 0; n < 2; ++n) _Pragma("unroll") for (int k = 0; k < 2; ++k) \
;         acc[ai][bj][m][n] = __builtin_amdgcn_mfma_f32_16x16x32_bf16(Bt[n][k], At[m][k], acc[ai][bj][m][n], 0, 0, 0); __builtin_amdgcn_s_setprio(0); } while (0)
; #define PG8_WAIT_V(n) asm volatile("s_waitcnt vmcnt(" #n ")" ::: "memory")
; #define PG8_WAIT_L(n) asm volatile("s_waitcnt lgkmcnt(" #n ")" ::: "memory")
; #define PG8_BAR __builtin_amdgcn_s_barrier()
; #define PG8_SCHED __builtin_amdgcn_sched_barrier(0)
; template <class Epi, class Sched, bool ALIGN_EPI = false, bool SP2 = false>
; __device__ __forceinline__ void gemm_phase(PG8_LAS unsigned char* lds, const Gemm g, const Sched S, const Epi E) {
;     ...
;             PG8_LDA(At, 1, 1); PG8_STAGE(PG8_SB(1, 0), b3, voffB); PG8_STAGE(PG8_SB(1, 1), b3 + hstep, voffB); PG8_STAGE(PG8_SA(1, 0), a3, voffA);
;             PG8_WAIT_V(8); PG8_WAIT_L(0); PG8_BAR; PG8_MMA(1, 0, At, B0); PG8_MMA(1, 1, At, B1); PG8_BAR; PG8_SCHED;
;     ...
;         if constexpr (ALIGN_EPI) { if (wr == 0) PG8_BAR; }
	s_add_i32 s25, s25, s16
	v_lshl_add_u64 v[140:141], v[140:141], 0, s[28:29]
	s_mov_b32 m0, s25
	ds_read_b128 v[184:187], v145 offset:49152
	ds_read_b128 v[188:191], v145 offset:50176
	ds_read_b128 v[192:195], v145 offset:51200
	ds_read_b128 v[196:199], v145 offset:52224
	ds_read_b128 v[200:203], v145 offset:53248
	ds_read_b128 v[224:227], v145 offset:54272
	ds_read_b128 v[228:231], v145 offset:55296
	ds_read_b128 v[232:235], v145 offset:56320
	global_load_lds_dwordx4 v[140:141], off
	s_add_i32 m0, s25, 0x2000
	s_add_u32 s26, s58, 0x20080
	v_lshl_add_u64 v[140:141], v[236:237], 0, s[28:29]
	s_addc_u32 s27, s59, 0
	s_add_i32 s25, s30, s16
	global_load_lds_dwordx4 v[140:141], off
	v_lshl_add_u64 v[140:141], s[26:27], 0, v[0:1]
	s_mov_b32 m0, s25
	s_nop 0
	global_load_lds_dwordx4 v[140:141], off
	v_lshl_add_u64 v[140:141], s[26:27], 0, v[130:131]
	s_add_i32 m0, s25, 0x2000
	s_nop 0
	global_load_lds_dwordx4 v[140:141], off
	v_lshl_add_u64 v[140:141], v[238:239], 0, s[28:29]
	s_mov_b32 m0, s63
	s_nop 0
	global_load_lds_dwordx4 v[140:141], off
	v_lshl_add_u64 v[140:141], v[240:241], 0, s[28:29]
	s_mov_b32 m0, s66
	s_nop 0
	global_load_lds_dwordx4 v[140:141], off
	s_waitcnt vmcnt(8)
	s_waitcnt lgkmcnt(0)
	s_barrier
	s_setprio 1
	v_mfma_f32_16x16x32_bf16 v[62:65], v[146:149], v[184:187], v[62:65]
	v_mfma_f32_16x16x32_bf16 v[62:65], v[150:153], v[188:191], v[62:65]
	v_mfma_f32_16x16x32_bf16 v[58:61], v[154:157], v[184:187], v[58:61]
	v_mfma_f32_16x16x32_bf16 v[58:61], v[158:161], v[188:191], v[58:61]
	v_mfma_f32_16x16x32_bf16 v[54:57], v[146:149], v[192:195], v[54:57]
	v_mfma_f32_16x16x32_bf16 v[54:57], v[150:153], v[196:199], v[54:57]
	v_mfma_f32_16x16x32_bf16 v[46:49], v[154:157], v[192:195], v[46:49]
	v_mfma_f32_16x16x32_bf16 v[46:49], v[158:161], v[196:199], v[46:49]
	v_mfma_f32_16x16x32_bf16 v[38:41], v[146:149], v[200:203], v[38:41]
	v_mfma_f32_16x16x32_bf16 v[38:41], v[150:153], v[224:227], v[38:41]
	v_mfma_f32_16x16x32_bf16 v[30:33], v[154:157], v[200:203], v[30:33]
	v_mfma_f32_16x16x32_bf16 v[30:33], v[158:161], v[224:227], v[30:33]
	v_mfma_f32_16x16x32_bf16 v[22:25], v[146:149], v[228:231], v[22:25]
	v_mfma_f32_16x16x32_bf16 v[22:25], v[150:153], v[232:235], v[22:25]
	v_mfma_f32_16x16x32_bf16 v[14:17], v[154:157], v[228:231], v[14:17]
	v_mfma_f32_16x16x32_bf16 v[14:17], v[158:161], v[232:235], v[14:17]
	v_mfma_f32_16x16x32_bf16 v[50:53], v[168:171], v[184:187], v[50:53]
	v_mfma_f32_16x16x32_bf16 v[50:53], v[172:175], v[188:191], v[50:53]
	v_mfma_f32_16x16x32_bf16 v[42:45], v[176:179], v[184:187], v[42:45]
	v_mfma_f32_16x16x32_bf16 v[42:45], v[180:183], v[188:191], v[42:45]
	v_mfma_f32_16x16x32_bf16 v[34:37], v[168:171], v[192:195], v[34:37]
	v_mfma_f32_16x16x32_bf16 v[34:37], v[172:175], v[196:199], v[34:37]
	v_mfma_f32_16x16x32_bf16 v[26:29], v[176:179], v[192:195], v[26:29]
	v_mfma_f32_16x16x32_bf16 v[26:29], v[180:183], v[196:199], v[26:29]
	v_mfma_f32_16x16x32_bf16 v[18:21], v[168:171], v[200:203], v[18:21]
	v_mfma_f32_16x16x32_bf16 v[18:21], v[172:175], v[224:227], v[18:21]
	v_mfma_f32_16x16x32_bf16 v[10:13], v[176:179], v[200:203], v[10:13]
	v_mfma_f32_16x16x32_bf16 v[10:13], v[180:183], v[224:227], v[10:13]
	v_mfma_f32_16x16x32_bf16 v[6:9], v[168:171], v[228:231], v[6:9]
	v_mfma_f32_16x16x32_bf16 v[6:9], v[172:175], v[232:235], v[6:9]
	v_mfma_f32_16x16x32_bf16 v[2:5], v[176:179], v[228:231], v[2:5]
	v_mfma_f32_16x16x32_bf16 v[2:5], v[180:183], v[232:235], v[2:5]
	s_setprio 0
	s_barrier
	s_add_i32 s24, s24, 2
	s_add_u32 s56, s56, 0x100
	s_addc_u32 s57, s57, 0
	s_add_u32 s14, s14, 0x100
	s_addc_u32 s15, s15, 0
	s_cmp_gt_u32 s24, 5
	s_cbranch_scc0 .LBB0_922
	s_and_b64 vcc, exec, s[38:39]
	s_cbranch_vccz .LBB0_925
	s_barrier

; #define PG8_STAGE(bufoff, gbase, voff) do { _Pragma("unroll") for (int _i = 0; _i < 2; ++_i) \
;         __builtin_amdgcn_global_load_lds((const unsigned*)((const char*)(gbase) + (voff)[_i]), (PG8_LAS unsigned*)(lds + (bufoff) + ldsw + _i * 8192), 16, 0, 0); } while (0)
; #define PG8_LDA(dst, b, h) do { _Pragma("unroll") for (int m = 0; m < 4; ++m) _Pragma("unroll") for (int k = 0; k < 2; ++k) dst[m][k] = *(const PG8_LAS bf16x8*)(lds + PG8_SA(b, h) + aoff + m * 2048 + k * 1024); } while (0)
; #define PG8_LDB(dst, b, h) do { _Pragma("unroll") for (int n = 0; n < 2; ++n) _Pragma("unroll") for (int k = 0; k < 2; ++k) dst[n][k] = *(const PG8_LAS bf16x8*)(lds + PG8_SB(b, h) + boff + n * 2048 + k * 1024); } while (0)
; #define PG8_MMA(ai, bj, At, Bt) do { __builtin_amdgcn_s_setprio(1); _Pragma("unroll") for (int m = 0; m < 4; ++m) _Pragma("unroll") for (int n = 0; n < 2; ++n) _Pragma("unroll") for (int k = 0; k < 2; ++k) \
;         acc[ai][bj][m][n] = __builtin_amdgcn_mfma_f32_16x16x32_bf16(Bt[n][k], At[m][k], acc[ai][bj][m][n], 0, 0, 0); __builtin_amdgcn_s_setprio(0); } while (0)
; #define PG8_WAIT_V(n) asm volatile("s_waitcnt vmcnt(" #n ")" ::: "memory")
; #define PG8_BAR __builtin_amdgcn_s_barrier()
; template <class Epi, class Sched, bool ALIGN_EPI = false, bool SP2 = false>
; __device__ __forceinline__ void gemm_phase(PG8_LAS unsigned char* lds, const Gemm g, const Sched S, const Epi E) {
;     ...
;         for (int t = 0; t < nt; t += 2) {
;             const bool last = (t == nt - 2);
;             const char* a1 = cA + (size_t)(t + 1) * kstep;
;             const char* a2 = last ? nA : cA + (size_t)(t + 2) * kstep; const char* b2 = last ? nB : cB + (size_t)(t + 2) * kstep;
;             const char* a3 = a2 + kstep; const char* b3 = b2 + kstep;
;             if (last && has_next) S.a_ready(nxt);
;             if constexpr (SP2) {
;             PG8_LDB(B0, 0, 0); PG8_LDB(B1, 0, 1); PG8_SCHED; PG8_LDA(At, 0, 0); PG8_STAGE(PG8_SA(1, 1), a1 + hstep, voffA);
;             PG8_WAIT_V(8); PG8_WAIT_L(0); PG8_BAR; PG8_MMA(0, 0, At, B0); PG8_MMA(0, 1, At, B1); PG8_BAR; PG8_SCHED;
;             PG8_LDA(At, 0, 1); PG8_STAGE(PG8_SB(0, 0), b2, voffB); PG8_STAGE(PG8_SB(0, 1), b2 + hstep, voffB); PG8_STAGE(PG8_SA(0, 0), a2, voffA);
;             PG8_WAIT_V(8); PG8_WAIT_L(0); PG8_BAR; PG8_MMA(1, 0, At, B0); PG8_MMA(1, 1, At, B1); PG8_BAR; PG8_SCHED;
.LBB0_2074:
	s_add_u32 s56, s52, 0x100
	s_addc_u32 s57, s53, 0
	s_add_i32 s25, 0, 0x10000
	s_cmp_eq_u32 s24, 28
	s_cselect_b32 s65, s43, s57
	s_cselect_b32 s64, s74, s56
	v_add_u32_e32 v140, s25, v143
	s_cselect_b32 s59, s41, s15
	s_cselect_b32 s58, s75, s14
	s_add_i32 s30, 0, 0x14000
	ds_read_b128 v[136:139], v140
	ds_read_b128 v[146:149], v140 offset:1024
	ds_read_b128 v[150:153], v140 offset:2048
	ds_read_b128 v[154:157], v140 offset:3072
	v_add_u32_e32 v140, s30, v143
	ds_read_b128 v[158:161], v140
	ds_read_b128 v[168:171], v140 offset:1024
	ds_read_b128 v[172:175], v140 offset:2048
	ds_read_b128 v[176:179], v140 offset:3072
	v_lshl_add_u64 v[140:141], s[52:53], 0, v[132:133]
	s_add_i32 m0, s21, 0xc000
	ds_read_b128 v[180:183], v145
	ds_read_b128 v[184:187], v145 offset:1024
	ds_read_b128 v[188:191], v145 offset:2048
	ds_read_b128 v[192:195], v145 offset:3072
	ds_read_b128 v[196:199], v145 offset:4096
	ds_read_b128 v[200:203], v145 offset:5120
	ds_read_b128 v[224:227], v145 offset:6144
	ds_read_b128 v[228:231], v145 offset:7168
	global_load_lds_dwordx4 v[140:141], off
	v_lshl_add_u64 v[140:141], s[52:53], 0, v[134:135]
	s_add_i32 m0, s21, 0xe000
	s_nop 0
	global_load_lds_dwordx4 v[140:141], off
	s_waitcnt vmcnt(8)
	s_waitcnt lgkmcnt(0)
	s_barrier
	s_setprio 1
	v_mfma_f32_16x16x32_bf16 v[126:129], v[136:139], v[180:183], v[126:129]
	v_mfma_f32_16x16x32_bf16 v[126:129], v[146:149], v[184:187], v[126:129]
	v_mfma_f32_16x16x32_bf16 v[122:125], v[150:153], v[180:183], v[122:125]
	v_mfma_f32_16x16x32_bf16 v[122:125], v[154:157], v[184:187], v[122:125]
	v_mfma_f32_16x16x32_bf16 v[110:113], v[136:139], v[188:191], v[110:113]
	v_mfma_f32_16x16x32_bf16 v[110:113], v[146:149], v[192:195], v[110:113]
	v_mfma_f32_16x16x32_bf16 v[106:109], v[150:153], v[188:191], v[106:109]
	v_mfma_f32_16x16x32_bf16 v[106:109], v[154:157], v[192:195], v[106:109]
	v_mfma_f32_16x16x32_bf16 v[94:97], v[136:139], v[196:199], v[94:97]
	v_mfma_f32_16x16x32_bf16 v[94:97], v[146:149], v[200:203], v[94:97]
	v_mfma_f32_16x16x32_bf16 v[90:93], v[150:153], v[196:199], v[90:93]
	v_mfma_f32_16x16x32_bf16 v[90:93], v[154:157], v[200:203], v[90:93]
	v_mfma_f32_16x16x32_bf16 v[78:81], v[136:139], v[224:227], v[78:81]
	v_mfma_f32_16x16x32_bf16 v[78:81], v[146:149], v[228:231], v[78:81]
	v_mfma_f32_16x16x32_bf16 v[74:77], v[150:153], v[224:227], v[74:77]
	v_mfma_f32_16x16x32_bf16 v[74:77], v[154:157], v[228:231], v[74:77]
	v_mfma_f32_16x16x32_bf16 v[118:121], v[158:161], v[180:183], v[118:121]
	v_mfma_f32_16x16x32_bf16 v[118:121], v[168:171], v[184:187], v[118:121]
	v_mfma_f32_16x16x32_bf16 v[114:117], v[172:175], v[180:183], v[114:117]
	v_mfma_f32_16x16x32_bf16 v[114:117], v[176:179], v[184:187], v[114:117]
	v_mfma_f32_16x16x32_bf16 v[102:105], v[158:161], v[188:191], v[102:105]
	v_mfma_f32_16x16x32_bf16 v[102:105], v[168:171], v[192:195], v[102:105]
	v_mfma_f32_16x16x32_bf16 v[98:101], v[172:175], v[188:191], v[98:101]
	v_mfma_f32_16x16x32_bf16 v[98:101], v[176:179], v[192:195], v[98:101]
	v_mfma_f32_16x16x32_bf16 v[86:89], v[158:161], v[196:199], v[86:89]
	v_mfma_f32_16x16x32_bf16 v[86:89], v[168:171], v[200:203], v[86:89]
	v_mfma_f32_16x16x32_bf16 v[82:85], v[172:175], v[196:199], v[82:85]
	v_mfma_f32_16x16x32_bf16 v[82:85], v[176:179], v[200:203], v[82:85]
	v_mfma_f32_16x16x32_bf16 v[70:73], v[158:161], v[224:227], v[70:73]
	v_mfma_f32_16x16x32_bf16 v[70:73], v[168:171], v[228:231], v[70:73]
	v_mfma_f32_16x16x32_bf16 v[66:69], v[172:175], v[224:227], v[66:69]
	v_mfma_f32_16x16x32_bf16 v[66:69], v[176:179], v[228:231], v[66:69]
	s_setprio 0
	s_barrier
	s_add_i32 s25, s25, s16
	v_lshl_add_u64 v[140:141], s[58:59], 0, v[0:1]
	s_mov_b32 m0, s25
	ds_read_b128 v[180:183], v145 offset:16384
	ds_read_b128 v[184:187], v145 offset:17408
	ds_read_b128 v[188:191], v145 offset:18432
	ds_read_b128 v[192:195], v145 offset:19456
	ds_read_b128 v[196:199], v145 offset:20480
	ds_read_b128 v[200:203], v145 offset:21504
	ds_read_b128 v[224:227], v145 offset:22528
	ds_read_b128 v[228:231], v145 offset:23552
	global_load_lds_dwordx4 v[140:141], off
	s_add_i32 m0, s25, 0x2000
	s_add_u32 s26, s58, 0x80000
	v_lshl_add_u64 v[232:233], s[58:59], 0, v[130:131]
	s_addc_u32 s27, s59, 0
	s_add_i32 s25, s30, s16
	global_load_lds_dwordx4 v[232:233], off
	v_lshl_add_u64 v[234:235], s[26:27], 0, v[0:1]
	s_mov_b32 m0, s25
	v_lshl_add_u64 v[236:237], s[64:65], 0, v[130:131]
	global_load_lds_dwordx4 v[234:235], off
	v_lshl_add_u64 v[234:235], s[26:27], 0, v[130:131]
	s_add_i32 m0, s25, 0x2000
	s_nop 0
	global_load_lds_dwordx4 v[234:235], off
	v_lshl_add_u64 v[234:235], s[64:65], 0, v[0:1]
	s_mov_b32 m0, s21
	s_nop 0
	global_load_lds_dwordx4 v[234:235], off
	s_mov_b32 m0, s22
	s_nop 0
	global_load_lds_dwordx4 v[236:237], off
	s_waitcnt vmcnt(8)
	s_waitcnt lgkmcnt(0)
	s_barrier
; #define PG8_STAGE(bufoff, gbase, voff) do { _Pragma("unroll") for (int _i = 0; _i < 2; ++_i) \
;         __builtin_amdgcn_global_load_lds((const unsigned*)((const char*)(gbase) + (voff)[_i]), (PG8_LAS unsigned*)(lds + (bufoff) + ldsw + _i * 8192), 16, 0, 0); } while (0)
; #define PG8_LDA(dst, b, h) do { _Pragma("unroll") for (int m = 0; m < 4; ++m) _Pragma("unroll") for (int k = 0; k < 2; ++k) dst[m][k] = *(const PG8_LAS bf16x8*)(lds + PG8_SA(b, h) + aoff + m * 2048 + k * 1024); } while (0)
; #define PG8_LDB(dst, b, h) do { _Pragma("unroll") for (int n = 0; n < 2; ++n) _Pragma("unroll") for (int k = 0; k < 2; ++k) dst[n][k] = *(const PG8_LAS bf16x8*)(lds + PG8_SB(b, h) + boff + n * 2048 + k * 1024); } while (0)
; #define PG8_MMA(ai, bj, At, Bt) do { __builtin_amdgcn_s_setprio(1); _Pragma("unroll") for (int m = 0; m < 4; ++m) _Pragma("unroll") for (int n = 0; n < 2; ++n) _Pragma("unroll") for (int k = 0; k < 2; ++k) \
;         acc[ai][bj][m][n] = __builtin_amdgcn_mfma_f32_16x16x32_bf16(Bt[n][k], At[m][k], acc[ai][bj][m][n], 0, 0, 0); __builtin_amdgcn_s_setprio(0); } while (0)
; #define PG8_WAIT_V(n) asm volatile("s_waitcnt vmcnt(" #n ")" ::: "memory")
; #define PG8_WAIT_L(n) asm volatile("s_waitcnt lgkmcnt(" #n ")" ::: "memory")
; #define PG8_BAR __builtin_amdgcn_s_barrier()
; #define PG8_SCHED __builtin_amdgcn_sched_barrier(0)
; template <class Epi, class Sched, bool ALIGN_EPI = false, bool SP2 = false>
; __device__ __forceinline__ void gemm_phase(PG8_LAS unsigned char* lds, const Gemm g, const Sched S, const Epi E) {
;     ...
;             PG8_WAIT_V(8); PG8_WAIT_L(0); PG8_BAR; PG8_MMA(1, 0, At, B0); PG8_MMA(1, 1, At, B1); PG8_BAR; PG8_SCHED;
;             PG8_LDB(B0, 1, 0); PG8_LDB(B1, 1, 1); PG8_SCHED; PG8_LDA(At, 1, 0); PG8_STAGE(PG8_SA(0, 1), a2 + hstep, voffA);
;             PG8_WAIT_V(8); PG8_WAIT_L(0); PG8_BAR; PG8_MMA(0, 0, At, B0); PG8_MMA(0, 1, At, B1); PG8_BAR; PG8_SCHED;
	s_setprio 1
	v_mfma_f32_16x16x32_bf16 v[62:65], v[136:139], v[180:183], v[62:65]
	v_mfma_f32_16x16x32_bf16 v[62:65], v[146:149], v[184:187], v[62:65]
	v_mfma_f32_16x16x32_bf16 v[58:61], v[150:153], v[180:183], v[58:61]
	v_mfma_f32_16x16x32_bf16 v[58:61], v[154:157], v[184:187], v[58:61]
	v_mfma_f32_16x16x32_bf16 v[46:49], v[136:139], v[188:191], v[46:49]
	v_mfma_f32_16x16x32_bf16 v[46:49], v[146:149], v[192:195], v[46:49]
	v_mfma_f32_16x16x32_bf16 v[42:45], v[150:153], v[188:191], v[42:45]
	v_mfma_f32_16x16x32_bf16 v[42:45], v[154:157], v[192:195], v[42:45]
	v_mfma_f32_16x16x32_bf16 v[30:33], v[136:139], v[196:199], v[30:33]
	v_mfma_f32_16x16x32_bf16 v[30:33], v[146:149], v[200:203], v[30:33]
	v_mfma_f32_16x16x32_bf16 v[26:29], v[150:153], v[196:199], v[26:29]
	v_mfma_f32_16x16x32_bf16 v[26:29], v[154:157], v[200:203], v[26:29]
	v_mfma_f32_16x16x32_bf16 v[14:17], v[136:139], v[224:227], v[14:17]
	v_mfma_f32_16x16x32_bf16 v[14:17], v[146:149], v[228:231], v[14:17]
	v_mfma_f32_16x16x32_bf16 v[10:13], v[150:153], v[224:227], v[10:13]
	v_mfma_f32_16x16x32_bf16 v[10:13], v[154:157], v[228:231], v[10:13]
	v_mfma_f32_16x16x32_bf16 v[54:57], v[158:161], v[180:183], v[54:57]
	v_mfma_f32_16x16x32_bf16 v[54:57], v[168:171], v[184:187], v[54:57]
	v_mfma_f32_16x16x32_bf16 v[50:53], v[172:175], v[180:183], v[50:53]
	v_mfma_f32_16x16x32_bf16 v[50:53], v[176:179], v[184:187], v[50:53]
	v_mfma_f32_16x16x32_bf16 v[38:41], v[158:161], v[188:191], v[38:41]
	v_mfma_f32_16x16x32_bf16 v[38:41], v[168:171], v[192:195], v[38:41]
	v_mfma_f32_16x16x32_bf16 v[34:37], v[172:175], v[188:191], v[34:37]
	v_mfma_f32_16x16x32_bf16 v[34:37], v[176:179], v[192:195], v[34:37]
	v_mfma_f32_16x16x32_bf16 v[22:25], v[158:161], v[196:199], v[22:25]
	v_mfma_f32_16x16x32_bf16 v[22:25], v[168:171], v[200:203], v[22:25]
	v_mfma_f32_16x16x32_bf16 v[18:21], v[172:175], v[196:199], v[18:21]
	v_mfma_f32_16x16x32_bf16 v[18:21], v[176:179], v[200:203], v[18:21]
	v_mfma_f32_16x16x32_bf16 v[6:9], v[158:161], v[224:227], v[6:9]
	v_mfma_f32_16x16x32_bf16 v[6:9], v[168:171], v[228:231], v[6:9]
	v_mfma_f32_16x16x32_bf16 v[2:5], v[172:175], v[224:227], v[2:5]
	v_mfma_f32_16x16x32_bf16 v[2:5], v[176:179], v[228:231], v[2:5]
	s_setprio 0
	s_barrier
	s_add_i32 s25, 0, 0x18000
	s_add_i32 s30, 0, 0x1c000
	v_add_u32_e32 v154, s25, v143
	v_add_u32_e32 v167, s30, v143
	ds_read_b128 v[136:139], v154
	ds_read_b128 v[146:149], v154 offset:1024
	ds_read_b128 v[150:153], v154 offset:2048
	ds_read_b128 v[154:157], v154 offset:3072
	ds_read_b128 v[158:161], v167
	ds_read_b128 v[168:171], v167 offset:1024
	ds_read_b128 v[172:175], v167 offset:2048
	ds_read_b128 v[176:179], v167 offset:3072
	s_add_u32 s26, s64, 0x80000
	s_addc_u32 s27, s65, 0
	s_mov_b32 m0, s47
	v_lshl_add_u64 v[238:239], s[26:27], 0, v[0:1]
	ds_read_b128 v[180:183], v145 offset:32768
	ds_read_b128 v[184:187], v145 offset:33792
	ds_read_b128 v[188:191], v145 offset:34816
	ds_read_b128 v[192:195], v145 offset:35840
	ds_read_b128 v[196:199], v145 offset:36864
	ds_read_b128 v[200:203], v145 offset:37888
	ds_read_b128 v[224:227], v145 offset:38912
	ds_read_b128 v[228:231], v145 offset:39936
	global_load_lds_dwordx4 v[238:239], off
	v_lshl_add_u64 v[238:239], s[26:27], 0, v[130:131]
	s_mov_b32 m0, s62
	s_nop 0
	global_load_lds_dwordx4 v[238:239], off
	s_waitcnt vmcnt(8)
	s_waitcnt lgkmcnt(0)
	s_barrier
	s_setprio 1
	v_mfma_f32_16x16x32_bf16 v[126:129], v[136:139], v[180:183], v[126:129]
	v_mfma_f32_16x16x32_bf16 v[126:129], v[146:149], v[184:187], v[126:129]
	v_mfma_f32_16x16x32_bf16 v[122:125], v[150:153], v[180:183], v[122:125]
	v_mfma_f32_16x16x32_bf16 v[122:125], v[154:157], v[184:187], v[122:125]
	v_mfma_f32_16x16x32_bf16 v[110:113], v[136:139], v[188:191], v[110:113]
	v_mfma_f32_16x16x32_bf16 v[110:113], v[146:149], v[192:195], v[110:113]
	v_mfma_f32_16x16x32_bf16 v[106:109], v[150:153], v[188:191], v[106:109]
	v_mfma_f32_16x16x32_bf16 v[106:109], v[154:157], v[192:195], v[106:109]
	v_mfma_f32_16x16x32_bf16 v[94:97], v[136:139], v[196:199], v[94:97]
	v_mfma_f32_16x16x32_bf16 v[94:97], v[146:149], v[200:203], v[94:97]
	v_mfma_f32_16x16x32_bf16 v[90:93], v[150:153], v[196:199], v[90:93]
	v_mfma_f32_16x16x32_bf16 v[90:93], v[154:157], v[200:203], v[90:93]
	v_mfma_f32_16x16x32_bf16 v[78:81], v[136:139], v[224:227], v[78:81]
	v_mfma_f32_16x16x32_bf16 v[78:81], v[146:149], v[228:231], v[78:81]
	v_mfma_f32_16x16x32_bf16 v[74:77], v[150:153], v[224:227], v[74:77]
	v_mfma_f32_16x16x32_bf16 v[74:77], v[154:157], v[228:231], v[74:77]
	v_mfma_f32_16x16x32_bf16 v[118:121], v[158:161], v[180:183], v[118:121]
	v_mfma_f32_16x16x32_bf16 v[118:121], v[168:171], v[184:187], v[118:121]
	v_mfma_f32_16x16x32_bf16 v[114:117], v[172:175], v[180:183], v[114:117]
	v_mfma_f32_16x16x32_bf16 v[114:117], v[176:179], v[184:187], v[114:117]
	v_mfma_f32_16x16x32_bf16 v[102:105], v[158:161], v[188:191], v[102:105]
	v_mfma_f32_16x16x32_bf16 v[102:105], v[168:171], v[192:195], v[102:105]
	v_mfma_f32_16x16x32_bf16 v[98:101], v[172:175], v[188:191], v[98:101]
	v_mfma_f32_16x16x32_bf16 v[98:101], v[176:179], v[192:195], v[98:101]
	v_mfma_f32_16x16x32_bf16 v[86:89], v[158:161], v[196:199], v[86:89]
	v_mfma_f32_16x16x32_bf16 v[86:89], v[168:171], v[200:203], v[86:89]
	v_mfma_f32_16x16x32_bf16 v[82:85], v[172:175], v[196:199], v[82:85]
	v_mfma_f32_16x16x32_bf16 v[82:85], v[176:179], v[200:203], v[82:85]
	v_mfma_f32_16x16x32_bf16 v[70:73], v[158:161], v[224:227], v[70:73]
	v_mfma_f32_16x16x32_bf16 v[70:73], v[168:171], v[228:231], v[70:73]
	v_mfma_f32_16x16x32_bf16 v[66:69], v[172:175], v[224:227], v[66:69]
	v_mfma_f32_16x16x32_bf16 v[66:69], v[176:179], v[228:231], v[66:69]
	s_setprio 0
	s_barrier
; #define PG8_STAGE(bufoff, gbase, voff) do { _Pragma("unroll") for (int _i = 0; _i < 2; ++_i) \
;         __builtin_amdgcn_global_load_lds((const unsigned*)((const char*)(gbase) + (voff)[_i]), (PG8_LAS unsigned*)(lds + (bufoff) + ldsw + _i * 8192), 16, 0, 0); } while (0)
; #define PG8_LDA(dst, b, h) do { _Pragma("unroll") for (int m = 0; m < 4; ++m) _Pragma("unroll") for (int k = 0; k < 2; ++k) dst[m][k] = *(const PG8_LAS bf16x8*)(lds + PG8_SA(b, h) + aoff + m * 2048 + k * 1024); } while (0)
; #define PG8_MMA(ai, bj, At, Bt) do { __builtin_amdgcn_s_setprio(1); _Pragma("unroll") for (int m = 0; m < 4; ++m) _Pragma("unroll") for (int n = 0; n < 2; ++n) _Pragma("unroll") for (int k = 0; k < 2; ++k) \
;         acc[ai][bj][m][n] = __builtin_amdgcn_mfma_f32_16x16x32_bf16(Bt[n][k], At[m][k], acc[ai][bj][m][n], 0, 0, 0); __builtin_amdgcn_s_setprio(0); } while (0)
; #define PG8_WAIT_V(n) asm volatile("s_waitcnt vmcnt(" #n ")" ::: "memory")
; #define PG8_WAIT_L(n) asm volatile("s_waitcnt lgkmcnt(" #n ")" ::: "memory")
; #define PG8_BAR __builtin_amdgcn_s_barrier()
; #define PG8_SCHED __builtin_amdgcn_sched_barrier(0)
; template <class Epi, class Sched, bool ALIGN_EPI = false, bool SP2 = false>
; __device__ __forceinline__ void gemm_phase(PG8_LAS unsigned char* lds, const Gemm g, const Sched S, const Epi E) {
;     ...
;             PG8_LDA(At, 1, 1); PG8_STAGE(PG8_SB(1, 0), b3, voffB); PG8_STAGE(PG8_SB(1, 1), b3 + hstep, voffB); PG8_STAGE(PG8_SA(1, 0), a3, voffA);
;             PG8_WAIT_V(8); PG8_WAIT_L(0); PG8_BAR; PG8_MMA(1, 0, At, B0); PG8_MMA(1, 1, At, B1); PG8_BAR; PG8_SCHED;
;     ...
;         if constexpr (ALIGN_EPI) { if (wr == 0) PG8_BAR; }
	s_add_i32 s25, s25, s16
	v_lshl_add_u64 v[140:141], v[140:141], 0, s[28:29]
	s_mov_b32 m0, s25
	ds_read_b128 v[180:183], v145 offset:49152
	ds_read_b128 v[184:187], v145 offset:50176
	ds_read_b128 v[188:191], v145 offset:51200
	ds_read_b128 v[192:195], v145 offset:52224
	ds_read_b128 v[196:199], v145 offset:53248
	ds_read_b128 v[200:203], v145 offset:54272
	ds_read_b128 v[224:227], v145 offset:55296
	ds_read_b128 v[228:231], v145 offset:56320
	global_load_lds_dwordx4 v[140:141], off
	s_add_i32 m0, s25, 0x2000
	s_add_u32 s26, s58, 0x80080
	v_lshl_add_u64 v[140:141], v[232:233], 0, s[28:29]
	s_addc_u32 s27, s59, 0
	s_add_i32 s25, s30, s16
	global_load_lds_dwordx4 v[140:141], off
	v_lshl_add_u64 v[140:141], s[26:27], 0, v[0:1]
	s_mov_b32 m0, s25
	s_nop 0
	global_load_lds_dwordx4 v[140:141], off
	v_lshl_add_u64 v[140:141], s[26:27], 0, v[130:131]
	s_add_i32 m0, s25, 0x2000
	s_nop 0
	global_load_lds_dwordx4 v[140:141], off
	v_lshl_add_u64 v[140:141], v[234:235], 0, s[28:29]
	s_mov_b32 m0, s63
	s_nop 0
	global_load_lds_dwordx4 v[140:141], off
	v_lshl_add_u64 v[140:141], v[236:237], 0, s[28:29]
	s_mov_b32 m0, s66
	s_nop 0
	global_load_lds_dwordx4 v[140:141], off
	s_waitcnt vmcnt(8)
	s_waitcnt lgkmcnt(0)
	s_barrier
	s_setprio 1
	v_mfma_f32_16x16x32_bf16 v[62:65], v[136:139], v[180:183], v[62:65]
	v_mfma_f32_16x16x32_bf16 v[62:65], v[146:149], v[184:187], v[62:65]
	v_mfma_f32_16x16x32_bf16 v[58:61], v[150:153], v[180:183], v[58:61]
	v_mfma_f32_16x16x32_bf16 v[58:61], v[154:157], v[184:187], v[58:61]
	v_mfma_f32_16x16x32_bf16 v[46:49], v[136:139], v[188:191], v[46:49]
	v_mfma_f32_16x16x32_bf16 v[46:49], v[146:149], v[192:195], v[46:49]
	v_mfma_f32_16x16x32_bf16 v[42:45], v[150:153], v[188:191], v[42:45]
	v_mfma_f32_16x16x32_bf16 v[42:45], v[154:157], v[192:195], v[42:45]
	v_mfma_f32_16x16x32_bf16 v[30:33], v[136:139], v[196:199], v[30:33]
	v_mfma_f32_16x16x32_bf16 v[30:33], v[146:149], v[200:203], v[30:33]
	v_mfma_f32_16x16x32_bf16 v[26:29], v[150:153], v[196:199], v[26:29]
	v_mfma_f32_16x16x32_bf16 v[26:29], v[154:157], v[200:203], v[26:29]
	v_mfma_f32_16x16x32_bf16 v[14:17], v[136:139], v[224:227], v[14:17]
	v_mfma_f32_16x16x32_bf16 v[14:17], v[146:149], v[228:231], v[14:17]
	v_mfma_f32_16x16x32_bf16 v[10:13], v[150:153], v[224:227], v[10:13]
	v_mfma_f32_16x16x32_bf16 v[10:13], v[154:157], v[228:231], v[10:13]
	v_mfma_f32_16x16x32_bf16 v[54:57], v[158:161], v[180:183], v[54:57]
	v_mfma_f32_16x16x32_bf16 v[54:57], v[168:171], v[184:187], v[54:57]
	v_mfma_f32_16x16x32_bf16 v[50:53], v[172:175], v[180:183], v[50:53]
	v_mfma_f32_16x16x32_bf16 v[50:53], v[176:179], v[184:187], v[50:53]
	v_mfma_f32_16x16x32_bf16 v[38:41], v[158:161], v[188:191], v[38:41]
	v_mfma_f32_16x16x32_bf16 v[38:41], v[168:171], v[192:195], v[38:41]
	v_mfma_f32_16x16x32_bf16 v[34:37], v[172:175], v[188:191], v[34:37]
	v_mfma_f32_16x16x32_bf16 v[34:37], v[176:179], v[192:195], v[34:37]
	v_mfma_f32_16x16x32_bf16 v[22:25], v[158:161], v[196:199], v[22:25]
	v_mfma_f32_16x16x32_bf16 v[22:25], v[168:171], v[200:203], v[22:25]
	v_mfma_f32_16x16x32_bf16 v[18:21], v[172:175], v[196:199], v[18:21]
	v_mfma_f32_16x16x32_bf16 v[18:21], v[176:179], v[200:203], v[18:21]
	v_mfma_f32_16x16x32_bf16 v[6:9], v[158:161], v[224:227], v[6:9]
	v_mfma_f32_16x16x32_bf16 v[6:9], v[168:171], v[228:231], v[6:9]
	v_mfma_f32_16x16x32_bf16 v[2:5], v[172:175], v[224:227], v[2:5]
	v_mfma_f32_16x16x32_bf16 v[2:5], v[176:179], v[228:231], v[2:5]
	s_setprio 0
	s_barrier
	s_add_i32 s24, s24, 2
	s_add_u32 s14, s14, 0x100
	s_addc_u32 s15, s15, 0
	s_cmp_gt_u32 s24, 29
	s_mov_b64 s[52:53], s[56:57]
	s_cbranch_scc0 .LBB0_2074
	s_and_b64 vcc, exec, s[38:39]
	s_cbranch_vccz .LBB0_2077
	s_barrier
